# GEMM K loops: counter / pointer-advance / exit-test SALU block moved in front of the loop-back barrier (loop-edge rotation, 15 loops)
# baseline (speedup 1.0000x reference)
.LBB0_161:
	ds_read_b128 v[152:155], v143
	ds_read_b128 v[162:165], v143 offset:1024
	ds_read_b128 v[166:169], v143 offset:2048
	ds_read_b128 v[170:173], v143 offset:3072
	ds_read_b128 v[174:177], v158
	ds_read_b128 v[178:181], v158 offset:1024
	ds_read_b128 v[182:185], v158 offset:2048
	ds_read_b128 v[186:189], v158 offset:3072
	s_add_u32 s30, s28, 0xfffc0080
	s_addc_u32 s31, s29, -1
	s_cmp_eq_u32 s55, 12
	s_cselect_b32 s35, s19, s31
	s_cselect_b32 s34, s25, s30
	s_cselect_b32 s31, s17, s54
	s_cselect_b32 s30, s27, s53
	s_waitcnt lgkmcnt(0)
	v_lshl_add_u64 v[156:157], s[28:29], 0, v[144:145]
	s_add_i32 m0, s39, 0xc000
	ds_read_b128 v[190:193], v159
	ds_read_b128 v[194:197], v159 offset:1024
	ds_read_b128 v[198:201], v159 offset:2048
	ds_read_b128 v[202:205], v159 offset:3072
	ds_read_b128 v[206:209], v159 offset:4096
	ds_read_b128 v[210:213], v159 offset:5120
	ds_read_b128 v[214:217], v159 offset:6144
	ds_read_b128 v[218:221], v159 offset:7168
	global_load_lds_dwordx4 v[156:157], off
	v_lshl_add_u64 v[156:157], s[28:29], 0, v[146:147]
	s_add_i32 m0, s39, 0xe000
	s_nop 0
	global_load_lds_dwordx4 v[156:157], off
	s_waitcnt vmcnt(8)
	s_waitcnt lgkmcnt(0)
	s_barrier
	s_setprio 1
	s_waitcnt lgkmcnt(0)
	v_mfma_f32_16x16x32_bf16 v[116:119], v[152:155], v[190:193], v[116:119]
	v_mfma_f32_16x16x32_bf16 v[112:115], v[166:169], v[190:193], v[112:115]
	v_mfma_f32_16x16x32_bf16 v[100:103], v[152:155], v[198:201], v[100:103]
	v_mfma_f32_16x16x32_bf16 v[96:99], v[166:169], v[198:201], v[96:99]
	v_mfma_f32_16x16x32_bf16 v[88:91], v[152:155], v[206:209], v[88:91]
	v_mfma_f32_16x16x32_bf16 v[84:87], v[166:169], v[206:209], v[84:87]
	v_mfma_f32_16x16x32_bf16 v[72:75], v[152:155], v[214:217], v[72:75]
	v_mfma_f32_16x16x32_bf16 v[68:71], v[166:169], v[214:217], v[68:71]
	v_mfma_f32_16x16x32_bf16 v[116:119], v[162:165], v[194:197], v[116:119]
	v_mfma_f32_16x16x32_bf16 v[112:115], v[170:173], v[194:197], v[112:115]
	v_mfma_f32_16x16x32_bf16 v[100:103], v[162:165], v[202:205], v[100:103]
	v_mfma_f32_16x16x32_bf16 v[96:99], v[170:173], v[202:205], v[96:99]
	v_mfma_f32_16x16x32_bf16 v[88:91], v[162:165], v[210:213], v[88:91]
	v_mfma_f32_16x16x32_bf16 v[84:87], v[170:173], v[210:213], v[84:87]
	v_mfma_f32_16x16x32_bf16 v[72:75], v[162:165], v[218:221], v[72:75]
	v_mfma_f32_16x16x32_bf16 v[68:71], v[170:173], v[218:221], v[68:71]
	s_setprio 0
	s_setprio 1
	v_mfma_f32_16x16x32_bf16 v[124:127], v[174:177], v[190:193], v[124:127]
	v_mfma_f32_16x16x32_bf16 v[120:123], v[182:185], v[190:193], v[120:123]
	v_mfma_f32_16x16x32_bf16 v[108:111], v[174:177], v[198:201], v[108:111]
	v_mfma_f32_16x16x32_bf16 v[104:107], v[182:185], v[198:201], v[104:107]
	v_mfma_f32_16x16x32_bf16 v[92:95], v[174:177], v[206:209], v[92:95]
	v_mfma_f32_16x16x32_bf16 v[80:83], v[182:185], v[206:209], v[80:83]
	v_mfma_f32_16x16x32_bf16 v[76:79], v[174:177], v[214:217], v[76:79]
	v_mfma_f32_16x16x32_bf16 v[64:67], v[182:185], v[214:217], v[64:67]
	v_mfma_f32_16x16x32_bf16 v[124:127], v[178:181], v[194:197], v[124:127]
	v_mfma_f32_16x16x32_bf16 v[120:123], v[186:189], v[194:197], v[120:123]
	v_mfma_f32_16x16x32_bf16 v[108:111], v[178:181], v[202:205], v[108:111]
	v_mfma_f32_16x16x32_bf16 v[104:107], v[186:189], v[202:205], v[104:107]
	v_mfma_f32_16x16x32_bf16 v[92:95], v[178:181], v[210:213], v[92:95]
	v_mfma_f32_16x16x32_bf16 v[80:83], v[186:189], v[210:213], v[80:83]
	v_mfma_f32_16x16x32_bf16 v[76:79], v[178:181], v[218:221], v[76:79]
	v_mfma_f32_16x16x32_bf16 v[64:67], v[186:189], v[218:221], v[64:67]
	s_setprio 0
	s_barrier
	s_add_i32 s56, s49, s36
	v_lshl_add_u64 v[156:157], s[30:31], 0, v[130:131]
	s_mov_b32 m0, s56
	ds_read_b128 v[190:193], v159 offset:16384
	ds_read_b128 v[194:197], v159 offset:17408
	ds_read_b128 v[198:201], v159 offset:18432
	ds_read_b128 v[202:205], v159 offset:19456
	ds_read_b128 v[206:209], v159 offset:20480
	ds_read_b128 v[210:213], v159 offset:21504
	ds_read_b128 v[214:217], v159 offset:22528
	ds_read_b128 v[218:221], v159 offset:23552
	global_load_lds_dwordx4 v[156:157], off
	s_add_i32 m0, s56, 0x2000
	s_add_u32 s56, s30, 0x40000
	v_lshl_add_u64 v[222:223], s[30:31], 0, v[134:135]
	s_addc_u32 s57, s31, 0
	s_add_i32 s58, s50, s36
	global_load_lds_dwordx4 v[222:223], off
	v_lshl_add_u64 v[224:225], s[56:57], 0, v[130:131]
	s_mov_b32 m0, s58
	v_lshl_add_u64 v[226:227], s[34:35], 0, v[132:133]
	global_load_lds_dwordx4 v[224:225], off
	v_lshl_add_u64 v[224:225], s[56:57], 0, v[134:135]
	s_add_i32 m0, s58, 0x2000
	s_nop 0
	global_load_lds_dwordx4 v[224:225], off
	v_lshl_add_u64 v[224:225], s[34:35], 0, v[128:129]
	s_mov_b32 m0, s39
	s_nop 0
	global_load_lds_dwordx4 v[224:225], off
	s_mov_b32 m0, s40
	s_nop 0
	global_load_lds_dwordx4 v[226:227], off
	s_waitcnt vmcnt(8)
	s_waitcnt lgkmcnt(0)
	s_barrier
	s_setprio 1
	s_waitcnt lgkmcnt(0)
	v_mfma_f32_16x16x32_bf16 v[56:59], v[152:155], v[190:193], v[56:59]
	v_mfma_f32_16x16x32_bf16 v[52:55], v[166:169], v[190:193], v[52:55]
	v_mfma_f32_16x16x32_bf16 v[40:43], v[152:155], v[198:201], v[40:43]
	v_mfma_f32_16x16x32_bf16 v[36:39], v[166:169], v[198:201], v[36:39]
	v_mfma_f32_16x16x32_bf16 v[24:27], v[152:155], v[206:209], v[24:27]
	v_mfma_f32_16x16x32_bf16 v[20:23], v[166:169], v[206:209], v[20:23]
	v_mfma_f32_16x16x32_bf16 v[8:11], v[152:155], v[214:217], v[8:11]
	v_mfma_f32_16x16x32_bf16 v[4:7], v[166:169], v[214:217], v[4:7]
	v_mfma_f32_16x16x32_bf16 v[56:59], v[162:165], v[194:197], v[56:59]
	v_mfma_f32_16x16x32_bf16 v[52:55], v[170:173], v[194:197], v[52:55]
	v_mfma_f32_16x16x32_bf16 v[40:43], v[162:165], v[202:205], v[40:43]
	v_mfma_f32_16x16x32_bf16 v[36:39], v[170:173], v[202:205], v[36:39]
	v_mfma_f32_16x16x32_bf16 v[24:27], v[162:165], v[210:213], v[24:27]
	v_mfma_f32_16x16x32_bf16 v[20:23], v[170:173], v[210:213], v[20:23]
	v_mfma_f32_16x16x32_bf16 v[8:11], v[162:165], v[218:221], v[8:11]
	v_mfma_f32_16x16x32_bf16 v[4:7], v[170:173], v[218:221], v[4:7]
	s_setprio 0
	s_setprio 1
	v_mfma_f32_16x16x32_bf16 v[60:63], v[174:177], v[190:193], v[60:63]
	v_mfma_f32_16x16x32_bf16 v[48:51], v[182:185], v[190:193], v[48:51]
	v_mfma_f32_16x16x32_bf16 v[44:47], v[174:177], v[198:201], v[44:47]
	v_mfma_f32_16x16x32_bf16 v[32:35], v[182:185], v[198:201], v[32:35]
	v_mfma_f32_16x16x32_bf16 v[28:31], v[174:177], v[206:209], v[28:31]
	v_mfma_f32_16x16x32_bf16 v[16:19], v[182:185], v[206:209], v[16:19]
	v_mfma_f32_16x16x32_bf16 v[12:15], v[174:177], v[214:217], v[12:15]
	v_mfma_f32_16x16x32_bf16 v[0:3], v[182:185], v[214:217], v[0:3]
	v_mfma_f32_16x16x32_bf16 v[60:63], v[178:181], v[194:197], v[60:63]
	v_mfma_f32_16x16x32_bf16 v[48:51], v[186:189], v[194:197], v[48:51]
	v_mfma_f32_16x16x32_bf16 v[44:47], v[178:181], v[202:205], v[44:47]
	v_mfma_f32_16x16x32_bf16 v[32:35], v[186:189], v[202:205], v[32:35]
	v_mfma_f32_16x16x32_bf16 v[28:31], v[178:181], v[210:213], v[28:31]
	v_mfma_f32_16x16x32_bf16 v[16:19], v[186:189], v[210:213], v[16:19]
	v_mfma_f32_16x16x32_bf16 v[12:15], v[178:181], v[218:221], v[12:15]
	v_mfma_f32_16x16x32_bf16 v[0:3], v[186:189], v[218:221], v[0:3]
	s_setprio 0
	s_barrier
	s_add_i32 s56, 0, 0x18000
	s_add_i32 s57, 0, 0x1c000
	v_add_u32_e32 v170, s56, v141
	v_add_u32_e32 v186, s57, v141
	ds_read_b128 v[152:155], v170
	ds_read_b128 v[162:165], v170 offset:1024
	ds_read_b128 v[166:169], v170 offset:2048
	ds_read_b128 v[170:173], v170 offset:3072
	ds_read_b128 v[174:177], v186
	ds_read_b128 v[178:181], v186 offset:1024
	ds_read_b128 v[182:185], v186 offset:2048
	ds_read_b128 v[186:189], v186 offset:3072
	s_add_u32 s34, s34, 0x40000
	s_addc_u32 s35, s35, 0
	s_mov_b32 m0, s41
	v_lshl_add_u64 v[228:229], s[34:35], 0, v[128:129]
	ds_read_b128 v[190:193], v159 offset:32768
	ds_read_b128 v[194:197], v159 offset:33792
	ds_read_b128 v[198:201], v159 offset:34816
	ds_read_b128 v[202:205], v159 offset:35840
	ds_read_b128 v[206:209], v159 offset:36864
	ds_read_b128 v[210:213], v159 offset:37888
	ds_read_b128 v[214:217], v159 offset:38912
	ds_read_b128 v[218:221], v159 offset:39936
	global_load_lds_dwordx4 v[228:229], off
	v_lshl_add_u64 v[228:229], s[34:35], 0, v[132:133]
	s_mov_b32 m0, s42
	s_nop 0
	global_load_lds_dwordx4 v[228:229], off
	s_waitcnt vmcnt(8)
	s_waitcnt lgkmcnt(0)
	s_barrier
	s_setprio 1
	s_waitcnt lgkmcnt(0)
	v_mfma_f32_16x16x32_bf16 v[116:119], v[152:155], v[190:193], v[116:119]
	v_mfma_f32_16x16x32_bf16 v[112:115], v[166:169], v[190:193], v[112:115]
	v_mfma_f32_16x16x32_bf16 v[100:103], v[152:155], v[198:201], v[100:103]
	v_mfma_f32_16x16x32_bf16 v[96:99], v[166:169], v[198:201], v[96:99]
	v_mfma_f32_16x16x32_bf16 v[88:91], v[152:155], v[206:209], v[88:91]
	v_mfma_f32_16x16x32_bf16 v[84:87], v[166:169], v[206:209], v[84:87]
	v_mfma_f32_16x16x32_bf16 v[72:75], v[152:155], v[214:217], v[72:75]
	v_mfma_f32_16x16x32_bf16 v[68:71], v[166:169], v[214:217], v[68:71]
	v_mfma_f32_16x16x32_bf16 v[116:119], v[162:165], v[194:197], v[116:119]
	v_mfma_f32_16x16x32_bf16 v[112:115], v[170:173], v[194:197], v[112:115]
	v_mfma_f32_16x16x32_bf16 v[100:103], v[162:165], v[202:205], v[100:103]
	v_mfma_f32_16x16x32_bf16 v[96:99], v[170:173], v[202:205], v[96:99]
	v_mfma_f32_16x16x32_bf16 v[88:91], v[162:165], v[210:213], v[88:91]
	v_mfma_f32_16x16x32_bf16 v[84:87], v[170:173], v[210:213], v[84:87]
	v_mfma_f32_16x16x32_bf16 v[72:75], v[162:165], v[218:221], v[72:75]
	v_mfma_f32_16x16x32_bf16 v[68:71], v[170:173], v[218:221], v[68:71]
	s_setprio 0
	s_setprio 1
	v_mfma_f32_16x16x32_bf16 v[124:127], v[174:177], v[190:193], v[124:127]
	v_mfma_f32_16x16x32_bf16 v[120:123], v[182:185], v[190:193], v[120:123]
	v_mfma_f32_16x16x32_bf16 v[108:111], v[174:177], v[198:201], v[108:111]
	v_mfma_f32_16x16x32_bf16 v[104:107], v[182:185], v[198:201], v[104:107]
	v_mfma_f32_16x16x32_bf16 v[92:95], v[174:177], v[206:209], v[92:95]
	v_mfma_f32_16x16x32_bf16 v[80:83], v[182:185], v[206:209], v[80:83]
	v_mfma_f32_16x16x32_bf16 v[76:79], v[174:177], v[214:217], v[76:79]
	v_mfma_f32_16x16x32_bf16 v[64:67], v[182:185], v[214:217], v[64:67]
	v_mfma_f32_16x16x32_bf16 v[124:127], v[178:181], v[194:197], v[124:127]
	v_mfma_f32_16x16x32_bf16 v[120:123], v[186:189], v[194:197], v[120:123]
	v_mfma_f32_16x16x32_bf16 v[108:111], v[178:181], v[202:205], v[108:111]
	v_mfma_f32_16x16x32_bf16 v[104:107], v[186:189], v[202:205], v[104:107]
	v_mfma_f32_16x16x32_bf16 v[92:95], v[178:181], v[210:213], v[92:95]
	v_mfma_f32_16x16x32_bf16 v[80:83], v[186:189], v[210:213], v[80:83]
	v_mfma_f32_16x16x32_bf16 v[76:79], v[178:181], v[218:221], v[76:79]
	v_mfma_f32_16x16x32_bf16 v[64:67], v[186:189], v[218:221], v[64:67]
	s_setprio 0
	s_barrier
	s_add_i32 s34, s56, s36
	v_lshl_add_u64 v[156:157], v[156:157], 0, s[10:11]
	s_mov_b32 m0, s34
	ds_read_b128 v[190:193], v159 offset:49152
	ds_read_b128 v[194:197], v159 offset:50176
	ds_read_b128 v[198:201], v159 offset:51200
	ds_read_b128 v[202:205], v159 offset:52224
	ds_read_b128 v[206:209], v159 offset:53248
	ds_read_b128 v[210:213], v159 offset:54272
	ds_read_b128 v[214:217], v159 offset:55296
	ds_read_b128 v[218:221], v159 offset:56320
	global_load_lds_dwordx4 v[156:157], off
	s_add_i32 m0, s34, 0x2000
	s_add_u32 s30, s30, 0x40080
	v_lshl_add_u64 v[156:157], v[222:223], 0, s[10:11]
	s_addc_u32 s31, s31, 0
	s_add_i32 s34, s57, s36
	global_load_lds_dwordx4 v[156:157], off
	v_lshl_add_u64 v[156:157], s[30:31], 0, v[130:131]
	s_mov_b32 m0, s34
	s_nop 0
	global_load_lds_dwordx4 v[156:157], off
	v_lshl_add_u64 v[156:157], s[30:31], 0, v[134:135]
	s_add_i32 m0, s34, 0x2000
	s_nop 0
	global_load_lds_dwordx4 v[156:157], off
	v_lshl_add_u64 v[156:157], v[224:225], 0, s[10:11]
	s_mov_b32 m0, s43
	s_nop 0
	global_load_lds_dwordx4 v[156:157], off
	v_lshl_add_u64 v[156:157], v[226:227], 0, s[10:11]
	s_mov_b32 m0, s44
	s_nop 0
	global_load_lds_dwordx4 v[156:157], off
	s_waitcnt vmcnt(8)
	s_waitcnt lgkmcnt(0)
	s_barrier
	s_setprio 1
	s_waitcnt lgkmcnt(0)
	v_mfma_f32_16x16x32_bf16 v[56:59], v[152:155], v[190:193], v[56:59]
	v_mfma_f32_16x16x32_bf16 v[52:55], v[166:169], v[190:193], v[52:55]
	v_mfma_f32_16x16x32_bf16 v[40:43], v[152:155], v[198:201], v[40:43]
	v_mfma_f32_16x16x32_bf16 v[36:39], v[166:169], v[198:201], v[36:39]
	v_mfma_f32_16x16x32_bf16 v[24:27], v[152:155], v[206:209], v[24:27]
	v_mfma_f32_16x16x32_bf16 v[20:23], v[166:169], v[206:209], v[20:23]
	v_mfma_f32_16x16x32_bf16 v[8:11], v[152:155], v[214:217], v[8:11]
	v_mfma_f32_16x16x32_bf16 v[4:7], v[166:169], v[214:217], v[4:7]
	v_mfma_f32_16x16x32_bf16 v[56:59], v[162:165], v[194:197], v[56:59]
	v_mfma_f32_16x16x32_bf16 v[52:55], v[170:173], v[194:197], v[52:55]
	v_mfma_f32_16x16x32_bf16 v[40:43], v[162:165], v[202:205], v[40:43]
	v_mfma_f32_16x16x32_bf16 v[36:39], v[170:173], v[202:205], v[36:39]
	v_mfma_f32_16x16x32_bf16 v[24:27], v[162:165], v[210:213], v[24:27]
	v_mfma_f32_16x16x32_bf16 v[20:23], v[170:173], v[210:213], v[20:23]
	v_mfma_f32_16x16x32_bf16 v[8:11], v[162:165], v[218:221], v[8:11]
	v_mfma_f32_16x16x32_bf16 v[4:7], v[170:173], v[218:221], v[4:7]
	s_setprio 0
	s_setprio 1
	v_mfma_f32_16x16x32_bf16 v[60:63], v[174:177], v[190:193], v[60:63]
	v_mfma_f32_16x16x32_bf16 v[48:51], v[182:185], v[190:193], v[48:51]
	v_mfma_f32_16x16x32_bf16 v[44:47], v[174:177], v[198:201], v[44:47]
	v_mfma_f32_16x16x32_bf16 v[32:35], v[182:185], v[198:201], v[32:35]
	v_mfma_f32_16x16x32_bf16 v[28:31], v[174:177], v[206:209], v[28:31]
	v_mfma_f32_16x16x32_bf16 v[16:19], v[182:185], v[206:209], v[16:19]
	v_mfma_f32_16x16x32_bf16 v[12:15], v[174:177], v[214:217], v[12:15]
	v_mfma_f32_16x16x32_bf16 v[0:3], v[182:185], v[214:217], v[0:3]
	v_mfma_f32_16x16x32_bf16 v[60:63], v[178:181], v[194:197], v[60:63]
	v_mfma_f32_16x16x32_bf16 v[48:51], v[186:189], v[194:197], v[48:51]
	v_mfma_f32_16x16x32_bf16 v[44:47], v[178:181], v[202:205], v[44:47]
	v_mfma_f32_16x16x32_bf16 v[32:35], v[186:189], v[202:205], v[32:35]
	v_mfma_f32_16x16x32_bf16 v[28:31], v[178:181], v[210:213], v[28:31]
	v_mfma_f32_16x16x32_bf16 v[16:19], v[186:189], v[210:213], v[16:19]
	v_mfma_f32_16x16x32_bf16 v[12:15], v[178:181], v[218:221], v[12:15]
	v_mfma_f32_16x16x32_bf16 v[0:3], v[186:189], v[218:221], v[0:3]
	s_setprio 0
	s_add_i32 s55, s55, 2
	s_add_u32 s28, s28, 0x100
	s_addc_u32 s29, s29, 0
	s_add_u32 s53, s53, 0x100
	s_addc_u32 s54, s54, 0
	s_cmp_gt_u32 s55, 13
	s_barrier
	s_cbranch_scc0 .LBB0_161
	s_and_b64 vcc, exec, s[12:13]
	s_cbranch_vccz .LBB0_166
	s_barrier
	v_lshl_add_u32 v152, s26, 8, v139
	s_cmp_gt_i32 s24, 21
	s_mov_b64 s[26:27], -1
	s_cbranch_scc1 .LBB0_167

.LBB0_247:
	ds_read_b128 v[148:151], v145
	ds_read_b128 v[152:155], v145 offset:1024
	ds_read_b128 v[156:159], v145 offset:2048
	ds_read_b128 v[160:163], v145 offset:3072
	ds_read_b128 v[164:167], v146
	ds_read_b128 v[168:171], v146 offset:1024
	ds_read_b128 v[172:175], v146 offset:2048
	ds_read_b128 v[176:179], v146 offset:3072
	s_add_u32 s28, s26, 0x100
	s_addc_u32 s29, s27, 0
	s_cmp_eq_u32 s56, 40
	s_cselect_b32 s35, s5, s29
	s_cselect_b32 s34, s4, s28
	s_cselect_b32 s31, s25, s55
	s_cselect_b32 s30, s24, s54
	v_lshl_add_u64 v[140:141], s[26:27], 0, v[132:133]
	s_add_i32 m0, s40, 0xc000
	ds_read_b128 v[180:183], v147
	ds_read_b128 v[184:187], v147 offset:1024
	ds_read_b128 v[188:191], v147 offset:2048
	ds_read_b128 v[192:195], v147 offset:3072
	ds_read_b128 v[196:199], v147 offset:4096
	ds_read_b128 v[200:203], v147 offset:5120
	ds_read_b128 v[204:207], v147 offset:6144
	ds_read_b128 v[208:211], v147 offset:7168
	global_load_lds_dwordx4 v[140:141], off
	v_lshl_add_u64 v[140:141], s[26:27], 0, v[134:135]
	s_add_i32 m0, s40, 0xe000
	s_nop 0
	global_load_lds_dwordx4 v[140:141], off
	s_waitcnt vmcnt(8)
	s_waitcnt lgkmcnt(0)
	s_barrier
	s_setprio 1
	s_waitcnt lgkmcnt(0)
	v_mfma_f32_16x16x32_bf16 v[124:127], v[148:151], v[180:183], v[124:127]
	v_mfma_f32_16x16x32_bf16 v[120:123], v[156:159], v[180:183], v[120:123]
	v_mfma_f32_16x16x32_bf16 v[112:115], v[148:151], v[188:191], v[112:115]
	v_mfma_f32_16x16x32_bf16 v[108:111], v[156:159], v[188:191], v[108:111]
	v_mfma_f32_16x16x32_bf16 v[96:99], v[148:151], v[196:199], v[96:99]
	v_mfma_f32_16x16x32_bf16 v[92:95], v[156:159], v[196:199], v[92:95]
	v_mfma_f32_16x16x32_bf16 v[80:83], v[148:151], v[204:207], v[80:83]
	v_mfma_f32_16x16x32_bf16 v[76:79], v[156:159], v[204:207], v[76:79]
	v_mfma_f32_16x16x32_bf16 v[124:127], v[152:155], v[184:187], v[124:127]
	v_mfma_f32_16x16x32_bf16 v[120:123], v[160:163], v[184:187], v[120:123]
	v_mfma_f32_16x16x32_bf16 v[112:115], v[152:155], v[192:195], v[112:115]
	v_mfma_f32_16x16x32_bf16 v[108:111], v[160:163], v[192:195], v[108:111]
	v_mfma_f32_16x16x32_bf16 v[96:99], v[152:155], v[200:203], v[96:99]
	v_mfma_f32_16x16x32_bf16 v[92:95], v[160:163], v[200:203], v[92:95]
	v_mfma_f32_16x16x32_bf16 v[80:83], v[152:155], v[208:211], v[80:83]
	v_mfma_f32_16x16x32_bf16 v[76:79], v[160:163], v[208:211], v[76:79]
	s_setprio 0
	s_setprio 1
	v_mfma_f32_16x16x32_bf16 v[116:119], v[164:167], v[180:183], v[116:119]
	v_mfma_f32_16x16x32_bf16 v[104:107], v[172:175], v[180:183], v[104:107]
	v_mfma_f32_16x16x32_bf16 v[100:103], v[164:167], v[188:191], v[100:103]
	v_mfma_f32_16x16x32_bf16 v[88:91], v[172:175], v[188:191], v[88:91]
	v_mfma_f32_16x16x32_bf16 v[84:87], v[164:167], v[196:199], v[84:87]
	v_mfma_f32_16x16x32_bf16 v[72:75], v[172:175], v[196:199], v[72:75]
	v_mfma_f32_16x16x32_bf16 v[68:71], v[164:167], v[204:207], v[68:71]
	v_mfma_f32_16x16x32_bf16 v[64:67], v[172:175], v[204:207], v[64:67]
	v_mfma_f32_16x16x32_bf16 v[116:119], v[168:171], v[184:187], v[116:119]
	v_mfma_f32_16x16x32_bf16 v[104:107], v[176:179], v[184:187], v[104:107]
	v_mfma_f32_16x16x32_bf16 v[100:103], v[168:171], v[192:195], v[100:103]
	v_mfma_f32_16x16x32_bf16 v[88:91], v[176:179], v[192:195], v[88:91]
	v_mfma_f32_16x16x32_bf16 v[84:87], v[168:171], v[200:203], v[84:87]
	v_mfma_f32_16x16x32_bf16 v[72:75], v[176:179], v[200:203], v[72:75]
	v_mfma_f32_16x16x32_bf16 v[68:71], v[168:171], v[208:211], v[68:71]
	v_mfma_f32_16x16x32_bf16 v[64:67], v[176:179], v[208:211], v[64:67]
	s_setprio 0
	s_barrier
	s_add_i32 s26, s48, s37
	v_lshl_add_u64 v[140:141], s[30:31], 0, v[128:129]
	s_mov_b32 m0, s26
	ds_read_b128 v[180:183], v147 offset:16384
	ds_read_b128 v[184:187], v147 offset:17408
	ds_read_b128 v[188:191], v147 offset:18432
	ds_read_b128 v[192:195], v147 offset:19456
	ds_read_b128 v[196:199], v147 offset:20480
	ds_read_b128 v[200:203], v147 offset:21504
	ds_read_b128 v[204:207], v147 offset:22528
	ds_read_b128 v[208:211], v147 offset:23552
	global_load_lds_dwordx4 v[140:141], off
	s_add_i32 m0, s26, 0x2000
	s_add_u32 s26, s30, 0xb0000
	v_lshl_add_u64 v[212:213], s[30:31], 0, v[130:131]
	s_addc_u32 s27, s31, 0
	s_add_i32 s57, s49, s37
	global_load_lds_dwordx4 v[212:213], off
	v_lshl_add_u64 v[214:215], s[26:27], 0, v[128:129]
	s_mov_b32 m0, s57
	v_lshl_add_u64 v[216:217], s[34:35], 0, v[130:131]
	global_load_lds_dwordx4 v[214:215], off
	v_lshl_add_u64 v[214:215], s[26:27], 0, v[130:131]
	s_add_i32 m0, s57, 0x2000
	s_nop 0
	global_load_lds_dwordx4 v[214:215], off
	v_lshl_add_u64 v[214:215], s[34:35], 0, v[128:129]
	s_mov_b32 m0, s40
	s_nop 0
	global_load_lds_dwordx4 v[214:215], off
	s_mov_b32 m0, s41
	s_nop 0
	global_load_lds_dwordx4 v[216:217], off
	s_waitcnt vmcnt(8)
	s_waitcnt lgkmcnt(0)
	s_barrier
	s_setprio 1
	s_waitcnt lgkmcnt(0)
	v_mfma_f32_16x16x32_bf16 v[60:63], v[148:151], v[180:183], v[60:63]
	v_mfma_f32_16x16x32_bf16 v[56:59], v[156:159], v[180:183], v[56:59]
	v_mfma_f32_16x16x32_bf16 v[48:51], v[148:151], v[188:191], v[48:51]
	v_mfma_f32_16x16x32_bf16 v[44:47], v[156:159], v[188:191], v[44:47]
	v_mfma_f32_16x16x32_bf16 v[32:35], v[148:151], v[196:199], v[32:35]
	v_mfma_f32_16x16x32_bf16 v[28:31], v[156:159], v[196:199], v[28:31]
	v_mfma_f32_16x16x32_bf16 v[16:19], v[148:151], v[204:207], v[16:19]
	v_mfma_f32_16x16x32_bf16 v[12:15], v[156:159], v[204:207], v[12:15]
	v_mfma_f32_16x16x32_bf16 v[60:63], v[152:155], v[184:187], v[60:63]
	v_mfma_f32_16x16x32_bf16 v[56:59], v[160:163], v[184:187], v[56:59]
	v_mfma_f32_16x16x32_bf16 v[48:51], v[152:155], v[192:195], v[48:51]
	v_mfma_f32_16x16x32_bf16 v[44:47], v[160:163], v[192:195], v[44:47]
	v_mfma_f32_16x16x32_bf16 v[32:35], v[152:155], v[200:203], v[32:35]
	v_mfma_f32_16x16x32_bf16 v[28:31], v[160:163], v[200:203], v[28:31]
	v_mfma_f32_16x16x32_bf16 v[16:19], v[152:155], v[208:211], v[16:19]
	v_mfma_f32_16x16x32_bf16 v[12:15], v[160:163], v[208:211], v[12:15]
	s_setprio 0
	s_setprio 1
	v_mfma_f32_16x16x32_bf16 v[52:55], v[164:167], v[180:183], v[52:55]
	v_mfma_f32_16x16x32_bf16 v[40:43], v[172:175], v[180:183], v[40:43]
	v_mfma_f32_16x16x32_bf16 v[36:39], v[164:167], v[188:191], v[36:39]
	v_mfma_f32_16x16x32_bf16 v[24:27], v[172:175], v[188:191], v[24:27]
	v_mfma_f32_16x16x32_bf16 v[20:23], v[164:167], v[196:199], v[20:23]
	v_mfma_f32_16x16x32_bf16 v[8:11], v[172:175], v[196:199], v[8:11]
	v_mfma_f32_16x16x32_bf16 v[4:7], v[164:167], v[204:207], v[4:7]
	v_mfma_f32_16x16x32_bf16 v[0:3], v[172:175], v[204:207], v[0:3]
	v_mfma_f32_16x16x32_bf16 v[52:55], v[168:171], v[184:187], v[52:55]
	v_mfma_f32_16x16x32_bf16 v[40:43], v[176:179], v[184:187], v[40:43]
	v_mfma_f32_16x16x32_bf16 v[36:39], v[168:171], v[192:195], v[36:39]
	v_mfma_f32_16x16x32_bf16 v[24:27], v[176:179], v[192:195], v[24:27]
	v_mfma_f32_16x16x32_bf16 v[20:23], v[168:171], v[200:203], v[20:23]
	v_mfma_f32_16x16x32_bf16 v[8:11], v[176:179], v[200:203], v[8:11]
	v_mfma_f32_16x16x32_bf16 v[4:7], v[168:171], v[208:211], v[4:7]
	v_mfma_f32_16x16x32_bf16 v[0:3], v[176:179], v[208:211], v[0:3]
	s_setprio 0
	s_barrier
	s_add_i32 s57, 0, 0x18000
	s_add_i32 s58, 0, 0x1c000
	v_add_u32_e32 v160, s57, v143
	v_add_u32_e32 v176, s58, v143
	ds_read_b128 v[148:151], v160
	ds_read_b128 v[152:155], v160 offset:1024
	ds_read_b128 v[156:159], v160 offset:2048
	ds_read_b128 v[160:163], v160 offset:3072
	ds_read_b128 v[164:167], v176
	ds_read_b128 v[168:171], v176 offset:1024
	ds_read_b128 v[172:175], v176 offset:2048
	ds_read_b128 v[176:179], v176 offset:3072
	s_add_u32 s26, s34, 0xb0000
	s_addc_u32 s27, s35, 0
	s_mov_b32 m0, s42
	v_lshl_add_u64 v[218:219], s[26:27], 0, v[128:129]
	ds_read_b128 v[180:183], v147 offset:32768
	ds_read_b128 v[184:187], v147 offset:33792
	ds_read_b128 v[188:191], v147 offset:34816
	ds_read_b128 v[192:195], v147 offset:35840
	ds_read_b128 v[196:199], v147 offset:36864
	ds_read_b128 v[200:203], v147 offset:37888
	ds_read_b128 v[204:207], v147 offset:38912
	ds_read_b128 v[208:211], v147 offset:39936
	global_load_lds_dwordx4 v[218:219], off
	v_lshl_add_u64 v[218:219], s[26:27], 0, v[130:131]
	s_mov_b32 m0, s43
	s_nop 0
	global_load_lds_dwordx4 v[218:219], off
	s_waitcnt vmcnt(8)
	s_waitcnt lgkmcnt(0)
	s_barrier
	s_setprio 1
	s_waitcnt lgkmcnt(0)
	v_mfma_f32_16x16x32_bf16 v[124:127], v[148:151], v[180:183], v[124:127]
	v_mfma_f32_16x16x32_bf16 v[120:123], v[156:159], v[180:183], v[120:123]
	v_mfma_f32_16x16x32_bf16 v[112:115], v[148:151], v[188:191], v[112:115]
	v_mfma_f32_16x16x32_bf16 v[108:111], v[156:159], v[188:191], v[108:111]
	v_mfma_f32_16x16x32_bf16 v[96:99], v[148:151], v[196:199], v[96:99]
	v_mfma_f32_16x16x32_bf16 v[92:95], v[156:159], v[196:199], v[92:95]
	v_mfma_f32_16x16x32_bf16 v[80:83], v[148:151], v[204:207], v[80:83]
	v_mfma_f32_16x16x32_bf16 v[76:79], v[156:159], v[204:207], v[76:79]
	v_mfma_f32_16x16x32_bf16 v[124:127], v[152:155], v[184:187], v[124:127]
	v_mfma_f32_16x16x32_bf16 v[120:123], v[160:163], v[184:187], v[120:123]
	v_mfma_f32_16x16x32_bf16 v[112:115], v[152:155], v[192:195], v[112:115]
	v_mfma_f32_16x16x32_bf16 v[108:111], v[160:163], v[192:195], v[108:111]
	v_mfma_f32_16x16x32_bf16 v[96:99], v[152:155], v[200:203], v[96:99]
	v_mfma_f32_16x16x32_bf16 v[92:95], v[160:163], v[200:203], v[92:95]
	v_mfma_f32_16x16x32_bf16 v[80:83], v[152:155], v[208:211], v[80:83]
	v_mfma_f32_16x16x32_bf16 v[76:79], v[160:163], v[208:211], v[76:79]
	s_setprio 0
	s_setprio 1
	v_mfma_f32_16x16x32_bf16 v[116:119], v[164:167], v[180:183], v[116:119]
	v_mfma_f32_16x16x32_bf16 v[104:107], v[172:175], v[180:183], v[104:107]
	v_mfma_f32_16x16x32_bf16 v[100:103], v[164:167], v[188:191], v[100:103]
	v_mfma_f32_16x16x32_bf16 v[88:91], v[172:175], v[188:191], v[88:91]
	v_mfma_f32_16x16x32_bf16 v[84:87], v[164:167], v[196:199], v[84:87]
	v_mfma_f32_16x16x32_bf16 v[72:75], v[172:175], v[196:199], v[72:75]
	v_mfma_f32_16x16x32_bf16 v[68:71], v[164:167], v[204:207], v[68:71]
	v_mfma_f32_16x16x32_bf16 v[64:67], v[172:175], v[204:207], v[64:67]
	v_mfma_f32_16x16x32_bf16 v[116:119], v[168:171], v[184:187], v[116:119]
	v_mfma_f32_16x16x32_bf16 v[104:107], v[176:179], v[184:187], v[104:107]
	v_mfma_f32_16x16x32_bf16 v[100:103], v[168:171], v[192:195], v[100:103]
	v_mfma_f32_16x16x32_bf16 v[88:91], v[176:179], v[192:195], v[88:91]
	v_mfma_f32_16x16x32_bf16 v[84:87], v[168:171], v[200:203], v[84:87]
	v_mfma_f32_16x16x32_bf16 v[72:75], v[176:179], v[200:203], v[72:75]
	v_mfma_f32_16x16x32_bf16 v[68:71], v[168:171], v[208:211], v[68:71]
	v_mfma_f32_16x16x32_bf16 v[64:67], v[176:179], v[208:211], v[64:67]
	s_setprio 0
	s_barrier
	s_add_i32 s26, s57, s37
	v_lshl_add_u64 v[140:141], v[140:141], 0, s[14:15]
	s_mov_b32 m0, s26
	ds_read_b128 v[180:183], v147 offset:49152
	ds_read_b128 v[184:187], v147 offset:50176
	ds_read_b128 v[188:191], v147 offset:51200
	ds_read_b128 v[192:195], v147 offset:52224
	ds_read_b128 v[196:199], v147 offset:53248
	ds_read_b128 v[200:203], v147 offset:54272
	ds_read_b128 v[204:207], v147 offset:55296
	ds_read_b128 v[208:211], v147 offset:56320
	global_load_lds_dwordx4 v[140:141], off
	s_add_i32 m0, s26, 0x2000
	s_add_u32 s26, s30, 0xb0080
	v_lshl_add_u64 v[140:141], v[212:213], 0, s[14:15]
	s_addc_u32 s27, s31, 0
	s_add_i32 s30, s58, s37
	global_load_lds_dwordx4 v[140:141], off
	v_lshl_add_u64 v[140:141], s[26:27], 0, v[128:129]
	s_mov_b32 m0, s30
	s_nop 0
	global_load_lds_dwordx4 v[140:141], off
	v_lshl_add_u64 v[140:141], s[26:27], 0, v[130:131]
	s_add_i32 m0, s30, 0x2000
	s_nop 0
	global_load_lds_dwordx4 v[140:141], off
	v_lshl_add_u64 v[140:141], v[214:215], 0, s[14:15]
	s_mov_b32 m0, s45
	s_nop 0
	global_load_lds_dwordx4 v[140:141], off
	v_lshl_add_u64 v[140:141], v[216:217], 0, s[14:15]
	s_mov_b32 m0, s46
	s_nop 0
	global_load_lds_dwordx4 v[140:141], off
	s_waitcnt vmcnt(8)
	s_waitcnt lgkmcnt(0)
	s_barrier
	s_setprio 1
	s_waitcnt lgkmcnt(0)
	v_mfma_f32_16x16x32_bf16 v[60:63], v[148:151], v[180:183], v[60:63]
	v_mfma_f32_16x16x32_bf16 v[56:59], v[156:159], v[180:183], v[56:59]
	v_mfma_f32_16x16x32_bf16 v[48:51], v[148:151], v[188:191], v[48:51]
	v_mfma_f32_16x16x32_bf16 v[44:47], v[156:159], v[188:191], v[44:47]
	v_mfma_f32_16x16x32_bf16 v[32:35], v[148:151], v[196:199], v[32:35]
	v_mfma_f32_16x16x32_bf16 v[28:31], v[156:159], v[196:199], v[28:31]
	v_mfma_f32_16x16x32_bf16 v[16:19], v[148:151], v[204:207], v[16:19]
	v_mfma_f32_16x16x32_bf16 v[12:15], v[156:159], v[204:207], v[12:15]
	v_mfma_f32_16x16x32_bf16 v[60:63], v[152:155], v[184:187], v[60:63]
	v_mfma_f32_16x16x32_bf16 v[56:59], v[160:163], v[184:187], v[56:59]
	v_mfma_f32_16x16x32_bf16 v[48:51], v[152:155], v[192:195], v[48:51]
	v_mfma_f32_16x16x32_bf16 v[44:47], v[160:163], v[192:195], v[44:47]
	v_mfma_f32_16x16x32_bf16 v[32:35], v[152:155], v[200:203], v[32:35]
	v_mfma_f32_16x16x32_bf16 v[28:31], v[160:163], v[200:203], v[28:31]
	v_mfma_f32_16x16x32_bf16 v[16:19], v[152:155], v[208:211], v[16:19]
	v_mfma_f32_16x16x32_bf16 v[12:15], v[160:163], v[208:211], v[12:15]
	s_setprio 0
	s_setprio 1
	v_mfma_f32_16x16x32_bf16 v[52:55], v[164:167], v[180:183], v[52:55]
	v_mfma_f32_16x16x32_bf16 v[40:43], v[172:175], v[180:183], v[40:43]
	v_mfma_f32_16x16x32_bf16 v[36:39], v[164:167], v[188:191], v[36:39]
	v_mfma_f32_16x16x32_bf16 v[24:27], v[172:175], v[188:191], v[24:27]
	v_mfma_f32_16x16x32_bf16 v[20:23], v[164:167], v[196:199], v[20:23]
	v_mfma_f32_16x16x32_bf16 v[8:11], v[172:175], v[196:199], v[8:11]
	v_mfma_f32_16x16x32_bf16 v[4:7], v[164:167], v[204:207], v[4:7]
	v_mfma_f32_16x16x32_bf16 v[0:3], v[172:175], v[204:207], v[0:3]
	v_mfma_f32_16x16x32_bf16 v[52:55], v[168:171], v[184:187], v[52:55]
	v_mfma_f32_16x16x32_bf16 v[40:43], v[176:179], v[184:187], v[40:43]
	v_mfma_f32_16x16x32_bf16 v[36:39], v[168:171], v[192:195], v[36:39]
	v_mfma_f32_16x16x32_bf16 v[24:27], v[176:179], v[192:195], v[24:27]
	v_mfma_f32_16x16x32_bf16 v[20:23], v[168:171], v[200:203], v[20:23]
	v_mfma_f32_16x16x32_bf16 v[8:11], v[176:179], v[200:203], v[8:11]
	v_mfma_f32_16x16x32_bf16 v[4:7], v[168:171], v[208:211], v[4:7]
	v_mfma_f32_16x16x32_bf16 v[0:3], v[176:179], v[208:211], v[0:3]
	s_setprio 0
	s_add_i32 s56, s56, 2
	s_add_u32 s54, s54, 0x100
	s_addc_u32 s55, s55, 0
	s_cmp_gt_u32 s56, 41
	s_mov_b64 s[26:27], s[28:29]
	s_barrier
	s_cbranch_scc0 .LBB0_247
	s_and_b64 vcc, exec, s[16:17]
	s_cbranch_vccz .LBB0_250
	s_barrier

.LBB0_340:
	ds_read_b128 v[128:131], v143
	ds_read_b128 v[150:153], v143 offset:1024
	ds_read_b128 v[154:157], v143 offset:2048
	ds_read_b128 v[164:167], v143 offset:3072
	ds_read_b128 v[168:171], v162
	ds_read_b128 v[172:175], v162 offset:1024
	ds_read_b128 v[176:179], v162 offset:2048
	ds_read_b128 v[180:183], v162 offset:3072
	s_add_i32 s86, s48, 2
	s_add_u32 s49, s46, 0xfff80080
	s_addc_u32 s50, s47, -1
	s_cmp_eq_u32 s83, s48
	s_cselect_b32 s48, s81, s84
	s_cselect_b32 s51, s3, s50
	s_cselect_b32 s50, s35, s49
	s_cselect_b32 s49, s37, s85
	v_lshl_add_u64 v[158:159], s[46:47], 0, v[146:147]
	s_add_i32 m0, s56, 0xc000
	ds_read_b128 v[184:187], v163
	ds_read_b128 v[188:191], v163 offset:1024
	ds_read_b128 v[192:195], v163 offset:2048
	ds_read_b128 v[196:199], v163 offset:3072
	ds_read_b128 v[200:203], v163 offset:4096
	ds_read_b128 v[204:207], v163 offset:5120
	ds_read_b128 v[208:211], v163 offset:6144
	ds_read_b128 v[212:215], v163 offset:7168
	global_load_lds_dwordx4 v[158:159], off
	v_lshl_add_u64 v[158:159], s[46:47], 0, v[148:149]
	s_add_i32 m0, s56, 0xe000
	s_nop 0
	global_load_lds_dwordx4 v[158:159], off
	s_waitcnt vmcnt(8)
	s_waitcnt lgkmcnt(0)
	s_barrier
	s_setprio 1
	s_waitcnt lgkmcnt(0)
	v_mfma_f32_16x16x32_bf16 v[124:127], v[128:131], v[184:187], v[124:127]
	v_mfma_f32_16x16x32_bf16 v[120:123], v[154:157], v[184:187], v[120:123]
	v_mfma_f32_16x16x32_bf16 v[116:119], v[128:131], v[192:195], v[116:119]
	v_mfma_f32_16x16x32_bf16 v[108:111], v[154:157], v[192:195], v[108:111]
	v_mfma_f32_16x16x32_bf16 v[100:103], v[128:131], v[200:203], v[100:103]
	v_mfma_f32_16x16x32_bf16 v[92:95], v[154:157], v[200:203], v[92:95]
	v_mfma_f32_16x16x32_bf16 v[84:87], v[128:131], v[208:211], v[84:87]
	v_mfma_f32_16x16x32_bf16 v[76:79], v[154:157], v[208:211], v[76:79]
	v_mfma_f32_16x16x32_bf16 v[124:127], v[150:153], v[188:191], v[124:127]
	v_mfma_f32_16x16x32_bf16 v[120:123], v[164:167], v[188:191], v[120:123]
	v_mfma_f32_16x16x32_bf16 v[116:119], v[150:153], v[196:199], v[116:119]
	v_mfma_f32_16x16x32_bf16 v[108:111], v[164:167], v[196:199], v[108:111]
	v_mfma_f32_16x16x32_bf16 v[100:103], v[150:153], v[204:207], v[100:103]
	v_mfma_f32_16x16x32_bf16 v[92:95], v[164:167], v[204:207], v[92:95]
	v_mfma_f32_16x16x32_bf16 v[84:87], v[150:153], v[212:215], v[84:87]
	v_mfma_f32_16x16x32_bf16 v[76:79], v[164:167], v[212:215], v[76:79]
	s_setprio 0
	s_setprio 1
	v_mfma_f32_16x16x32_bf16 v[112:115], v[168:171], v[184:187], v[112:115]
	v_mfma_f32_16x16x32_bf16 v[104:107], v[176:179], v[184:187], v[104:107]
	v_mfma_f32_16x16x32_bf16 v[96:99], v[168:171], v[192:195], v[96:99]
	v_mfma_f32_16x16x32_bf16 v[88:91], v[176:179], v[192:195], v[88:91]
	v_mfma_f32_16x16x32_bf16 v[80:83], v[168:171], v[200:203], v[80:83]
	v_mfma_f32_16x16x32_bf16 v[72:75], v[176:179], v[200:203], v[72:75]
	v_mfma_f32_16x16x32_bf16 v[68:71], v[168:171], v[208:211], v[68:71]
	v_mfma_f32_16x16x32_bf16 v[64:67], v[176:179], v[208:211], v[64:67]
	v_mfma_f32_16x16x32_bf16 v[112:115], v[172:175], v[188:191], v[112:115]
	v_mfma_f32_16x16x32_bf16 v[104:107], v[180:183], v[188:191], v[104:107]
	v_mfma_f32_16x16x32_bf16 v[96:99], v[172:175], v[196:199], v[96:99]
	v_mfma_f32_16x16x32_bf16 v[88:91], v[180:183], v[196:199], v[88:91]
	v_mfma_f32_16x16x32_bf16 v[80:83], v[172:175], v[204:207], v[80:83]
	v_mfma_f32_16x16x32_bf16 v[72:75], v[180:183], v[204:207], v[72:75]
	v_mfma_f32_16x16x32_bf16 v[68:71], v[172:175], v[212:215], v[68:71]
	v_mfma_f32_16x16x32_bf16 v[64:67], v[180:183], v[212:215], v[64:67]
	s_setprio 0
	s_barrier
	s_add_i32 s87, s65, s55
	v_lshl_add_u64 v[158:159], s[48:49], 0, v[134:135]
	s_mov_b32 m0, s87
	ds_read_b128 v[184:187], v163 offset:16384
	ds_read_b128 v[188:191], v163 offset:17408
	ds_read_b128 v[192:195], v163 offset:18432
	ds_read_b128 v[196:199], v163 offset:19456
	ds_read_b128 v[200:203], v163 offset:20480
	ds_read_b128 v[204:207], v163 offset:21504
	ds_read_b128 v[208:211], v163 offset:22528
	ds_read_b128 v[212:215], v163 offset:23552
	global_load_lds_dwordx4 v[158:159], off
	s_add_i32 m0, s87, 0x2000
	s_add_u32 s88, s48, 0x80000
	v_lshl_add_u64 v[216:217], s[48:49], 0, v[138:139]
	s_addc_u32 s89, s49, 0
	s_add_i32 s87, s66, s55
	global_load_lds_dwordx4 v[216:217], off
	v_lshl_add_u64 v[218:219], s[88:89], 0, v[134:135]
	s_mov_b32 m0, s87
	v_lshl_add_u64 v[220:221], s[50:51], 0, v[136:137]
	global_load_lds_dwordx4 v[218:219], off
	v_lshl_add_u64 v[218:219], s[88:89], 0, v[138:139]
	s_add_i32 m0, s87, 0x2000
	s_nop 0
	global_load_lds_dwordx4 v[218:219], off
	v_lshl_add_u64 v[218:219], s[50:51], 0, v[132:133]
	s_mov_b32 m0, s56
	s_nop 0
	global_load_lds_dwordx4 v[218:219], off
	s_mov_b32 m0, s57
	s_nop 0
	global_load_lds_dwordx4 v[220:221], off
	s_waitcnt vmcnt(8)
	s_waitcnt lgkmcnt(0)
	s_barrier
	s_setprio 1
	s_waitcnt lgkmcnt(0)
	v_mfma_f32_16x16x32_bf16 v[60:63], v[128:131], v[184:187], v[60:63]
	v_mfma_f32_16x16x32_bf16 v[56:59], v[154:157], v[184:187], v[56:59]
	v_mfma_f32_16x16x32_bf16 v[52:55], v[128:131], v[192:195], v[52:55]
	v_mfma_f32_16x16x32_bf16 v[44:47], v[154:157], v[192:195], v[44:47]
	v_mfma_f32_16x16x32_bf16 v[36:39], v[128:131], v[200:203], v[36:39]
	v_mfma_f32_16x16x32_bf16 v[28:31], v[154:157], v[200:203], v[28:31]
	v_mfma_f32_16x16x32_bf16 v[20:23], v[128:131], v[208:211], v[20:23]
	v_mfma_f32_16x16x32_bf16 v[12:15], v[154:157], v[208:211], v[12:15]
	v_mfma_f32_16x16x32_bf16 v[60:63], v[150:153], v[188:191], v[60:63]
	v_mfma_f32_16x16x32_bf16 v[56:59], v[164:167], v[188:191], v[56:59]
	v_mfma_f32_16x16x32_bf16 v[52:55], v[150:153], v[196:199], v[52:55]
	v_mfma_f32_16x16x32_bf16 v[44:47], v[164:167], v[196:199], v[44:47]
	v_mfma_f32_16x16x32_bf16 v[36:39], v[150:153], v[204:207], v[36:39]
	v_mfma_f32_16x16x32_bf16 v[28:31], v[164:167], v[204:207], v[28:31]
	v_mfma_f32_16x16x32_bf16 v[20:23], v[150:153], v[212:215], v[20:23]
	v_mfma_f32_16x16x32_bf16 v[12:15], v[164:167], v[212:215], v[12:15]
	s_setprio 0
	s_setprio 1
	v_mfma_f32_16x16x32_bf16 v[48:51], v[168:171], v[184:187], v[48:51]
	v_mfma_f32_16x16x32_bf16 v[40:43], v[176:179], v[184:187], v[40:43]
	v_mfma_f32_16x16x32_bf16 v[32:35], v[168:171], v[192:195], v[32:35]
	v_mfma_f32_16x16x32_bf16 v[24:27], v[176:179], v[192:195], v[24:27]
	v_mfma_f32_16x16x32_bf16 v[16:19], v[168:171], v[200:203], v[16:19]
	v_mfma_f32_16x16x32_bf16 v[8:11], v[176:179], v[200:203], v[8:11]
	v_mfma_f32_16x16x32_bf16 v[4:7], v[168:171], v[208:211], v[4:7]
	v_mfma_f32_16x16x32_bf16 v[0:3], v[176:179], v[208:211], v[0:3]
	v_mfma_f32_16x16x32_bf16 v[48:51], v[172:175], v[188:191], v[48:51]
	v_mfma_f32_16x16x32_bf16 v[40:43], v[180:183], v[188:191], v[40:43]
	v_mfma_f32_16x16x32_bf16 v[32:35], v[172:175], v[196:199], v[32:35]
	v_mfma_f32_16x16x32_bf16 v[24:27], v[180:183], v[196:199], v[24:27]
	v_mfma_f32_16x16x32_bf16 v[16:19], v[172:175], v[204:207], v[16:19]
	v_mfma_f32_16x16x32_bf16 v[8:11], v[180:183], v[204:207], v[8:11]
	v_mfma_f32_16x16x32_bf16 v[4:7], v[172:175], v[212:215], v[4:7]
	v_mfma_f32_16x16x32_bf16 v[0:3], v[180:183], v[212:215], v[0:3]
	s_setprio 0
	s_barrier
	s_add_i32 s87, 0, 0x18000
	v_add_u32_e32 v140, s87, v161
	s_add_i32 s88, 0, 0x1c000
	ds_read_b128 v[128:131], v140
	ds_read_b128 v[150:153], v140 offset:1024
	ds_read_b128 v[154:157], v140 offset:2048
	ds_read_b128 v[164:167], v140 offset:3072
	v_add_u32_e32 v140, s88, v161
	ds_read_b128 v[168:171], v140
	ds_read_b128 v[172:175], v140 offset:1024
	ds_read_b128 v[176:179], v140 offset:2048
	ds_read_b128 v[180:183], v140 offset:3072
	s_add_u32 s50, s50, 0x80000
	s_addc_u32 s51, s51, 0
	s_mov_b32 m0, s58
	v_lshl_add_u64 v[222:223], s[50:51], 0, v[132:133]
	ds_read_b128 v[184:187], v163 offset:32768
	ds_read_b128 v[188:191], v163 offset:33792
	ds_read_b128 v[192:195], v163 offset:34816
	ds_read_b128 v[196:199], v163 offset:35840
	ds_read_b128 v[200:203], v163 offset:36864
	ds_read_b128 v[204:207], v163 offset:37888
	ds_read_b128 v[208:211], v163 offset:38912
	ds_read_b128 v[212:215], v163 offset:39936
	global_load_lds_dwordx4 v[222:223], off
	v_lshl_add_u64 v[222:223], s[50:51], 0, v[136:137]
	s_mov_b32 m0, s59
	s_nop 0
	global_load_lds_dwordx4 v[222:223], off
	s_waitcnt vmcnt(8)
	s_waitcnt lgkmcnt(0)
	s_barrier
	s_setprio 1
	s_waitcnt lgkmcnt(0)
	v_mfma_f32_16x16x32_bf16 v[124:127], v[128:131], v[184:187], v[124:127]
	v_mfma_f32_16x16x32_bf16 v[120:123], v[154:157], v[184:187], v[120:123]
	v_mfma_f32_16x16x32_bf16 v[116:119], v[128:131], v[192:195], v[116:119]
	v_mfma_f32_16x16x32_bf16 v[108:111], v[154:157], v[192:195], v[108:111]
	v_mfma_f32_16x16x32_bf16 v[100:103], v[128:131], v[200:203], v[100:103]
	v_mfma_f32_16x16x32_bf16 v[92:95], v[154:157], v[200:203], v[92:95]
	v_mfma_f32_16x16x32_bf16 v[84:87], v[128:131], v[208:211], v[84:87]
	v_mfma_f32_16x16x32_bf16 v[76:79], v[154:157], v[208:211], v[76:79]
	v_mfma_f32_16x16x32_bf16 v[124:127], v[150:153], v[188:191], v[124:127]
	v_mfma_f32_16x16x32_bf16 v[120:123], v[164:167], v[188:191], v[120:123]
	v_mfma_f32_16x16x32_bf16 v[116:119], v[150:153], v[196:199], v[116:119]
	v_mfma_f32_16x16x32_bf16 v[108:111], v[164:167], v[196:199], v[108:111]
	v_mfma_f32_16x16x32_bf16 v[100:103], v[150:153], v[204:207], v[100:103]
	v_mfma_f32_16x16x32_bf16 v[92:95], v[164:167], v[204:207], v[92:95]
	v_mfma_f32_16x16x32_bf16 v[84:87], v[150:153], v[212:215], v[84:87]
	v_mfma_f32_16x16x32_bf16 v[76:79], v[164:167], v[212:215], v[76:79]
	s_setprio 0
	s_setprio 1
	v_mfma_f32_16x16x32_bf16 v[112:115], v[168:171], v[184:187], v[112:115]
	v_mfma_f32_16x16x32_bf16 v[104:107], v[176:179], v[184:187], v[104:107]
	v_mfma_f32_16x16x32_bf16 v[96:99], v[168:171], v[192:195], v[96:99]
	v_mfma_f32_16x16x32_bf16 v[88:91], v[176:179], v[192:195], v[88:91]
	v_mfma_f32_16x16x32_bf16 v[80:83], v[168:171], v[200:203], v[80:83]
	v_mfma_f32_16x16x32_bf16 v[72:75], v[176:179], v[200:203], v[72:75]
	v_mfma_f32_16x16x32_bf16 v[68:71], v[168:171], v[208:211], v[68:71]
	v_mfma_f32_16x16x32_bf16 v[64:67], v[176:179], v[208:211], v[64:67]
	v_mfma_f32_16x16x32_bf16 v[112:115], v[172:175], v[188:191], v[112:115]
	v_mfma_f32_16x16x32_bf16 v[104:107], v[180:183], v[188:191], v[104:107]
	v_mfma_f32_16x16x32_bf16 v[96:99], v[172:175], v[196:199], v[96:99]
	v_mfma_f32_16x16x32_bf16 v[88:91], v[180:183], v[196:199], v[88:91]
	v_mfma_f32_16x16x32_bf16 v[80:83], v[172:175], v[204:207], v[80:83]
	v_mfma_f32_16x16x32_bf16 v[72:75], v[180:183], v[204:207], v[72:75]
	v_mfma_f32_16x16x32_bf16 v[68:71], v[172:175], v[212:215], v[68:71]
	v_mfma_f32_16x16x32_bf16 v[64:67], v[180:183], v[212:215], v[64:67]
	s_setprio 0
	s_barrier
	s_add_i32 s50, s87, s55
	v_lshl_add_u64 v[158:159], v[158:159], 0, s[10:11]
	s_mov_b32 m0, s50
	ds_read_b128 v[184:187], v163 offset:49152
	ds_read_b128 v[188:191], v163 offset:50176
	ds_read_b128 v[192:195], v163 offset:51200
	ds_read_b128 v[196:199], v163 offset:52224
	ds_read_b128 v[200:203], v163 offset:53248
	ds_read_b128 v[204:207], v163 offset:54272
	ds_read_b128 v[208:211], v163 offset:55296
	ds_read_b128 v[212:215], v163 offset:56320
	global_load_lds_dwordx4 v[158:159], off
	s_add_i32 m0, s50, 0x2000
	s_add_u32 s48, s48, 0x80080
	v_lshl_add_u64 v[158:159], v[216:217], 0, s[10:11]
	s_addc_u32 s49, s49, 0
	s_add_i32 s50, s88, s55
	global_load_lds_dwordx4 v[158:159], off
	v_lshl_add_u64 v[158:159], s[48:49], 0, v[134:135]
	s_mov_b32 m0, s50
	s_nop 0
	global_load_lds_dwordx4 v[158:159], off
	v_lshl_add_u64 v[158:159], s[48:49], 0, v[138:139]
	s_add_i32 m0, s50, 0x2000
	s_nop 0
	global_load_lds_dwordx4 v[158:159], off
	v_lshl_add_u64 v[158:159], v[218:219], 0, s[10:11]
	s_mov_b32 m0, s63
	s_nop 0
	global_load_lds_dwordx4 v[158:159], off
	v_lshl_add_u64 v[158:159], v[220:221], 0, s[10:11]
	s_mov_b32 m0, s64
	s_nop 0
	global_load_lds_dwordx4 v[158:159], off
	s_waitcnt vmcnt(8)
	s_waitcnt lgkmcnt(0)
	s_barrier
	s_setprio 1
	s_waitcnt lgkmcnt(0)
	v_mfma_f32_16x16x32_bf16 v[60:63], v[128:131], v[184:187], v[60:63]
	v_mfma_f32_16x16x32_bf16 v[56:59], v[154:157], v[184:187], v[56:59]
	v_mfma_f32_16x16x32_bf16 v[52:55], v[128:131], v[192:195], v[52:55]
	v_mfma_f32_16x16x32_bf16 v[44:47], v[154:157], v[192:195], v[44:47]
	v_mfma_f32_16x16x32_bf16 v[36:39], v[128:131], v[200:203], v[36:39]
	v_mfma_f32_16x16x32_bf16 v[28:31], v[154:157], v[200:203], v[28:31]
	v_mfma_f32_16x16x32_bf16 v[20:23], v[128:131], v[208:211], v[20:23]
	v_mfma_f32_16x16x32_bf16 v[12:15], v[154:157], v[208:211], v[12:15]
	v_mfma_f32_16x16x32_bf16 v[60:63], v[150:153], v[188:191], v[60:63]
	v_mfma_f32_16x16x32_bf16 v[56:59], v[164:167], v[188:191], v[56:59]
	v_mfma_f32_16x16x32_bf16 v[52:55], v[150:153], v[196:199], v[52:55]
	v_mfma_f32_16x16x32_bf16 v[44:47], v[164:167], v[196:199], v[44:47]
	v_mfma_f32_16x16x32_bf16 v[36:39], v[150:153], v[204:207], v[36:39]
	v_mfma_f32_16x16x32_bf16 v[28:31], v[164:167], v[204:207], v[28:31]
	v_mfma_f32_16x16x32_bf16 v[20:23], v[150:153], v[212:215], v[20:23]
	v_mfma_f32_16x16x32_bf16 v[12:15], v[164:167], v[212:215], v[12:15]
	s_setprio 0
	s_setprio 1
	v_mfma_f32_16x16x32_bf16 v[48:51], v[168:171], v[184:187], v[48:51]
	v_mfma_f32_16x16x32_bf16 v[40:43], v[176:179], v[184:187], v[40:43]
	v_mfma_f32_16x16x32_bf16 v[32:35], v[168:171], v[192:195], v[32:35]
	v_mfma_f32_16x16x32_bf16 v[24:27], v[176:179], v[192:195], v[24:27]
	v_mfma_f32_16x16x32_bf16 v[16:19], v[168:171], v[200:203], v[16:19]
	v_mfma_f32_16x16x32_bf16 v[8:11], v[176:179], v[200:203], v[8:11]
	v_mfma_f32_16x16x32_bf16 v[4:7], v[168:171], v[208:211], v[4:7]
	v_mfma_f32_16x16x32_bf16 v[0:3], v[176:179], v[208:211], v[0:3]
	v_mfma_f32_16x16x32_bf16 v[48:51], v[172:175], v[188:191], v[48:51]
	v_mfma_f32_16x16x32_bf16 v[40:43], v[180:183], v[188:191], v[40:43]
	v_mfma_f32_16x16x32_bf16 v[32:35], v[172:175], v[196:199], v[32:35]
	v_mfma_f32_16x16x32_bf16 v[24:27], v[180:183], v[196:199], v[24:27]
	v_mfma_f32_16x16x32_bf16 v[16:19], v[172:175], v[204:207], v[16:19]
	v_mfma_f32_16x16x32_bf16 v[8:11], v[180:183], v[204:207], v[8:11]
	v_mfma_f32_16x16x32_bf16 v[4:7], v[172:175], v[212:215], v[4:7]
	v_mfma_f32_16x16x32_bf16 v[0:3], v[180:183], v[212:215], v[0:3]
	s_setprio 0
	s_add_u32 s46, s46, 0x100
	s_addc_u32 s47, s47, 0
	s_add_u32 s84, s84, 0x100
	s_addc_u32 s85, s85, 0
	s_cmp_ge_u32 s86, s82
	s_mov_b32 s48, s86
	s_barrier
	s_cbranch_scc0 .LBB0_340
	s_and_b64 vcc, exec, s[12:13]
	s_cbranch_vccz .LBB0_343
	s_barrier

.LBB0_416:
	ds_read_b128 v[152:155], v149
	ds_read_b128 v[156:159], v149 offset:1024
	ds_read_b128 v[160:163], v149 offset:2048
	ds_read_b128 v[164:167], v149 offset:3072
	ds_read_b128 v[168:171], v150
	ds_read_b128 v[172:175], v150 offset:1024
	ds_read_b128 v[176:179], v150 offset:2048
	ds_read_b128 v[180:183], v150 offset:3072
	s_add_u32 s34, s30, 0xfffc0080
	s_addc_u32 s35, s31, -1
	s_cmp_eq_u32 s62, 12
	s_cselect_b32 s37, s23, s35
	s_cselect_b32 s36, s58, s34
	s_cselect_b32 s35, s21, s61
	s_cselect_b32 s34, s59, s60
	v_lshl_add_u64 v[144:145], s[30:31], 0, v[136:137]
	s_add_i32 m0, s29, 0xc000
	ds_read_b128 v[184:187], v151
	ds_read_b128 v[188:191], v151 offset:1024
	ds_read_b128 v[192:195], v151 offset:2048
	ds_read_b128 v[196:199], v151 offset:3072
	ds_read_b128 v[200:203], v151 offset:4096
	ds_read_b128 v[204:207], v151 offset:5120
	ds_read_b128 v[208:211], v151 offset:6144
	ds_read_b128 v[212:215], v151 offset:7168
	global_load_lds_dwordx4 v[144:145], off
	v_lshl_add_u64 v[144:145], s[30:31], 0, v[138:139]
	s_add_i32 m0, s29, 0xe000
	s_nop 0
	global_load_lds_dwordx4 v[144:145], off
	s_waitcnt vmcnt(8)
	s_waitcnt lgkmcnt(0)
	s_barrier
	s_setprio 1
	s_waitcnt lgkmcnt(0)
	v_mfma_f32_16x16x32_bf16 v[124:127], v[152:155], v[184:187], v[124:127]
	v_mfma_f32_16x16x32_bf16 v[120:123], v[160:163], v[184:187], v[120:123]
	v_mfma_f32_16x16x32_bf16 v[116:119], v[152:155], v[192:195], v[116:119]
	v_mfma_f32_16x16x32_bf16 v[108:111], v[160:163], v[192:195], v[108:111]
	v_mfma_f32_16x16x32_bf16 v[100:103], v[152:155], v[200:203], v[100:103]
	v_mfma_f32_16x16x32_bf16 v[92:95], v[160:163], v[200:203], v[92:95]
	v_mfma_f32_16x16x32_bf16 v[84:87], v[152:155], v[208:211], v[84:87]
	v_mfma_f32_16x16x32_bf16 v[76:79], v[160:163], v[208:211], v[76:79]
	v_mfma_f32_16x16x32_bf16 v[124:127], v[156:159], v[188:191], v[124:127]
	v_mfma_f32_16x16x32_bf16 v[120:123], v[164:167], v[188:191], v[120:123]
	v_mfma_f32_16x16x32_bf16 v[116:119], v[156:159], v[196:199], v[116:119]
	v_mfma_f32_16x16x32_bf16 v[108:111], v[164:167], v[196:199], v[108:111]
	v_mfma_f32_16x16x32_bf16 v[100:103], v[156:159], v[204:207], v[100:103]
	v_mfma_f32_16x16x32_bf16 v[92:95], v[164:167], v[204:207], v[92:95]
	v_mfma_f32_16x16x32_bf16 v[84:87], v[156:159], v[212:215], v[84:87]
	v_mfma_f32_16x16x32_bf16 v[76:79], v[164:167], v[212:215], v[76:79]
	s_setprio 0
	s_setprio 1
	v_mfma_f32_16x16x32_bf16 v[112:115], v[168:171], v[184:187], v[112:115]
	v_mfma_f32_16x16x32_bf16 v[104:107], v[176:179], v[184:187], v[104:107]
	v_mfma_f32_16x16x32_bf16 v[96:99], v[168:171], v[192:195], v[96:99]
	v_mfma_f32_16x16x32_bf16 v[88:91], v[176:179], v[192:195], v[88:91]
	v_mfma_f32_16x16x32_bf16 v[80:83], v[168:171], v[200:203], v[80:83]
	v_mfma_f32_16x16x32_bf16 v[72:75], v[176:179], v[200:203], v[72:75]
	v_mfma_f32_16x16x32_bf16 v[68:71], v[168:171], v[208:211], v[68:71]
	v_mfma_f32_16x16x32_bf16 v[64:67], v[176:179], v[208:211], v[64:67]
	v_mfma_f32_16x16x32_bf16 v[112:115], v[172:175], v[188:191], v[112:115]
	v_mfma_f32_16x16x32_bf16 v[104:107], v[180:183], v[188:191], v[104:107]
	v_mfma_f32_16x16x32_bf16 v[96:99], v[172:175], v[196:199], v[96:99]
	v_mfma_f32_16x16x32_bf16 v[88:91], v[180:183], v[196:199], v[88:91]
	v_mfma_f32_16x16x32_bf16 v[80:83], v[172:175], v[204:207], v[80:83]
	v_mfma_f32_16x16x32_bf16 v[72:75], v[180:183], v[204:207], v[72:75]
	v_mfma_f32_16x16x32_bf16 v[68:71], v[172:175], v[212:215], v[68:71]
	v_mfma_f32_16x16x32_bf16 v[64:67], v[180:183], v[212:215], v[64:67]
	s_setprio 0
	s_barrier
	s_add_i32 s63, s51, s43
	v_lshl_add_u64 v[144:145], s[34:35], 0, v[130:131]
	s_mov_b32 m0, s63
	ds_read_b128 v[184:187], v151 offset:16384
	ds_read_b128 v[188:191], v151 offset:17408
	ds_read_b128 v[192:195], v151 offset:18432
	ds_read_b128 v[196:199], v151 offset:19456
	ds_read_b128 v[200:203], v151 offset:20480
	ds_read_b128 v[204:207], v151 offset:21504
	ds_read_b128 v[208:211], v151 offset:22528
	ds_read_b128 v[212:215], v151 offset:23552
	global_load_lds_dwordx4 v[144:145], off
	s_add_i32 m0, s63, 0x2000
	s_add_u32 s64, s34, 0x40000
	v_lshl_add_u64 v[216:217], s[34:35], 0, v[134:135]
	s_addc_u32 s65, s35, 0
	s_add_i32 s63, s52, s43
	global_load_lds_dwordx4 v[216:217], off
	v_lshl_add_u64 v[218:219], s[64:65], 0, v[130:131]
	s_mov_b32 m0, s63
	v_lshl_add_u64 v[220:221], s[36:37], 0, v[132:133]
	global_load_lds_dwordx4 v[218:219], off
	v_lshl_add_u64 v[218:219], s[64:65], 0, v[134:135]
	s_add_i32 m0, s63, 0x2000
	s_nop 0
	global_load_lds_dwordx4 v[218:219], off
	v_lshl_add_u64 v[218:219], s[36:37], 0, v[128:129]
	s_mov_b32 m0, s29
	s_nop 0
	global_load_lds_dwordx4 v[218:219], off
	s_mov_b32 m0, s44
	s_nop 0
	global_load_lds_dwordx4 v[220:221], off
	s_waitcnt vmcnt(8)
	s_waitcnt lgkmcnt(0)
	s_barrier
	s_setprio 1
	s_waitcnt lgkmcnt(0)
	v_mfma_f32_16x16x32_bf16 v[60:63], v[152:155], v[184:187], v[60:63]
	v_mfma_f32_16x16x32_bf16 v[56:59], v[160:163], v[184:187], v[56:59]
	v_mfma_f32_16x16x32_bf16 v[52:55], v[152:155], v[192:195], v[52:55]
	v_mfma_f32_16x16x32_bf16 v[44:47], v[160:163], v[192:195], v[44:47]
	v_mfma_f32_16x16x32_bf16 v[36:39], v[152:155], v[200:203], v[36:39]
	v_mfma_f32_16x16x32_bf16 v[28:31], v[160:163], v[200:203], v[28:31]
	v_mfma_f32_16x16x32_bf16 v[20:23], v[152:155], v[208:211], v[20:23]
	v_mfma_f32_16x16x32_bf16 v[12:15], v[160:163], v[208:211], v[12:15]
	v_mfma_f32_16x16x32_bf16 v[60:63], v[156:159], v[188:191], v[60:63]
	v_mfma_f32_16x16x32_bf16 v[56:59], v[164:167], v[188:191], v[56:59]
	v_mfma_f32_16x16x32_bf16 v[52:55], v[156:159], v[196:199], v[52:55]
	v_mfma_f32_16x16x32_bf16 v[44:47], v[164:167], v[196:199], v[44:47]
	v_mfma_f32_16x16x32_bf16 v[36:39], v[156:159], v[204:207], v[36:39]
	v_mfma_f32_16x16x32_bf16 v[28:31], v[164:167], v[204:207], v[28:31]
	v_mfma_f32_16x16x32_bf16 v[20:23], v[156:159], v[212:215], v[20:23]
	v_mfma_f32_16x16x32_bf16 v[12:15], v[164:167], v[212:215], v[12:15]
	s_setprio 0
	s_setprio 1
	v_mfma_f32_16x16x32_bf16 v[48:51], v[168:171], v[184:187], v[48:51]
	v_mfma_f32_16x16x32_bf16 v[40:43], v[176:179], v[184:187], v[40:43]
	v_mfma_f32_16x16x32_bf16 v[32:35], v[168:171], v[192:195], v[32:35]
	v_mfma_f32_16x16x32_bf16 v[24:27], v[176:179], v[192:195], v[24:27]
	v_mfma_f32_16x16x32_bf16 v[16:19], v[168:171], v[200:203], v[16:19]
	v_mfma_f32_16x16x32_bf16 v[8:11], v[176:179], v[200:203], v[8:11]
	v_mfma_f32_16x16x32_bf16 v[4:7], v[168:171], v[208:211], v[4:7]
	v_mfma_f32_16x16x32_bf16 v[0:3], v[176:179], v[208:211], v[0:3]
	v_mfma_f32_16x16x32_bf16 v[48:51], v[172:175], v[188:191], v[48:51]
	v_mfma_f32_16x16x32_bf16 v[40:43], v[180:183], v[188:191], v[40:43]
	v_mfma_f32_16x16x32_bf16 v[32:35], v[172:175], v[196:199], v[32:35]
	v_mfma_f32_16x16x32_bf16 v[24:27], v[180:183], v[196:199], v[24:27]
	v_mfma_f32_16x16x32_bf16 v[16:19], v[172:175], v[204:207], v[16:19]
	v_mfma_f32_16x16x32_bf16 v[8:11], v[180:183], v[204:207], v[8:11]
	v_mfma_f32_16x16x32_bf16 v[4:7], v[172:175], v[212:215], v[4:7]
	v_mfma_f32_16x16x32_bf16 v[0:3], v[180:183], v[212:215], v[0:3]
	s_setprio 0
	s_barrier
	s_add_i32 s63, 0, 0x18000
	s_add_i32 s64, 0, 0x1c000
	v_add_u32_e32 v164, s63, v147
	v_add_u32_e32 v180, s64, v147
	ds_read_b128 v[152:155], v164
	ds_read_b128 v[156:159], v164 offset:1024
	ds_read_b128 v[160:163], v164 offset:2048
	ds_read_b128 v[164:167], v164 offset:3072
	ds_read_b128 v[168:171], v180
	ds_read_b128 v[172:175], v180 offset:1024
	ds_read_b128 v[176:179], v180 offset:2048
	ds_read_b128 v[180:183], v180 offset:3072
	s_add_u32 s36, s36, 0x40000
	s_addc_u32 s37, s37, 0
	s_mov_b32 m0, s45
	v_lshl_add_u64 v[222:223], s[36:37], 0, v[128:129]
	ds_read_b128 v[184:187], v151 offset:32768
	ds_read_b128 v[188:191], v151 offset:33792
	ds_read_b128 v[192:195], v151 offset:34816
	ds_read_b128 v[196:199], v151 offset:35840
	ds_read_b128 v[200:203], v151 offset:36864
	ds_read_b128 v[204:207], v151 offset:37888
	ds_read_b128 v[208:211], v151 offset:38912
	ds_read_b128 v[212:215], v151 offset:39936
	global_load_lds_dwordx4 v[222:223], off
	v_lshl_add_u64 v[222:223], s[36:37], 0, v[132:133]
	s_mov_b32 m0, s46
	s_nop 0
	global_load_lds_dwordx4 v[222:223], off
	s_waitcnt vmcnt(8)
	s_waitcnt lgkmcnt(0)
	s_barrier
	s_setprio 1
	s_waitcnt lgkmcnt(0)
	v_mfma_f32_16x16x32_bf16 v[124:127], v[152:155], v[184:187], v[124:127]
	v_mfma_f32_16x16x32_bf16 v[120:123], v[160:163], v[184:187], v[120:123]
	v_mfma_f32_16x16x32_bf16 v[116:119], v[152:155], v[192:195], v[116:119]
	v_mfma_f32_16x16x32_bf16 v[108:111], v[160:163], v[192:195], v[108:111]
	v_mfma_f32_16x16x32_bf16 v[100:103], v[152:155], v[200:203], v[100:103]
	v_mfma_f32_16x16x32_bf16 v[92:95], v[160:163], v[200:203], v[92:95]
	v_mfma_f32_16x16x32_bf16 v[84:87], v[152:155], v[208:211], v[84:87]
	v_mfma_f32_16x16x32_bf16 v[76:79], v[160:163], v[208:211], v[76:79]
	v_mfma_f32_16x16x32_bf16 v[124:127], v[156:159], v[188:191], v[124:127]
	v_mfma_f32_16x16x32_bf16 v[120:123], v[164:167], v[188:191], v[120:123]
	v_mfma_f32_16x16x32_bf16 v[116:119], v[156:159], v[196:199], v[116:119]
	v_mfma_f32_16x16x32_bf16 v[108:111], v[164:167], v[196:199], v[108:111]
	v_mfma_f32_16x16x32_bf16 v[100:103], v[156:159], v[204:207], v[100:103]
	v_mfma_f32_16x16x32_bf16 v[92:95], v[164:167], v[204:207], v[92:95]
	v_mfma_f32_16x16x32_bf16 v[84:87], v[156:159], v[212:215], v[84:87]
	v_mfma_f32_16x16x32_bf16 v[76:79], v[164:167], v[212:215], v[76:79]
	s_setprio 0
	s_setprio 1
	v_mfma_f32_16x16x32_bf16 v[112:115], v[168:171], v[184:187], v[112:115]
	v_mfma_f32_16x16x32_bf16 v[104:107], v[176:179], v[184:187], v[104:107]
	v_mfma_f32_16x16x32_bf16 v[96:99], v[168:171], v[192:195], v[96:99]
	v_mfma_f32_16x16x32_bf16 v[88:91], v[176:179], v[192:195], v[88:91]
	v_mfma_f32_16x16x32_bf16 v[80:83], v[168:171], v[200:203], v[80:83]
	v_mfma_f32_16x16x32_bf16 v[72:75], v[176:179], v[200:203], v[72:75]
	v_mfma_f32_16x16x32_bf16 v[68:71], v[168:171], v[208:211], v[68:71]
	v_mfma_f32_16x16x32_bf16 v[64:67], v[176:179], v[208:211], v[64:67]
	v_mfma_f32_16x16x32_bf16 v[112:115], v[172:175], v[188:191], v[112:115]
	v_mfma_f32_16x16x32_bf16 v[104:107], v[180:183], v[188:191], v[104:107]
	v_mfma_f32_16x16x32_bf16 v[96:99], v[172:175], v[196:199], v[96:99]
	v_mfma_f32_16x16x32_bf16 v[88:91], v[180:183], v[196:199], v[88:91]
	v_mfma_f32_16x16x32_bf16 v[80:83], v[172:175], v[204:207], v[80:83]
	v_mfma_f32_16x16x32_bf16 v[72:75], v[180:183], v[204:207], v[72:75]
	v_mfma_f32_16x16x32_bf16 v[68:71], v[172:175], v[212:215], v[68:71]
	v_mfma_f32_16x16x32_bf16 v[64:67], v[180:183], v[212:215], v[64:67]
	s_setprio 0
	s_barrier
	s_add_i32 s36, s63, s43
	v_lshl_add_u64 v[144:145], v[144:145], 0, s[10:11]
	s_mov_b32 m0, s36
	ds_read_b128 v[184:187], v151 offset:49152
	ds_read_b128 v[188:191], v151 offset:50176
	ds_read_b128 v[192:195], v151 offset:51200
	ds_read_b128 v[196:199], v151 offset:52224
	ds_read_b128 v[200:203], v151 offset:53248
	ds_read_b128 v[204:207], v151 offset:54272
	ds_read_b128 v[208:211], v151 offset:55296
	ds_read_b128 v[212:215], v151 offset:56320
	global_load_lds_dwordx4 v[144:145], off
	s_add_i32 m0, s36, 0x2000
	s_add_u32 s34, s34, 0x40080
	v_lshl_add_u64 v[144:145], v[216:217], 0, s[10:11]
	s_addc_u32 s35, s35, 0
	s_add_i32 s36, s64, s43
	global_load_lds_dwordx4 v[144:145], off
	v_lshl_add_u64 v[144:145], s[34:35], 0, v[130:131]
	s_mov_b32 m0, s36
	s_nop 0
	global_load_lds_dwordx4 v[144:145], off
	v_lshl_add_u64 v[144:145], s[34:35], 0, v[134:135]
	s_add_i32 m0, s36, 0x2000
	s_nop 0
	global_load_lds_dwordx4 v[144:145], off
	v_lshl_add_u64 v[144:145], v[218:219], 0, s[10:11]
	s_mov_b32 m0, s48
	s_nop 0
	global_load_lds_dwordx4 v[144:145], off
	v_lshl_add_u64 v[144:145], v[220:221], 0, s[10:11]
	s_mov_b32 m0, s49
	s_nop 0
	global_load_lds_dwordx4 v[144:145], off
	s_waitcnt vmcnt(8)
	s_waitcnt lgkmcnt(0)
	s_barrier
	s_setprio 1
	s_waitcnt lgkmcnt(0)
	v_mfma_f32_16x16x32_bf16 v[60:63], v[152:155], v[184:187], v[60:63]
	v_mfma_f32_16x16x32_bf16 v[56:59], v[160:163], v[184:187], v[56:59]
	v_mfma_f32_16x16x32_bf16 v[52:55], v[152:155], v[192:195], v[52:55]
	v_mfma_f32_16x16x32_bf16 v[44:47], v[160:163], v[192:195], v[44:47]
	v_mfma_f32_16x16x32_bf16 v[36:39], v[152:155], v[200:203], v[36:39]
	v_mfma_f32_16x16x32_bf16 v[28:31], v[160:163], v[200:203], v[28:31]
	v_mfma_f32_16x16x32_bf16 v[20:23], v[152:155], v[208:211], v[20:23]
	v_mfma_f32_16x16x32_bf16 v[12:15], v[160:163], v[208:211], v[12:15]
	v_mfma_f32_16x16x32_bf16 v[60:63], v[156:159], v[188:191], v[60:63]
	v_mfma_f32_16x16x32_bf16 v[56:59], v[164:167], v[188:191], v[56:59]
	v_mfma_f32_16x16x32_bf16 v[52:55], v[156:159], v[196:199], v[52:55]
	v_mfma_f32_16x16x32_bf16 v[44:47], v[164:167], v[196:199], v[44:47]
	v_mfma_f32_16x16x32_bf16 v[36:39], v[156:159], v[204:207], v[36:39]
	v_mfma_f32_16x16x32_bf16 v[28:31], v[164:167], v[204:207], v[28:31]
	v_mfma_f32_16x16x32_bf16 v[20:23], v[156:159], v[212:215], v[20:23]
	v_mfma_f32_16x16x32_bf16 v[12:15], v[164:167], v[212:215], v[12:15]
	s_setprio 0
	s_setprio 1
	v_mfma_f32_16x16x32_bf16 v[48:51], v[168:171], v[184:187], v[48:51]
	v_mfma_f32_16x16x32_bf16 v[40:43], v[176:179], v[184:187], v[40:43]
	v_mfma_f32_16x16x32_bf16 v[32:35], v[168:171], v[192:195], v[32:35]
	v_mfma_f32_16x16x32_bf16 v[24:27], v[176:179], v[192:195], v[24:27]
	v_mfma_f32_16x16x32_bf16 v[16:19], v[168:171], v[200:203], v[16:19]
	v_mfma_f32_16x16x32_bf16 v[8:11], v[176:179], v[200:203], v[8:11]
	v_mfma_f32_16x16x32_bf16 v[4:7], v[168:171], v[208:211], v[4:7]
	v_mfma_f32_16x16x32_bf16 v[0:3], v[176:179], v[208:211], v[0:3]
	v_mfma_f32_16x16x32_bf16 v[48:51], v[172:175], v[188:191], v[48:51]
	v_mfma_f32_16x16x32_bf16 v[40:43], v[180:183], v[188:191], v[40:43]
	v_mfma_f32_16x16x32_bf16 v[32:35], v[172:175], v[196:199], v[32:35]
	v_mfma_f32_16x16x32_bf16 v[24:27], v[180:183], v[196:199], v[24:27]
	v_mfma_f32_16x16x32_bf16 v[16:19], v[172:175], v[204:207], v[16:19]
	v_mfma_f32_16x16x32_bf16 v[8:11], v[180:183], v[204:207], v[8:11]
	v_mfma_f32_16x16x32_bf16 v[4:7], v[172:175], v[212:215], v[4:7]
	v_mfma_f32_16x16x32_bf16 v[0:3], v[180:183], v[212:215], v[0:3]
	s_setprio 0
	s_add_i32 s62, s62, 2
	s_add_u32 s30, s30, 0x100
	s_addc_u32 s31, s31, 0
	s_add_u32 s60, s60, 0x100
	s_addc_u32 s61, s61, 0
	s_cmp_gt_u32 s62, 13
	s_barrier
	s_cbranch_scc0 .LBB0_416
	s_and_b64 vcc, exec, s[12:13]
	s_cbranch_vccz .LBB0_419
	s_barrier

.LBB0_440:
	ds_read_b128 v[152:155], v149
	ds_read_b128 v[156:159], v149 offset:1024
	ds_read_b128 v[160:163], v149 offset:2048
	ds_read_b128 v[164:167], v149 offset:3072
	ds_read_b128 v[168:171], v150
	ds_read_b128 v[172:175], v150 offset:1024
	ds_read_b128 v[176:179], v150 offset:2048
	ds_read_b128 v[180:183], v150 offset:3072
	s_add_u32 s30, s28, 0xfffc0080
	s_addc_u32 s31, s29, -1
	s_cmp_eq_u32 s60, 12
	s_cselect_b32 s35, s21, s31
	s_cselect_b32 s34, s56, s30
	s_cselect_b32 s31, s19, s59
	s_cselect_b32 s30, s57, s58
	v_lshl_add_u64 v[144:145], s[28:29], 0, v[136:137]
	s_add_i32 m0, s27, 0xc000
	ds_read_b128 v[184:187], v151
	ds_read_b128 v[188:191], v151 offset:1024
	ds_read_b128 v[192:195], v151 offset:2048
	ds_read_b128 v[196:199], v151 offset:3072
	ds_read_b128 v[200:203], v151 offset:4096
	ds_read_b128 v[204:207], v151 offset:5120
	ds_read_b128 v[208:211], v151 offset:6144
	ds_read_b128 v[212:215], v151 offset:7168
	global_load_lds_dwordx4 v[144:145], off
	v_lshl_add_u64 v[144:145], s[28:29], 0, v[138:139]
	s_add_i32 m0, s27, 0xe000
	s_nop 0
	global_load_lds_dwordx4 v[144:145], off
	s_waitcnt vmcnt(8)
	s_waitcnt lgkmcnt(0)
	s_barrier
	s_setprio 1
	s_waitcnt lgkmcnt(0)
	v_mfma_f32_16x16x32_bf16 v[124:127], v[152:155], v[184:187], v[124:127]
	v_mfma_f32_16x16x32_bf16 v[120:123], v[160:163], v[184:187], v[120:123]
	v_mfma_f32_16x16x32_bf16 v[116:119], v[152:155], v[192:195], v[116:119]
	v_mfma_f32_16x16x32_bf16 v[108:111], v[160:163], v[192:195], v[108:111]
	v_mfma_f32_16x16x32_bf16 v[100:103], v[152:155], v[200:203], v[100:103]
	v_mfma_f32_16x16x32_bf16 v[92:95], v[160:163], v[200:203], v[92:95]
	v_mfma_f32_16x16x32_bf16 v[84:87], v[152:155], v[208:211], v[84:87]
	v_mfma_f32_16x16x32_bf16 v[76:79], v[160:163], v[208:211], v[76:79]
	v_mfma_f32_16x16x32_bf16 v[124:127], v[156:159], v[188:191], v[124:127]
	v_mfma_f32_16x16x32_bf16 v[120:123], v[164:167], v[188:191], v[120:123]
	v_mfma_f32_16x16x32_bf16 v[116:119], v[156:159], v[196:199], v[116:119]
	v_mfma_f32_16x16x32_bf16 v[108:111], v[164:167], v[196:199], v[108:111]
	v_mfma_f32_16x16x32_bf16 v[100:103], v[156:159], v[204:207], v[100:103]
	v_mfma_f32_16x16x32_bf16 v[92:95], v[164:167], v[204:207], v[92:95]
	v_mfma_f32_16x16x32_bf16 v[84:87], v[156:159], v[212:215], v[84:87]
	v_mfma_f32_16x16x32_bf16 v[76:79], v[164:167], v[212:215], v[76:79]
	s_setprio 0
	s_setprio 1
	v_mfma_f32_16x16x32_bf16 v[112:115], v[168:171], v[184:187], v[112:115]
	v_mfma_f32_16x16x32_bf16 v[104:107], v[176:179], v[184:187], v[104:107]
	v_mfma_f32_16x16x32_bf16 v[96:99], v[168:171], v[192:195], v[96:99]
	v_mfma_f32_16x16x32_bf16 v[88:91], v[176:179], v[192:195], v[88:91]
	v_mfma_f32_16x16x32_bf16 v[80:83], v[168:171], v[200:203], v[80:83]
	v_mfma_f32_16x16x32_bf16 v[72:75], v[176:179], v[200:203], v[72:75]
	v_mfma_f32_16x16x32_bf16 v[68:71], v[168:171], v[208:211], v[68:71]
	v_mfma_f32_16x16x32_bf16 v[64:67], v[176:179], v[208:211], v[64:67]
	v_mfma_f32_16x16x32_bf16 v[112:115], v[172:175], v[188:191], v[112:115]
	v_mfma_f32_16x16x32_bf16 v[104:107], v[180:183], v[188:191], v[104:107]
	v_mfma_f32_16x16x32_bf16 v[96:99], v[172:175], v[196:199], v[96:99]
	v_mfma_f32_16x16x32_bf16 v[88:91], v[180:183], v[196:199], v[88:91]
	v_mfma_f32_16x16x32_bf16 v[80:83], v[172:175], v[204:207], v[80:83]
	v_mfma_f32_16x16x32_bf16 v[72:75], v[180:183], v[204:207], v[72:75]
	v_mfma_f32_16x16x32_bf16 v[68:71], v[172:175], v[212:215], v[68:71]
	v_mfma_f32_16x16x32_bf16 v[64:67], v[180:183], v[212:215], v[64:67]
	s_setprio 0
	s_barrier
	s_add_i32 s61, s49, s41
	v_lshl_add_u64 v[144:145], s[30:31], 0, v[130:131]
	s_mov_b32 m0, s61
	ds_read_b128 v[184:187], v151 offset:16384
	ds_read_b128 v[188:191], v151 offset:17408
	ds_read_b128 v[192:195], v151 offset:18432
	ds_read_b128 v[196:199], v151 offset:19456
	ds_read_b128 v[200:203], v151 offset:20480
	ds_read_b128 v[204:207], v151 offset:21504
	ds_read_b128 v[208:211], v151 offset:22528
	ds_read_b128 v[212:215], v151 offset:23552
	global_load_lds_dwordx4 v[144:145], off
	s_add_i32 m0, s61, 0x2000
	s_add_u32 s62, s30, 0x40000
	v_lshl_add_u64 v[216:217], s[30:31], 0, v[134:135]
	s_addc_u32 s63, s31, 0
	s_add_i32 s61, s50, s41
	global_load_lds_dwordx4 v[216:217], off
	v_lshl_add_u64 v[218:219], s[62:63], 0, v[130:131]
	s_mov_b32 m0, s61
	v_lshl_add_u64 v[220:221], s[34:35], 0, v[132:133]
	global_load_lds_dwordx4 v[218:219], off
	v_lshl_add_u64 v[218:219], s[62:63], 0, v[134:135]
	s_add_i32 m0, s61, 0x2000
	s_nop 0
	global_load_lds_dwordx4 v[218:219], off
	v_lshl_add_u64 v[218:219], s[34:35], 0, v[128:129]
	s_mov_b32 m0, s27
	s_nop 0
	global_load_lds_dwordx4 v[218:219], off
	s_mov_b32 m0, s42
	s_nop 0
	global_load_lds_dwordx4 v[220:221], off
	s_waitcnt vmcnt(8)
	s_waitcnt lgkmcnt(0)
	s_barrier
	s_setprio 1
	s_waitcnt lgkmcnt(0)
	v_mfma_f32_16x16x32_bf16 v[60:63], v[152:155], v[184:187], v[60:63]
	v_mfma_f32_16x16x32_bf16 v[56:59], v[160:163], v[184:187], v[56:59]
	v_mfma_f32_16x16x32_bf16 v[52:55], v[152:155], v[192:195], v[52:55]
	v_mfma_f32_16x16x32_bf16 v[44:47], v[160:163], v[192:195], v[44:47]
	v_mfma_f32_16x16x32_bf16 v[36:39], v[152:155], v[200:203], v[36:39]
	v_mfma_f32_16x16x32_bf16 v[28:31], v[160:163], v[200:203], v[28:31]
	v_mfma_f32_16x16x32_bf16 v[20:23], v[152:155], v[208:211], v[20:23]
	v_mfma_f32_16x16x32_bf16 v[12:15], v[160:163], v[208:211], v[12:15]
	v_mfma_f32_16x16x32_bf16 v[60:63], v[156:159], v[188:191], v[60:63]
	v_mfma_f32_16x16x32_bf16 v[56:59], v[164:167], v[188:191], v[56:59]
	v_mfma_f32_16x16x32_bf16 v[52:55], v[156:159], v[196:199], v[52:55]
	v_mfma_f32_16x16x32_bf16 v[44:47], v[164:167], v[196:199], v[44:47]
	v_mfma_f32_16x16x32_bf16 v[36:39], v[156:159], v[204:207], v[36:39]
	v_mfma_f32_16x16x32_bf16 v[28:31], v[164:167], v[204:207], v[28:31]
	v_mfma_f32_16x16x32_bf16 v[20:23], v[156:159], v[212:215], v[20:23]
	v_mfma_f32_16x16x32_bf16 v[12:15], v[164:167], v[212:215], v[12:15]
	s_setprio 0
	s_setprio 1
	v_mfma_f32_16x16x32_bf16 v[48:51], v[168:171], v[184:187], v[48:51]
	v_mfma_f32_16x16x32_bf16 v[40:43], v[176:179], v[184:187], v[40:43]
	v_mfma_f32_16x16x32_bf16 v[32:35], v[168:171], v[192:195], v[32:35]
	v_mfma_f32_16x16x32_bf16 v[24:27], v[176:179], v[192:195], v[24:27]
	v_mfma_f32_16x16x32_bf16 v[16:19], v[168:171], v[200:203], v[16:19]
	v_mfma_f32_16x16x32_bf16 v[8:11], v[176:179], v[200:203], v[8:11]
	v_mfma_f32_16x16x32_bf16 v[4:7], v[168:171], v[208:211], v[4:7]
	v_mfma_f32_16x16x32_bf16 v[0:3], v[176:179], v[208:211], v[0:3]
	v_mfma_f32_16x16x32_bf16 v[48:51], v[172:175], v[188:191], v[48:51]
	v_mfma_f32_16x16x32_bf16 v[40:43], v[180:183], v[188:191], v[40:43]
	v_mfma_f32_16x16x32_bf16 v[32:35], v[172:175], v[196:199], v[32:35]
	v_mfma_f32_16x16x32_bf16 v[24:27], v[180:183], v[196:199], v[24:27]
	v_mfma_f32_16x16x32_bf16 v[16:19], v[172:175], v[204:207], v[16:19]
	v_mfma_f32_16x16x32_bf16 v[8:11], v[180:183], v[204:207], v[8:11]
	v_mfma_f32_16x16x32_bf16 v[4:7], v[172:175], v[212:215], v[4:7]
	v_mfma_f32_16x16x32_bf16 v[0:3], v[180:183], v[212:215], v[0:3]
	s_setprio 0
	s_barrier
	s_add_i32 s61, 0, 0x18000
	s_add_i32 s62, 0, 0x1c000
	v_add_u32_e32 v164, s61, v147
	v_add_u32_e32 v180, s62, v147
	ds_read_b128 v[152:155], v164
	ds_read_b128 v[156:159], v164 offset:1024
	ds_read_b128 v[160:163], v164 offset:2048
	ds_read_b128 v[164:167], v164 offset:3072
	ds_read_b128 v[168:171], v180
	ds_read_b128 v[172:175], v180 offset:1024
	ds_read_b128 v[176:179], v180 offset:2048
	ds_read_b128 v[180:183], v180 offset:3072
	s_add_u32 s34, s34, 0x40000
	s_addc_u32 s35, s35, 0
	s_mov_b32 m0, s43
	v_lshl_add_u64 v[222:223], s[34:35], 0, v[128:129]
	ds_read_b128 v[184:187], v151 offset:32768
	ds_read_b128 v[188:191], v151 offset:33792
	ds_read_b128 v[192:195], v151 offset:34816
	ds_read_b128 v[196:199], v151 offset:35840
	ds_read_b128 v[200:203], v151 offset:36864
	ds_read_b128 v[204:207], v151 offset:37888
	ds_read_b128 v[208:211], v151 offset:38912
	ds_read_b128 v[212:215], v151 offset:39936
	global_load_lds_dwordx4 v[222:223], off
	v_lshl_add_u64 v[222:223], s[34:35], 0, v[132:133]
	s_mov_b32 m0, s44
	s_nop 0
	global_load_lds_dwordx4 v[222:223], off
	s_waitcnt vmcnt(8)
	s_waitcnt lgkmcnt(0)
	s_barrier
	s_setprio 1
	s_waitcnt lgkmcnt(0)
	v_mfma_f32_16x16x32_bf16 v[124:127], v[152:155], v[184:187], v[124:127]
	v_mfma_f32_16x16x32_bf16 v[120:123], v[160:163], v[184:187], v[120:123]
	v_mfma_f32_16x16x32_bf16 v[116:119], v[152:155], v[192:195], v[116:119]
	v_mfma_f32_16x16x32_bf16 v[108:111], v[160:163], v[192:195], v[108:111]
	v_mfma_f32_16x16x32_bf16 v[100:103], v[152:155], v[200:203], v[100:103]
	v_mfma_f32_16x16x32_bf16 v[92:95], v[160:163], v[200:203], v[92:95]
	v_mfma_f32_16x16x32_bf16 v[84:87], v[152:155], v[208:211], v[84:87]
	v_mfma_f32_16x16x32_bf16 v[76:79], v[160:163], v[208:211], v[76:79]
	v_mfma_f32_16x16x32_bf16 v[124:127], v[156:159], v[188:191], v[124:127]
	v_mfma_f32_16x16x32_bf16 v[120:123], v[164:167], v[188:191], v[120:123]
	v_mfma_f32_16x16x32_bf16 v[116:119], v[156:159], v[196:199], v[116:119]
	v_mfma_f32_16x16x32_bf16 v[108:111], v[164:167], v[196:199], v[108:111]
	v_mfma_f32_16x16x32_bf16 v[100:103], v[156:159], v[204:207], v[100:103]
	v_mfma_f32_16x16x32_bf16 v[92:95], v[164:167], v[204:207], v[92:95]
	v_mfma_f32_16x16x32_bf16 v[84:87], v[156:159], v[212:215], v[84:87]
	v_mfma_f32_16x16x32_bf16 v[76:79], v[164:167], v[212:215], v[76:79]
	s_setprio 0
	s_setprio 1
	v_mfma_f32_16x16x32_bf16 v[112:115], v[168:171], v[184:187], v[112:115]
	v_mfma_f32_16x16x32_bf16 v[104:107], v[176:179], v[184:187], v[104:107]
	v_mfma_f32_16x16x32_bf16 v[96:99], v[168:171], v[192:195], v[96:99]
	v_mfma_f32_16x16x32_bf16 v[88:91], v[176:179], v[192:195], v[88:91]
	v_mfma_f32_16x16x32_bf16 v[80:83], v[168:171], v[200:203], v[80:83]
	v_mfma_f32_16x16x32_bf16 v[72:75], v[176:179], v[200:203], v[72:75]
	v_mfma_f32_16x16x32_bf16 v[68:71], v[168:171], v[208:211], v[68:71]
	v_mfma_f32_16x16x32_bf16 v[64:67], v[176:179], v[208:211], v[64:67]
	v_mfma_f32_16x16x32_bf16 v[112:115], v[172:175], v[188:191], v[112:115]
	v_mfma_f32_16x16x32_bf16 v[104:107], v[180:183], v[188:191], v[104:107]
	v_mfma_f32_16x16x32_bf16 v[96:99], v[172:175], v[196:199], v[96:99]
	v_mfma_f32_16x16x32_bf16 v[88:91], v[180:183], v[196:199], v[88:91]
	v_mfma_f32_16x16x32_bf16 v[80:83], v[172:175], v[204:207], v[80:83]
	v_mfma_f32_16x16x32_bf16 v[72:75], v[180:183], v[204:207], v[72:75]
	v_mfma_f32_16x16x32_bf16 v[68:71], v[172:175], v[212:215], v[68:71]
	v_mfma_f32_16x16x32_bf16 v[64:67], v[180:183], v[212:215], v[64:67]
	s_setprio 0
	s_barrier
	s_add_i32 s34, s61, s41
	v_lshl_add_u64 v[144:145], v[144:145], 0, s[8:9]
	s_mov_b32 m0, s34
	ds_read_b128 v[184:187], v151 offset:49152
	ds_read_b128 v[188:191], v151 offset:50176
	ds_read_b128 v[192:195], v151 offset:51200
	ds_read_b128 v[196:199], v151 offset:52224
	ds_read_b128 v[200:203], v151 offset:53248
	ds_read_b128 v[204:207], v151 offset:54272
	ds_read_b128 v[208:211], v151 offset:55296
	ds_read_b128 v[212:215], v151 offset:56320
	global_load_lds_dwordx4 v[144:145], off
	s_add_i32 m0, s34, 0x2000
	s_add_u32 s30, s30, 0x40080
	v_lshl_add_u64 v[144:145], v[216:217], 0, s[8:9]
	s_addc_u32 s31, s31, 0
	s_add_i32 s34, s62, s41
	global_load_lds_dwordx4 v[144:145], off
	v_lshl_add_u64 v[144:145], s[30:31], 0, v[130:131]
	s_mov_b32 m0, s34
	s_nop 0
	global_load_lds_dwordx4 v[144:145], off
	v_lshl_add_u64 v[144:145], s[30:31], 0, v[134:135]
	s_add_i32 m0, s34, 0x2000
	s_nop 0
	global_load_lds_dwordx4 v[144:145], off
	v_lshl_add_u64 v[144:145], v[218:219], 0, s[8:9]
	s_mov_b32 m0, s46
	s_nop 0
	global_load_lds_dwordx4 v[144:145], off
	v_lshl_add_u64 v[144:145], v[220:221], 0, s[8:9]
	s_mov_b32 m0, s47
	s_nop 0
	global_load_lds_dwordx4 v[144:145], off
	s_waitcnt vmcnt(8)
	s_waitcnt lgkmcnt(0)
	s_barrier
	s_setprio 1
	s_waitcnt lgkmcnt(0)
	v_mfma_f32_16x16x32_bf16 v[60:63], v[152:155], v[184:187], v[60:63]
	v_mfma_f32_16x16x32_bf16 v[56:59], v[160:163], v[184:187], v[56:59]
	v_mfma_f32_16x16x32_bf16 v[52:55], v[152:155], v[192:195], v[52:55]
	v_mfma_f32_16x16x32_bf16 v[44:47], v[160:163], v[192:195], v[44:47]
	v_mfma_f32_16x16x32_bf16 v[36:39], v[152:155], v[200:203], v[36:39]
	v_mfma_f32_16x16x32_bf16 v[28:31], v[160:163], v[200:203], v[28:31]
	v_mfma_f32_16x16x32_bf16 v[20:23], v[152:155], v[208:211], v[20:23]
	v_mfma_f32_16x16x32_bf16 v[12:15], v[160:163], v[208:211], v[12:15]
	v_mfma_f32_16x16x32_bf16 v[60:63], v[156:159], v[188:191], v[60:63]
	v_mfma_f32_16x16x32_bf16 v[56:59], v[164:167], v[188:191], v[56:59]
	v_mfma_f32_16x16x32_bf16 v[52:55], v[156:159], v[196:199], v[52:55]
	v_mfma_f32_16x16x32_bf16 v[44:47], v[164:167], v[196:199], v[44:47]
	v_mfma_f32_16x16x32_bf16 v[36:39], v[156:159], v[204:207], v[36:39]
	v_mfma_f32_16x16x32_bf16 v[28:31], v[164:167], v[204:207], v[28:31]
	v_mfma_f32_16x16x32_bf16 v[20:23], v[156:159], v[212:215], v[20:23]
	v_mfma_f32_16x16x32_bf16 v[12:15], v[164:167], v[212:215], v[12:15]
	s_setprio 0
	s_setprio 1
	v_mfma_f32_16x16x32_bf16 v[48:51], v[168:171], v[184:187], v[48:51]
	v_mfma_f32_16x16x32_bf16 v[40:43], v[176:179], v[184:187], v[40:43]
	v_mfma_f32_16x16x32_bf16 v[32:35], v[168:171], v[192:195], v[32:35]
	v_mfma_f32_16x16x32_bf16 v[24:27], v[176:179], v[192:195], v[24:27]
	v_mfma_f32_16x16x32_bf16 v[16:19], v[168:171], v[200:203], v[16:19]
	v_mfma_f32_16x16x32_bf16 v[8:11], v[176:179], v[200:203], v[8:11]
	v_mfma_f32_16x16x32_bf16 v[4:7], v[168:171], v[208:211], v[4:7]
	v_mfma_f32_16x16x32_bf16 v[0:3], v[176:179], v[208:211], v[0:3]
	v_mfma_f32_16x16x32_bf16 v[48:51], v[172:175], v[188:191], v[48:51]
	v_mfma_f32_16x16x32_bf16 v[40:43], v[180:183], v[188:191], v[40:43]
	v_mfma_f32_16x16x32_bf16 v[32:35], v[172:175], v[196:199], v[32:35]
	v_mfma_f32_16x16x32_bf16 v[24:27], v[180:183], v[196:199], v[24:27]
	v_mfma_f32_16x16x32_bf16 v[16:19], v[172:175], v[204:207], v[16:19]
	v_mfma_f32_16x16x32_bf16 v[8:11], v[180:183], v[204:207], v[8:11]
	v_mfma_f32_16x16x32_bf16 v[4:7], v[172:175], v[212:215], v[4:7]
	v_mfma_f32_16x16x32_bf16 v[0:3], v[180:183], v[212:215], v[0:3]
	s_setprio 0
	s_add_i32 s60, s60, 2
	s_add_u32 s28, s28, 0x100
	s_addc_u32 s29, s29, 0
	s_add_u32 s58, s58, 0x100
	s_addc_u32 s59, s59, 0
	s_cmp_gt_u32 s60, 13
	s_barrier
	s_cbranch_scc0 .LBB0_440
	s_and_b64 vcc, exec, s[10:11]
	s_cbranch_vccz .LBB0_443
	s_barrier

.LBB0_911:
	ds_read_b128 v[140:143], v147
	ds_read_b128 v[152:155], v147 offset:1024
	ds_read_b128 v[156:159], v147 offset:2048
	ds_read_b128 v[160:163], v147 offset:3072
	ds_read_b128 v[164:167], v148
	ds_read_b128 v[168:171], v148 offset:1024
	ds_read_b128 v[172:175], v148 offset:2048
	ds_read_b128 v[176:179], v148 offset:3072
	s_add_u32 s30, s28, 0xfffc0080
	s_addc_u32 s31, s29, -1
	s_cmp_eq_u32 s56, 12
	s_cselect_b32 s35, s21, s31
	s_cselect_b32 s34, s27, s30
	s_cselect_b32 s31, s19, s55
	s_cselect_b32 s30, s53, s54
	v_lshl_add_u64 v[212:213], s[28:29], 0, v[132:133]
	s_add_i32 m0, s41, 0xc000
	ds_read_b128 v[180:183], v149
	ds_read_b128 v[184:187], v149 offset:1024
	ds_read_b128 v[188:191], v149 offset:2048
	ds_read_b128 v[192:195], v149 offset:3072
	ds_read_b128 v[196:199], v149 offset:4096
	ds_read_b128 v[200:203], v149 offset:5120
	ds_read_b128 v[204:207], v149 offset:6144
	ds_read_b128 v[208:211], v149 offset:7168
	global_load_lds_dwordx4 v[212:213], off
	v_lshl_add_u64 v[212:213], s[28:29], 0, v[134:135]
	s_add_i32 m0, s41, 0xe000
	s_nop 0
	global_load_lds_dwordx4 v[212:213], off
	s_waitcnt vmcnt(8)
	s_waitcnt lgkmcnt(0)
	s_barrier
	s_setprio 1
	s_waitcnt lgkmcnt(0)
	v_mfma_f32_16x16x32_bf16 v[124:127], v[140:143], v[180:183], v[124:127]
	v_mfma_f32_16x16x32_bf16 v[120:123], v[156:159], v[180:183], v[120:123]
	v_mfma_f32_16x16x32_bf16 v[108:111], v[140:143], v[188:191], v[108:111]
	v_mfma_f32_16x16x32_bf16 v[104:107], v[156:159], v[188:191], v[104:107]
	v_mfma_f32_16x16x32_bf16 v[92:95], v[140:143], v[196:199], v[92:95]
	v_mfma_f32_16x16x32_bf16 v[88:91], v[156:159], v[196:199], v[88:91]
	v_mfma_f32_16x16x32_bf16 v[76:79], v[140:143], v[204:207], v[76:79]
	v_mfma_f32_16x16x32_bf16 v[72:75], v[156:159], v[204:207], v[72:75]
	v_mfma_f32_16x16x32_bf16 v[124:127], v[152:155], v[184:187], v[124:127]
	v_mfma_f32_16x16x32_bf16 v[120:123], v[160:163], v[184:187], v[120:123]
	v_mfma_f32_16x16x32_bf16 v[108:111], v[152:155], v[192:195], v[108:111]
	v_mfma_f32_16x16x32_bf16 v[104:107], v[160:163], v[192:195], v[104:107]
	v_mfma_f32_16x16x32_bf16 v[92:95], v[152:155], v[200:203], v[92:95]
	v_mfma_f32_16x16x32_bf16 v[88:91], v[160:163], v[200:203], v[88:91]
	v_mfma_f32_16x16x32_bf16 v[76:79], v[152:155], v[208:211], v[76:79]
	v_mfma_f32_16x16x32_bf16 v[72:75], v[160:163], v[208:211], v[72:75]
	s_setprio 0
	s_setprio 1
	v_mfma_f32_16x16x32_bf16 v[116:119], v[164:167], v[180:183], v[116:119]
	v_mfma_f32_16x16x32_bf16 v[112:115], v[172:175], v[180:183], v[112:115]
	v_mfma_f32_16x16x32_bf16 v[100:103], v[164:167], v[188:191], v[100:103]
	v_mfma_f32_16x16x32_bf16 v[96:99], v[172:175], v[188:191], v[96:99]
	v_mfma_f32_16x16x32_bf16 v[84:87], v[164:167], v[196:199], v[84:87]
	v_mfma_f32_16x16x32_bf16 v[80:83], v[172:175], v[196:199], v[80:83]
	v_mfma_f32_16x16x32_bf16 v[68:71], v[164:167], v[204:207], v[68:71]
	v_mfma_f32_16x16x32_bf16 v[64:67], v[172:175], v[204:207], v[64:67]
	v_mfma_f32_16x16x32_bf16 v[116:119], v[168:171], v[184:187], v[116:119]
	v_mfma_f32_16x16x32_bf16 v[112:115], v[176:179], v[184:187], v[112:115]
	v_mfma_f32_16x16x32_bf16 v[100:103], v[168:171], v[192:195], v[100:103]
	v_mfma_f32_16x16x32_bf16 v[96:99], v[176:179], v[192:195], v[96:99]
	v_mfma_f32_16x16x32_bf16 v[84:87], v[168:171], v[200:203], v[84:87]
	v_mfma_f32_16x16x32_bf16 v[80:83], v[176:179], v[200:203], v[80:83]
	v_mfma_f32_16x16x32_bf16 v[68:71], v[168:171], v[208:211], v[68:71]
	v_mfma_f32_16x16x32_bf16 v[64:67], v[176:179], v[208:211], v[64:67]
	s_setprio 0
	s_barrier
	s_add_i32 s57, s50, s40
	v_lshl_add_u64 v[212:213], s[30:31], 0, v[128:129]
	s_mov_b32 m0, s57
	ds_read_b128 v[180:183], v149 offset:16384
	ds_read_b128 v[184:187], v149 offset:17408
	ds_read_b128 v[188:191], v149 offset:18432
	ds_read_b128 v[192:195], v149 offset:19456
	ds_read_b128 v[196:199], v149 offset:20480
	ds_read_b128 v[200:203], v149 offset:21504
	ds_read_b128 v[204:207], v149 offset:22528
	ds_read_b128 v[208:211], v149 offset:23552
	global_load_lds_dwordx4 v[212:213], off
	s_add_i32 m0, s57, 0x2000
	s_add_u32 s58, s30, 0x40000
	v_lshl_add_u64 v[214:215], s[30:31], 0, v[130:131]
	s_addc_u32 s59, s31, 0
	s_add_i32 s57, s51, s40
	global_load_lds_dwordx4 v[214:215], off
	v_lshl_add_u64 v[216:217], s[58:59], 0, v[128:129]
	s_mov_b32 m0, s57
	v_lshl_add_u64 v[218:219], s[34:35], 0, v[130:131]
	global_load_lds_dwordx4 v[216:217], off
	v_lshl_add_u64 v[216:217], s[58:59], 0, v[130:131]
	s_add_i32 m0, s57, 0x2000
	s_nop 0
	global_load_lds_dwordx4 v[216:217], off
	v_lshl_add_u64 v[216:217], s[34:35], 0, v[128:129]
	s_mov_b32 m0, s41
	s_nop 0
	global_load_lds_dwordx4 v[216:217], off
	s_mov_b32 m0, s42
	s_nop 0
	global_load_lds_dwordx4 v[218:219], off
	s_waitcnt vmcnt(8)
	s_waitcnt lgkmcnt(0)
	s_barrier
	s_setprio 1
	s_waitcnt lgkmcnt(0)
	v_mfma_f32_16x16x32_bf16 v[60:63], v[140:143], v[180:183], v[60:63]
	v_mfma_f32_16x16x32_bf16 v[56:59], v[156:159], v[180:183], v[56:59]
	v_mfma_f32_16x16x32_bf16 v[44:47], v[140:143], v[188:191], v[44:47]
	v_mfma_f32_16x16x32_bf16 v[40:43], v[156:159], v[188:191], v[40:43]
	v_mfma_f32_16x16x32_bf16 v[28:31], v[140:143], v[196:199], v[28:31]
	v_mfma_f32_16x16x32_bf16 v[24:27], v[156:159], v[196:199], v[24:27]
	v_mfma_f32_16x16x32_bf16 v[12:15], v[140:143], v[204:207], v[12:15]
	v_mfma_f32_16x16x32_bf16 v[8:11], v[156:159], v[204:207], v[8:11]
	v_mfma_f32_16x16x32_bf16 v[60:63], v[152:155], v[184:187], v[60:63]
	v_mfma_f32_16x16x32_bf16 v[56:59], v[160:163], v[184:187], v[56:59]
	v_mfma_f32_16x16x32_bf16 v[44:47], v[152:155], v[192:195], v[44:47]
	v_mfma_f32_16x16x32_bf16 v[40:43], v[160:163], v[192:195], v[40:43]
	v_mfma_f32_16x16x32_bf16 v[28:31], v[152:155], v[200:203], v[28:31]
	v_mfma_f32_16x16x32_bf16 v[24:27], v[160:163], v[200:203], v[24:27]
	v_mfma_f32_16x16x32_bf16 v[12:15], v[152:155], v[208:211], v[12:15]
	v_mfma_f32_16x16x32_bf16 v[8:11], v[160:163], v[208:211], v[8:11]
	s_setprio 0
	s_setprio 1
	v_mfma_f32_16x16x32_bf16 v[52:55], v[164:167], v[180:183], v[52:55]
	v_mfma_f32_16x16x32_bf16 v[48:51], v[172:175], v[180:183], v[48:51]
	v_mfma_f32_16x16x32_bf16 v[36:39], v[164:167], v[188:191], v[36:39]
	v_mfma_f32_16x16x32_bf16 v[32:35], v[172:175], v[188:191], v[32:35]
	v_mfma_f32_16x16x32_bf16 v[20:23], v[164:167], v[196:199], v[20:23]
	v_mfma_f32_16x16x32_bf16 v[16:19], v[172:175], v[196:199], v[16:19]
	v_mfma_f32_16x16x32_bf16 v[4:7], v[164:167], v[204:207], v[4:7]
	v_mfma_f32_16x16x32_bf16 v[0:3], v[172:175], v[204:207], v[0:3]
	v_mfma_f32_16x16x32_bf16 v[52:55], v[168:171], v[184:187], v[52:55]
	v_mfma_f32_16x16x32_bf16 v[48:51], v[176:179], v[184:187], v[48:51]
	v_mfma_f32_16x16x32_bf16 v[36:39], v[168:171], v[192:195], v[36:39]
	v_mfma_f32_16x16x32_bf16 v[32:35], v[176:179], v[192:195], v[32:35]
	v_mfma_f32_16x16x32_bf16 v[20:23], v[168:171], v[200:203], v[20:23]
	v_mfma_f32_16x16x32_bf16 v[16:19], v[176:179], v[200:203], v[16:19]
	v_mfma_f32_16x16x32_bf16 v[4:7], v[168:171], v[208:211], v[4:7]
	v_mfma_f32_16x16x32_bf16 v[0:3], v[176:179], v[208:211], v[0:3]
	s_setprio 0
	s_barrier
	s_add_i32 s57, 0, 0x18000
	v_add_u32_e32 v151, s57, v145
	s_add_i32 s58, 0, 0x1c000
	ds_read_b128 v[140:143], v151
	ds_read_b128 v[152:155], v151 offset:1024
	ds_read_b128 v[156:159], v151 offset:2048
	ds_read_b128 v[160:163], v151 offset:3072
	v_add_u32_e32 v151, s58, v145
	ds_read_b128 v[164:167], v151
	ds_read_b128 v[168:171], v151 offset:1024
	ds_read_b128 v[172:175], v151 offset:2048
	ds_read_b128 v[176:179], v151 offset:3072
	s_add_u32 s34, s34, 0x40000
	s_addc_u32 s35, s35, 0
	s_mov_b32 m0, s43
	v_lshl_add_u64 v[220:221], s[34:35], 0, v[128:129]
	ds_read_b128 v[180:183], v149 offset:32768
	ds_read_b128 v[184:187], v149 offset:33792
	ds_read_b128 v[188:191], v149 offset:34816
	ds_read_b128 v[192:195], v149 offset:35840
	ds_read_b128 v[196:199], v149 offset:36864
	ds_read_b128 v[200:203], v149 offset:37888
	ds_read_b128 v[204:207], v149 offset:38912
	ds_read_b128 v[208:211], v149 offset:39936
	global_load_lds_dwordx4 v[220:221], off
	v_lshl_add_u64 v[220:221], s[34:35], 0, v[130:131]
	s_mov_b32 m0, s44
	s_nop 0
	global_load_lds_dwordx4 v[220:221], off
	s_waitcnt vmcnt(8)
	s_waitcnt lgkmcnt(0)
	s_barrier
	s_setprio 1
	s_waitcnt lgkmcnt(0)
	v_mfma_f32_16x16x32_bf16 v[124:127], v[140:143], v[180:183], v[124:127]
	v_mfma_f32_16x16x32_bf16 v[120:123], v[156:159], v[180:183], v[120:123]
	v_mfma_f32_16x16x32_bf16 v[108:111], v[140:143], v[188:191], v[108:111]
	v_mfma_f32_16x16x32_bf16 v[104:107], v[156:159], v[188:191], v[104:107]
	v_mfma_f32_16x16x32_bf16 v[92:95], v[140:143], v[196:199], v[92:95]
	v_mfma_f32_16x16x32_bf16 v[88:91], v[156:159], v[196:199], v[88:91]
	v_mfma_f32_16x16x32_bf16 v[76:79], v[140:143], v[204:207], v[76:79]
	v_mfma_f32_16x16x32_bf16 v[72:75], v[156:159], v[204:207], v[72:75]
	v_mfma_f32_16x16x32_bf16 v[124:127], v[152:155], v[184:187], v[124:127]
	v_mfma_f32_16x16x32_bf16 v[120:123], v[160:163], v[184:187], v[120:123]
	v_mfma_f32_16x16x32_bf16 v[108:111], v[152:155], v[192:195], v[108:111]
	v_mfma_f32_16x16x32_bf16 v[104:107], v[160:163], v[192:195], v[104:107]
	v_mfma_f32_16x16x32_bf16 v[92:95], v[152:155], v[200:203], v[92:95]
	v_mfma_f32_16x16x32_bf16 v[88:91], v[160:163], v[200:203], v[88:91]
	v_mfma_f32_16x16x32_bf16 v[76:79], v[152:155], v[208:211], v[76:79]
	v_mfma_f32_16x16x32_bf16 v[72:75], v[160:163], v[208:211], v[72:75]
	s_setprio 0
	s_setprio 1
	v_mfma_f32_16x16x32_bf16 v[116:119], v[164:167], v[180:183], v[116:119]
	v_mfma_f32_16x16x32_bf16 v[112:115], v[172:175], v[180:183], v[112:115]
	v_mfma_f32_16x16x32_bf16 v[100:103], v[164:167], v[188:191], v[100:103]
	v_mfma_f32_16x16x32_bf16 v[96:99], v[172:175], v[188:191], v[96:99]
	v_mfma_f32_16x16x32_bf16 v[84:87], v[164:167], v[196:199], v[84:87]
	v_mfma_f32_16x16x32_bf16 v[80:83], v[172:175], v[196:199], v[80:83]
	v_mfma_f32_16x16x32_bf16 v[68:71], v[164:167], v[204:207], v[68:71]
	v_mfma_f32_16x16x32_bf16 v[64:67], v[172:175], v[204:207], v[64:67]
	v_mfma_f32_16x16x32_bf16 v[116:119], v[168:171], v[184:187], v[116:119]
	v_mfma_f32_16x16x32_bf16 v[112:115], v[176:179], v[184:187], v[112:115]
	v_mfma_f32_16x16x32_bf16 v[100:103], v[168:171], v[192:195], v[100:103]
	v_mfma_f32_16x16x32_bf16 v[96:99], v[176:179], v[192:195], v[96:99]
	v_mfma_f32_16x16x32_bf16 v[84:87], v[168:171], v[200:203], v[84:87]
	v_mfma_f32_16x16x32_bf16 v[80:83], v[176:179], v[200:203], v[80:83]
	v_mfma_f32_16x16x32_bf16 v[68:71], v[168:171], v[208:211], v[68:71]
	v_mfma_f32_16x16x32_bf16 v[64:67], v[176:179], v[208:211], v[64:67]
	s_setprio 0
	s_barrier
	s_add_i32 s34, s57, s40
	v_lshl_add_u64 v[212:213], v[212:213], 0, s[14:15]
	s_mov_b32 m0, s34
	ds_read_b128 v[180:183], v149 offset:49152
	ds_read_b128 v[184:187], v149 offset:50176
	ds_read_b128 v[188:191], v149 offset:51200
	ds_read_b128 v[192:195], v149 offset:52224
	ds_read_b128 v[196:199], v149 offset:53248
	ds_read_b128 v[200:203], v149 offset:54272
	ds_read_b128 v[204:207], v149 offset:55296
	ds_read_b128 v[208:211], v149 offset:56320
	global_load_lds_dwordx4 v[212:213], off
	s_add_i32 m0, s34, 0x2000
	s_add_u32 s30, s30, 0x40080
	v_lshl_add_u64 v[212:213], v[214:215], 0, s[14:15]
	s_addc_u32 s31, s31, 0
	s_add_i32 s34, s58, s40
	global_load_lds_dwordx4 v[212:213], off
	v_lshl_add_u64 v[212:213], s[30:31], 0, v[128:129]
	s_mov_b32 m0, s34
	s_nop 0
	global_load_lds_dwordx4 v[212:213], off
	v_lshl_add_u64 v[212:213], s[30:31], 0, v[130:131]
	s_add_i32 m0, s34, 0x2000
	s_nop 0
	global_load_lds_dwordx4 v[212:213], off
	v_lshl_add_u64 v[212:213], v[216:217], 0, s[14:15]
	s_mov_b32 m0, s46
	s_nop 0
	global_load_lds_dwordx4 v[212:213], off
	v_lshl_add_u64 v[212:213], v[218:219], 0, s[14:15]
	s_mov_b32 m0, s47
	s_nop 0
	global_load_lds_dwordx4 v[212:213], off
	s_waitcnt vmcnt(8)
	s_waitcnt lgkmcnt(0)
	s_barrier
	s_setprio 1
	s_waitcnt lgkmcnt(0)
	v_mfma_f32_16x16x32_bf16 v[60:63], v[140:143], v[180:183], v[60:63]
	v_mfma_f32_16x16x32_bf16 v[56:59], v[156:159], v[180:183], v[56:59]
	v_mfma_f32_16x16x32_bf16 v[44:47], v[140:143], v[188:191], v[44:47]
	v_mfma_f32_16x16x32_bf16 v[40:43], v[156:159], v[188:191], v[40:43]
	v_mfma_f32_16x16x32_bf16 v[28:31], v[140:143], v[196:199], v[28:31]
	v_mfma_f32_16x16x32_bf16 v[24:27], v[156:159], v[196:199], v[24:27]
	v_mfma_f32_16x16x32_bf16 v[12:15], v[140:143], v[204:207], v[12:15]
	v_mfma_f32_16x16x32_bf16 v[8:11], v[156:159], v[204:207], v[8:11]
	v_mfma_f32_16x16x32_bf16 v[60:63], v[152:155], v[184:187], v[60:63]
	v_mfma_f32_16x16x32_bf16 v[56:59], v[160:163], v[184:187], v[56:59]
	v_mfma_f32_16x16x32_bf16 v[44:47], v[152:155], v[192:195], v[44:47]
	v_mfma_f32_16x16x32_bf16 v[40:43], v[160:163], v[192:195], v[40:43]
	v_mfma_f32_16x16x32_bf16 v[28:31], v[152:155], v[200:203], v[28:31]
	v_mfma_f32_16x16x32_bf16 v[24:27], v[160:163], v[200:203], v[24:27]
	v_mfma_f32_16x16x32_bf16 v[12:15], v[152:155], v[208:211], v[12:15]
	v_mfma_f32_16x16x32_bf16 v[8:11], v[160:163], v[208:211], v[8:11]
	s_setprio 0
	s_setprio 1
	v_mfma_f32_16x16x32_bf16 v[52:55], v[164:167], v[180:183], v[52:55]
	v_mfma_f32_16x16x32_bf16 v[48:51], v[172:175], v[180:183], v[48:51]
	v_mfma_f32_16x16x32_bf16 v[36:39], v[164:167], v[188:191], v[36:39]
	v_mfma_f32_16x16x32_bf16 v[32:35], v[172:175], v[188:191], v[32:35]
	v_mfma_f32_16x16x32_bf16 v[20:23], v[164:167], v[196:199], v[20:23]
	v_mfma_f32_16x16x32_bf16 v[16:19], v[172:175], v[196:199], v[16:19]
	v_mfma_f32_16x16x32_bf16 v[4:7], v[164:167], v[204:207], v[4:7]
	v_mfma_f32_16x16x32_bf16 v[0:3], v[172:175], v[204:207], v[0:3]
	v_mfma_f32_16x16x32_bf16 v[52:55], v[168:171], v[184:187], v[52:55]
	v_mfma_f32_16x16x32_bf16 v[48:51], v[176:179], v[184:187], v[48:51]
	v_mfma_f32_16x16x32_bf16 v[36:39], v[168:171], v[192:195], v[36:39]
	v_mfma_f32_16x16x32_bf16 v[32:35], v[176:179], v[192:195], v[32:35]
	v_mfma_f32_16x16x32_bf16 v[20:23], v[168:171], v[200:203], v[20:23]
	v_mfma_f32_16x16x32_bf16 v[16:19], v[176:179], v[200:203], v[16:19]
	v_mfma_f32_16x16x32_bf16 v[4:7], v[168:171], v[208:211], v[4:7]
	v_mfma_f32_16x16x32_bf16 v[0:3], v[176:179], v[208:211], v[0:3]
	s_setprio 0
	s_add_i32 s56, s56, 2
	s_add_u32 s28, s28, 0x100
	s_addc_u32 s29, s29, 0
	s_add_u32 s54, s54, 0x100
	s_addc_u32 s55, s55, 0
	s_cmp_gt_u32 s56, 13
	s_barrier
	s_cbranch_scc0 .LBB0_911
	s_and_b64 vcc, exec, s[16:17]
	s_cbranch_vccz .LBB0_914
	s_barrier

.LBB0_977:
	ds_read_b128 v[152:155], v143
	ds_read_b128 v[162:165], v143 offset:1024
	ds_read_b128 v[166:169], v143 offset:2048
	ds_read_b128 v[170:173], v143 offset:3072
	ds_read_b128 v[174:177], v158
	ds_read_b128 v[178:181], v158 offset:1024
	ds_read_b128 v[182:185], v158 offset:2048
	ds_read_b128 v[186:189], v158 offset:3072
	s_add_u32 s34, s30, 0xfffc0080
	s_addc_u32 s35, s31, -1
	s_cmp_eq_u32 s57, 12
	s_cselect_b32 s37, s21, s35
	s_cselect_b32 s36, s27, s34
	s_cselect_b32 s35, s19, s56
	s_cselect_b32 s34, s29, s55
	s_waitcnt lgkmcnt(0)
	v_lshl_add_u64 v[156:157], s[30:31], 0, v[144:145]
	s_add_i32 m0, s41, 0xc000
	ds_read_b128 v[190:193], v159
	ds_read_b128 v[194:197], v159 offset:1024
	ds_read_b128 v[198:201], v159 offset:2048
	ds_read_b128 v[202:205], v159 offset:3072
	ds_read_b128 v[206:209], v159 offset:4096
	ds_read_b128 v[210:213], v159 offset:5120
	ds_read_b128 v[214:217], v159 offset:6144
	ds_read_b128 v[218:221], v159 offset:7168
	global_load_lds_dwordx4 v[156:157], off
	v_lshl_add_u64 v[156:157], s[30:31], 0, v[146:147]
	s_add_i32 m0, s41, 0xe000
	s_nop 0
	global_load_lds_dwordx4 v[156:157], off
	s_waitcnt vmcnt(8)
	s_waitcnt lgkmcnt(0)
	s_barrier
	s_setprio 1
	s_waitcnt lgkmcnt(0)
	v_mfma_f32_16x16x32_bf16 v[116:119], v[152:155], v[190:193], v[116:119]
	v_mfma_f32_16x16x32_bf16 v[112:115], v[166:169], v[190:193], v[112:115]
	v_mfma_f32_16x16x32_bf16 v[100:103], v[152:155], v[198:201], v[100:103]
	v_mfma_f32_16x16x32_bf16 v[96:99], v[166:169], v[198:201], v[96:99]
	v_mfma_f32_16x16x32_bf16 v[88:91], v[152:155], v[206:209], v[88:91]
	v_mfma_f32_16x16x32_bf16 v[84:87], v[166:169], v[206:209], v[84:87]
	v_mfma_f32_16x16x32_bf16 v[72:75], v[152:155], v[214:217], v[72:75]
	v_mfma_f32_16x16x32_bf16 v[68:71], v[166:169], v[214:217], v[68:71]
	v_mfma_f32_16x16x32_bf16 v[116:119], v[162:165], v[194:197], v[116:119]
	v_mfma_f32_16x16x32_bf16 v[112:115], v[170:173], v[194:197], v[112:115]
	v_mfma_f32_16x16x32_bf16 v[100:103], v[162:165], v[202:205], v[100:103]
	v_mfma_f32_16x16x32_bf16 v[96:99], v[170:173], v[202:205], v[96:99]
	v_mfma_f32_16x16x32_bf16 v[88:91], v[162:165], v[210:213], v[88:91]
	v_mfma_f32_16x16x32_bf16 v[84:87], v[170:173], v[210:213], v[84:87]
	v_mfma_f32_16x16x32_bf16 v[72:75], v[162:165], v[218:221], v[72:75]
	v_mfma_f32_16x16x32_bf16 v[68:71], v[170:173], v[218:221], v[68:71]
	s_setprio 0
	s_setprio 1
	v_mfma_f32_16x16x32_bf16 v[124:127], v[174:177], v[190:193], v[124:127]
	v_mfma_f32_16x16x32_bf16 v[120:123], v[182:185], v[190:193], v[120:123]
	v_mfma_f32_16x16x32_bf16 v[108:111], v[174:177], v[198:201], v[108:111]
	v_mfma_f32_16x16x32_bf16 v[104:107], v[182:185], v[198:201], v[104:107]
	v_mfma_f32_16x16x32_bf16 v[92:95], v[174:177], v[206:209], v[92:95]
	v_mfma_f32_16x16x32_bf16 v[80:83], v[182:185], v[206:209], v[80:83]
	v_mfma_f32_16x16x32_bf16 v[76:79], v[174:177], v[214:217], v[76:79]
	v_mfma_f32_16x16x32_bf16 v[64:67], v[182:185], v[214:217], v[64:67]
	v_mfma_f32_16x16x32_bf16 v[124:127], v[178:181], v[194:197], v[124:127]
	v_mfma_f32_16x16x32_bf16 v[120:123], v[186:189], v[194:197], v[120:123]
	v_mfma_f32_16x16x32_bf16 v[108:111], v[178:181], v[202:205], v[108:111]
	v_mfma_f32_16x16x32_bf16 v[104:107], v[186:189], v[202:205], v[104:107]
	v_mfma_f32_16x16x32_bf16 v[92:95], v[178:181], v[210:213], v[92:95]
	v_mfma_f32_16x16x32_bf16 v[80:83], v[186:189], v[210:213], v[80:83]
	v_mfma_f32_16x16x32_bf16 v[76:79], v[178:181], v[218:221], v[76:79]
	v_mfma_f32_16x16x32_bf16 v[64:67], v[186:189], v[218:221], v[64:67]
	s_setprio 0
	s_barrier
	s_add_i32 s58, s51, s40
	v_lshl_add_u64 v[156:157], s[34:35], 0, v[130:131]
	s_mov_b32 m0, s58
	ds_read_b128 v[190:193], v159 offset:16384
	ds_read_b128 v[194:197], v159 offset:17408
	ds_read_b128 v[198:201], v159 offset:18432
	ds_read_b128 v[202:205], v159 offset:19456
	ds_read_b128 v[206:209], v159 offset:20480
	ds_read_b128 v[210:213], v159 offset:21504
	ds_read_b128 v[214:217], v159 offset:22528
	ds_read_b128 v[218:221], v159 offset:23552
	global_load_lds_dwordx4 v[156:157], off
	s_add_i32 m0, s58, 0x2000
	s_add_u32 s58, s34, 0x40000
	v_lshl_add_u64 v[222:223], s[34:35], 0, v[134:135]
	s_addc_u32 s59, s35, 0
	s_add_i32 s60, s52, s40
	global_load_lds_dwordx4 v[222:223], off
	v_lshl_add_u64 v[224:225], s[58:59], 0, v[130:131]
	s_mov_b32 m0, s60
	v_lshl_add_u64 v[226:227], s[36:37], 0, v[132:133]
	global_load_lds_dwordx4 v[224:225], off
	v_lshl_add_u64 v[224:225], s[58:59], 0, v[134:135]
	s_add_i32 m0, s60, 0x2000
	s_nop 0
	global_load_lds_dwordx4 v[224:225], off
	v_lshl_add_u64 v[224:225], s[36:37], 0, v[128:129]
	s_mov_b32 m0, s41
	s_nop 0
	global_load_lds_dwordx4 v[224:225], off
	s_mov_b32 m0, s42
	s_nop 0
	global_load_lds_dwordx4 v[226:227], off
	s_waitcnt vmcnt(8)
	s_waitcnt lgkmcnt(0)
	s_barrier
	s_setprio 1
	s_waitcnt lgkmcnt(0)
	v_mfma_f32_16x16x32_bf16 v[56:59], v[152:155], v[190:193], v[56:59]
	v_mfma_f32_16x16x32_bf16 v[52:55], v[166:169], v[190:193], v[52:55]
	v_mfma_f32_16x16x32_bf16 v[40:43], v[152:155], v[198:201], v[40:43]
	v_mfma_f32_16x16x32_bf16 v[36:39], v[166:169], v[198:201], v[36:39]
	v_mfma_f32_16x16x32_bf16 v[24:27], v[152:155], v[206:209], v[24:27]
	v_mfma_f32_16x16x32_bf16 v[20:23], v[166:169], v[206:209], v[20:23]
	v_mfma_f32_16x16x32_bf16 v[8:11], v[152:155], v[214:217], v[8:11]
	v_mfma_f32_16x16x32_bf16 v[4:7], v[166:169], v[214:217], v[4:7]
	v_mfma_f32_16x16x32_bf16 v[56:59], v[162:165], v[194:197], v[56:59]
	v_mfma_f32_16x16x32_bf16 v[52:55], v[170:173], v[194:197], v[52:55]
	v_mfma_f32_16x16x32_bf16 v[40:43], v[162:165], v[202:205], v[40:43]
	v_mfma_f32_16x16x32_bf16 v[36:39], v[170:173], v[202:205], v[36:39]
	v_mfma_f32_16x16x32_bf16 v[24:27], v[162:165], v[210:213], v[24:27]
	v_mfma_f32_16x16x32_bf16 v[20:23], v[170:173], v[210:213], v[20:23]
	v_mfma_f32_16x16x32_bf16 v[8:11], v[162:165], v[218:221], v[8:11]
	v_mfma_f32_16x16x32_bf16 v[4:7], v[170:173], v[218:221], v[4:7]
	s_setprio 0
	s_setprio 1
	v_mfma_f32_16x16x32_bf16 v[60:63], v[174:177], v[190:193], v[60:63]
	v_mfma_f32_16x16x32_bf16 v[48:51], v[182:185], v[190:193], v[48:51]
	v_mfma_f32_16x16x32_bf16 v[44:47], v[174:177], v[198:201], v[44:47]
	v_mfma_f32_16x16x32_bf16 v[32:35], v[182:185], v[198:201], v[32:35]
	v_mfma_f32_16x16x32_bf16 v[28:31], v[174:177], v[206:209], v[28:31]
	v_mfma_f32_16x16x32_bf16 v[16:19], v[182:185], v[206:209], v[16:19]
	v_mfma_f32_16x16x32_bf16 v[12:15], v[174:177], v[214:217], v[12:15]
	v_mfma_f32_16x16x32_bf16 v[0:3], v[182:185], v[214:217], v[0:3]
	v_mfma_f32_16x16x32_bf16 v[60:63], v[178:181], v[194:197], v[60:63]
	v_mfma_f32_16x16x32_bf16 v[48:51], v[186:189], v[194:197], v[48:51]
	v_mfma_f32_16x16x32_bf16 v[44:47], v[178:181], v[202:205], v[44:47]
	v_mfma_f32_16x16x32_bf16 v[32:35], v[186:189], v[202:205], v[32:35]
	v_mfma_f32_16x16x32_bf16 v[28:31], v[178:181], v[210:213], v[28:31]
	v_mfma_f32_16x16x32_bf16 v[16:19], v[186:189], v[210:213], v[16:19]
	v_mfma_f32_16x16x32_bf16 v[12:15], v[178:181], v[218:221], v[12:15]
	v_mfma_f32_16x16x32_bf16 v[0:3], v[186:189], v[218:221], v[0:3]
	s_setprio 0
	s_barrier
	s_add_i32 s58, 0, 0x18000
	s_add_i32 s59, 0, 0x1c000
	v_add_u32_e32 v170, s58, v141
	v_add_u32_e32 v186, s59, v141
	ds_read_b128 v[152:155], v170
	ds_read_b128 v[162:165], v170 offset:1024
	ds_read_b128 v[166:169], v170 offset:2048
	ds_read_b128 v[170:173], v170 offset:3072
	ds_read_b128 v[174:177], v186
	ds_read_b128 v[178:181], v186 offset:1024
	ds_read_b128 v[182:185], v186 offset:2048
	ds_read_b128 v[186:189], v186 offset:3072
	s_add_u32 s36, s36, 0x40000
	s_addc_u32 s37, s37, 0
	s_mov_b32 m0, s43
	v_lshl_add_u64 v[228:229], s[36:37], 0, v[128:129]
	ds_read_b128 v[190:193], v159 offset:32768
	ds_read_b128 v[194:197], v159 offset:33792
	ds_read_b128 v[198:201], v159 offset:34816
	ds_read_b128 v[202:205], v159 offset:35840
	ds_read_b128 v[206:209], v159 offset:36864
	ds_read_b128 v[210:213], v159 offset:37888
	ds_read_b128 v[214:217], v159 offset:38912
	ds_read_b128 v[218:221], v159 offset:39936
	global_load_lds_dwordx4 v[228:229], off
	v_lshl_add_u64 v[228:229], s[36:37], 0, v[132:133]
	s_mov_b32 m0, s44
	s_nop 0
	global_load_lds_dwordx4 v[228:229], off
	s_waitcnt vmcnt(8)
	s_waitcnt lgkmcnt(0)
	s_barrier
	s_setprio 1
	s_waitcnt lgkmcnt(0)
	v_mfma_f32_16x16x32_bf16 v[116:119], v[152:155], v[190:193], v[116:119]
	v_mfma_f32_16x16x32_bf16 v[112:115], v[166:169], v[190:193], v[112:115]
	v_mfma_f32_16x16x32_bf16 v[100:103], v[152:155], v[198:201], v[100:103]
	v_mfma_f32_16x16x32_bf16 v[96:99], v[166:169], v[198:201], v[96:99]
	v_mfma_f32_16x16x32_bf16 v[88:91], v[152:155], v[206:209], v[88:91]
	v_mfma_f32_16x16x32_bf16 v[84:87], v[166:169], v[206:209], v[84:87]
	v_mfma_f32_16x16x32_bf16 v[72:75], v[152:155], v[214:217], v[72:75]
	v_mfma_f32_16x16x32_bf16 v[68:71], v[166:169], v[214:217], v[68:71]
	v_mfma_f32_16x16x32_bf16 v[116:119], v[162:165], v[194:197], v[116:119]
	v_mfma_f32_16x16x32_bf16 v[112:115], v[170:173], v[194:197], v[112:115]
	v_mfma_f32_16x16x32_bf16 v[100:103], v[162:165], v[202:205], v[100:103]
	v_mfma_f32_16x16x32_bf16 v[96:99], v[170:173], v[202:205], v[96:99]
	v_mfma_f32_16x16x32_bf16 v[88:91], v[162:165], v[210:213], v[88:91]
	v_mfma_f32_16x16x32_bf16 v[84:87], v[170:173], v[210:213], v[84:87]
	v_mfma_f32_16x16x32_bf16 v[72:75], v[162:165], v[218:221], v[72:75]
	v_mfma_f32_16x16x32_bf16 v[68:71], v[170:173], v[218:221], v[68:71]
	s_setprio 0
	s_setprio 1
	v_mfma_f32_16x16x32_bf16 v[124:127], v[174:177], v[190:193], v[124:127]
	v_mfma_f32_16x16x32_bf16 v[120:123], v[182:185], v[190:193], v[120:123]
	v_mfma_f32_16x16x32_bf16 v[108:111], v[174:177], v[198:201], v[108:111]
	v_mfma_f32_16x16x32_bf16 v[104:107], v[182:185], v[198:201], v[104:107]
	v_mfma_f32_16x16x32_bf16 v[92:95], v[174:177], v[206:209], v[92:95]
	v_mfma_f32_16x16x32_bf16 v[80:83], v[182:185], v[206:209], v[80:83]
	v_mfma_f32_16x16x32_bf16 v[76:79], v[174:177], v[214:217], v[76:79]
	v_mfma_f32_16x16x32_bf16 v[64:67], v[182:185], v[214:217], v[64:67]
	v_mfma_f32_16x16x32_bf16 v[124:127], v[178:181], v[194:197], v[124:127]
	v_mfma_f32_16x16x32_bf16 v[120:123], v[186:189], v[194:197], v[120:123]
	v_mfma_f32_16x16x32_bf16 v[108:111], v[178:181], v[202:205], v[108:111]
	v_mfma_f32_16x16x32_bf16 v[104:107], v[186:189], v[202:205], v[104:107]
	v_mfma_f32_16x16x32_bf16 v[92:95], v[178:181], v[210:213], v[92:95]
	v_mfma_f32_16x16x32_bf16 v[80:83], v[186:189], v[210:213], v[80:83]
	v_mfma_f32_16x16x32_bf16 v[76:79], v[178:181], v[218:221], v[76:79]
	v_mfma_f32_16x16x32_bf16 v[64:67], v[186:189], v[218:221], v[64:67]
	s_setprio 0
	s_barrier
	s_add_i32 s36, s58, s40
	v_lshl_add_u64 v[156:157], v[156:157], 0, s[12:13]
	s_mov_b32 m0, s36
	ds_read_b128 v[190:193], v159 offset:49152
	ds_read_b128 v[194:197], v159 offset:50176
	ds_read_b128 v[198:201], v159 offset:51200
	ds_read_b128 v[202:205], v159 offset:52224
	ds_read_b128 v[206:209], v159 offset:53248
	ds_read_b128 v[210:213], v159 offset:54272
	ds_read_b128 v[214:217], v159 offset:55296
	ds_read_b128 v[218:221], v159 offset:56320
	global_load_lds_dwordx4 v[156:157], off
	s_add_i32 m0, s36, 0x2000
	s_add_u32 s34, s34, 0x40080
	v_lshl_add_u64 v[156:157], v[222:223], 0, s[12:13]
	s_addc_u32 s35, s35, 0
	s_add_i32 s36, s59, s40
	global_load_lds_dwordx4 v[156:157], off
	v_lshl_add_u64 v[156:157], s[34:35], 0, v[130:131]
	s_mov_b32 m0, s36
	s_nop 0
	global_load_lds_dwordx4 v[156:157], off
	v_lshl_add_u64 v[156:157], s[34:35], 0, v[134:135]
	s_add_i32 m0, s36, 0x2000
	s_nop 0
	global_load_lds_dwordx4 v[156:157], off
	v_lshl_add_u64 v[156:157], v[224:225], 0, s[12:13]
	s_mov_b32 m0, s45
	s_nop 0
	global_load_lds_dwordx4 v[156:157], off
	v_lshl_add_u64 v[156:157], v[226:227], 0, s[12:13]
	s_mov_b32 m0, s46
	s_nop 0
	global_load_lds_dwordx4 v[156:157], off
	s_waitcnt vmcnt(8)
	s_waitcnt lgkmcnt(0)
	s_barrier
	s_setprio 1
	s_waitcnt lgkmcnt(0)
	v_mfma_f32_16x16x32_bf16 v[56:59], v[152:155], v[190:193], v[56:59]
	v_mfma_f32_16x16x32_bf16 v[52:55], v[166:169], v[190:193], v[52:55]
	v_mfma_f32_16x16x32_bf16 v[40:43], v[152:155], v[198:201], v[40:43]
	v_mfma_f32_16x16x32_bf16 v[36:39], v[166:169], v[198:201], v[36:39]
	v_mfma_f32_16x16x32_bf16 v[24:27], v[152:155], v[206:209], v[24:27]
	v_mfma_f32_16x16x32_bf16 v[20:23], v[166:169], v[206:209], v[20:23]
	v_mfma_f32_16x16x32_bf16 v[8:11], v[152:155], v[214:217], v[8:11]
	v_mfma_f32_16x16x32_bf16 v[4:7], v[166:169], v[214:217], v[4:7]
	v_mfma_f32_16x16x32_bf16 v[56:59], v[162:165], v[194:197], v[56:59]
	v_mfma_f32_16x16x32_bf16 v[52:55], v[170:173], v[194:197], v[52:55]
	v_mfma_f32_16x16x32_bf16 v[40:43], v[162:165], v[202:205], v[40:43]
	v_mfma_f32_16x16x32_bf16 v[36:39], v[170:173], v[202:205], v[36:39]
	v_mfma_f32_16x16x32_bf16 v[24:27], v[162:165], v[210:213], v[24:27]
	v_mfma_f32_16x16x32_bf16 v[20:23], v[170:173], v[210:213], v[20:23]
	v_mfma_f32_16x16x32_bf16 v[8:11], v[162:165], v[218:221], v[8:11]
	v_mfma_f32_16x16x32_bf16 v[4:7], v[170:173], v[218:221], v[4:7]
	s_setprio 0
	s_setprio 1
	v_mfma_f32_16x16x32_bf16 v[60:63], v[174:177], v[190:193], v[60:63]
	v_mfma_f32_16x16x32_bf16 v[48:51], v[182:185], v[190:193], v[48:51]
	v_mfma_f32_16x16x32_bf16 v[44:47], v[174:177], v[198:201], v[44:47]
	v_mfma_f32_16x16x32_bf16 v[32:35], v[182:185], v[198:201], v[32:35]
	v_mfma_f32_16x16x32_bf16 v[28:31], v[174:177], v[206:209], v[28:31]
	v_mfma_f32_16x16x32_bf16 v[16:19], v[182:185], v[206:209], v[16:19]
	v_mfma_f32_16x16x32_bf16 v[12:15], v[174:177], v[214:217], v[12:15]
	v_mfma_f32_16x16x32_bf16 v[0:3], v[182:185], v[214:217], v[0:3]
	v_mfma_f32_16x16x32_bf16 v[60:63], v[178:181], v[194:197], v[60:63]
	v_mfma_f32_16x16x32_bf16 v[48:51], v[186:189], v[194:197], v[48:51]
	v_mfma_f32_16x16x32_bf16 v[44:47], v[178:181], v[202:205], v[44:47]
	v_mfma_f32_16x16x32_bf16 v[32:35], v[186:189], v[202:205], v[32:35]
	v_mfma_f32_16x16x32_bf16 v[28:31], v[178:181], v[210:213], v[28:31]
	v_mfma_f32_16x16x32_bf16 v[16:19], v[186:189], v[210:213], v[16:19]
	v_mfma_f32_16x16x32_bf16 v[12:15], v[178:181], v[218:221], v[12:15]
	v_mfma_f32_16x16x32_bf16 v[0:3], v[186:189], v[218:221], v[0:3]
	s_setprio 0
	s_add_i32 s57, s57, 2
	s_add_u32 s30, s30, 0x100
	s_addc_u32 s31, s31, 0
	s_add_u32 s55, s55, 0x100
	s_addc_u32 s56, s56, 0
	s_cmp_gt_u32 s57, 13
	s_barrier
	s_cbranch_scc0 .LBB0_977
	s_and_b64 vcc, exec, s[14:15]
	s_cbranch_vccz .LBB0_982
	s_barrier
	v_lshl_add_u32 v152, s28, 8, v139
	s_cmp_gt_i32 s26, 21
	s_mov_b64 s[28:29], -1
	s_cbranch_scc1 .LBB0_983

.LBB0_1065:
	ds_read_b128 v[140:143], v147
	ds_read_b128 v[152:155], v147 offset:1024
	ds_read_b128 v[156:159], v147 offset:2048
	ds_read_b128 v[160:163], v147 offset:3072
	ds_read_b128 v[164:167], v148
	ds_read_b128 v[168:171], v148 offset:1024
	ds_read_b128 v[172:175], v148 offset:2048
	ds_read_b128 v[176:179], v148 offset:3072
	s_add_u32 s24, s22, 0x100
	s_addc_u32 s25, s23, 0
	s_cmp_eq_u32 s52, 40
	s_cselect_b32 s29, s7, s25
	s_cselect_b32 s28, s6, s24
	s_cselect_b32 s27, s21, s51
	s_cselect_b32 s26, s20, s50
	v_lshl_add_u64 v[212:213], s[22:23], 0, v[132:133]
	s_add_i32 m0, s35, 0xc000
	ds_read_b128 v[180:183], v149
	ds_read_b128 v[184:187], v149 offset:1024
	ds_read_b128 v[188:191], v149 offset:2048
	ds_read_b128 v[192:195], v149 offset:3072
	ds_read_b128 v[196:199], v149 offset:4096
	ds_read_b128 v[200:203], v149 offset:5120
	ds_read_b128 v[204:207], v149 offset:6144
	ds_read_b128 v[208:211], v149 offset:7168
	global_load_lds_dwordx4 v[212:213], off
	v_lshl_add_u64 v[212:213], s[22:23], 0, v[134:135]
	s_add_i32 m0, s35, 0xe000
	s_nop 0
	global_load_lds_dwordx4 v[212:213], off
	s_waitcnt vmcnt(8)
	s_waitcnt lgkmcnt(0)
	s_barrier
	s_setprio 1
	s_waitcnt lgkmcnt(0)
	v_mfma_f32_16x16x32_bf16 v[124:127], v[140:143], v[180:183], v[124:127]
	v_mfma_f32_16x16x32_bf16 v[120:123], v[156:159], v[180:183], v[120:123]
	v_mfma_f32_16x16x32_bf16 v[108:111], v[140:143], v[188:191], v[108:111]
	v_mfma_f32_16x16x32_bf16 v[104:107], v[156:159], v[188:191], v[104:107]
	v_mfma_f32_16x16x32_bf16 v[92:95], v[140:143], v[196:199], v[92:95]
	v_mfma_f32_16x16x32_bf16 v[88:91], v[156:159], v[196:199], v[88:91]
	v_mfma_f32_16x16x32_bf16 v[76:79], v[140:143], v[204:207], v[76:79]
	v_mfma_f32_16x16x32_bf16 v[72:75], v[156:159], v[204:207], v[72:75]
	v_mfma_f32_16x16x32_bf16 v[124:127], v[152:155], v[184:187], v[124:127]
	v_mfma_f32_16x16x32_bf16 v[120:123], v[160:163], v[184:187], v[120:123]
	v_mfma_f32_16x16x32_bf16 v[108:111], v[152:155], v[192:195], v[108:111]
	v_mfma_f32_16x16x32_bf16 v[104:107], v[160:163], v[192:195], v[104:107]
	v_mfma_f32_16x16x32_bf16 v[92:95], v[152:155], v[200:203], v[92:95]
	v_mfma_f32_16x16x32_bf16 v[88:91], v[160:163], v[200:203], v[88:91]
	v_mfma_f32_16x16x32_bf16 v[76:79], v[152:155], v[208:211], v[76:79]
	v_mfma_f32_16x16x32_bf16 v[72:75], v[160:163], v[208:211], v[72:75]
	s_setprio 0
	s_setprio 1
	v_mfma_f32_16x16x32_bf16 v[116:119], v[164:167], v[180:183], v[116:119]
	v_mfma_f32_16x16x32_bf16 v[112:115], v[172:175], v[180:183], v[112:115]
	v_mfma_f32_16x16x32_bf16 v[100:103], v[164:167], v[188:191], v[100:103]
	v_mfma_f32_16x16x32_bf16 v[96:99], v[172:175], v[188:191], v[96:99]
	v_mfma_f32_16x16x32_bf16 v[84:87], v[164:167], v[196:199], v[84:87]
	v_mfma_f32_16x16x32_bf16 v[80:83], v[172:175], v[196:199], v[80:83]
	v_mfma_f32_16x16x32_bf16 v[68:71], v[164:167], v[204:207], v[68:71]
	v_mfma_f32_16x16x32_bf16 v[64:67], v[172:175], v[204:207], v[64:67]
	v_mfma_f32_16x16x32_bf16 v[116:119], v[168:171], v[184:187], v[116:119]
	v_mfma_f32_16x16x32_bf16 v[112:115], v[176:179], v[184:187], v[112:115]
	v_mfma_f32_16x16x32_bf16 v[100:103], v[168:171], v[192:195], v[100:103]
	v_mfma_f32_16x16x32_bf16 v[96:99], v[176:179], v[192:195], v[96:99]
	v_mfma_f32_16x16x32_bf16 v[84:87], v[168:171], v[200:203], v[84:87]
	v_mfma_f32_16x16x32_bf16 v[80:83], v[176:179], v[200:203], v[80:83]
	v_mfma_f32_16x16x32_bf16 v[68:71], v[168:171], v[208:211], v[68:71]
	v_mfma_f32_16x16x32_bf16 v[64:67], v[176:179], v[208:211], v[64:67]
	s_setprio 0
	s_barrier
	s_add_i32 s22, s44, s34
	v_lshl_add_u64 v[212:213], s[26:27], 0, v[128:129]
	s_mov_b32 m0, s22
	ds_read_b128 v[180:183], v149 offset:16384
	ds_read_b128 v[184:187], v149 offset:17408
	ds_read_b128 v[188:191], v149 offset:18432
	ds_read_b128 v[192:195], v149 offset:19456
	ds_read_b128 v[196:199], v149 offset:20480
	ds_read_b128 v[200:203], v149 offset:21504
	ds_read_b128 v[204:207], v149 offset:22528
	ds_read_b128 v[208:211], v149 offset:23552
	global_load_lds_dwordx4 v[212:213], off
	s_add_i32 m0, s22, 0x2000
	s_add_u32 s22, s26, 0xb0000
	v_lshl_add_u64 v[214:215], s[26:27], 0, v[130:131]
	s_addc_u32 s23, s27, 0
	s_add_i32 s53, s45, s34
	global_load_lds_dwordx4 v[214:215], off
	v_lshl_add_u64 v[216:217], s[22:23], 0, v[128:129]
	s_mov_b32 m0, s53
	v_lshl_add_u64 v[218:219], s[28:29], 0, v[130:131]
	global_load_lds_dwordx4 v[216:217], off
	v_lshl_add_u64 v[216:217], s[22:23], 0, v[130:131]
	s_add_i32 m0, s53, 0x2000
	s_nop 0
	global_load_lds_dwordx4 v[216:217], off
	v_lshl_add_u64 v[216:217], s[28:29], 0, v[128:129]
	s_mov_b32 m0, s35
	s_nop 0
	global_load_lds_dwordx4 v[216:217], off
	s_mov_b32 m0, s36
	s_nop 0
	global_load_lds_dwordx4 v[218:219], off
	s_waitcnt vmcnt(8)
	s_waitcnt lgkmcnt(0)
	s_barrier
	s_setprio 1
	s_waitcnt lgkmcnt(0)
	v_mfma_f32_16x16x32_bf16 v[60:63], v[140:143], v[180:183], v[60:63]
	v_mfma_f32_16x16x32_bf16 v[56:59], v[156:159], v[180:183], v[56:59]
	v_mfma_f32_16x16x32_bf16 v[44:47], v[140:143], v[188:191], v[44:47]
	v_mfma_f32_16x16x32_bf16 v[40:43], v[156:159], v[188:191], v[40:43]
	v_mfma_f32_16x16x32_bf16 v[28:31], v[140:143], v[196:199], v[28:31]
	v_mfma_f32_16x16x32_bf16 v[24:27], v[156:159], v[196:199], v[24:27]
	v_mfma_f32_16x16x32_bf16 v[12:15], v[140:143], v[204:207], v[12:15]
	v_mfma_f32_16x16x32_bf16 v[8:11], v[156:159], v[204:207], v[8:11]
	v_mfma_f32_16x16x32_bf16 v[60:63], v[152:155], v[184:187], v[60:63]
	v_mfma_f32_16x16x32_bf16 v[56:59], v[160:163], v[184:187], v[56:59]
	v_mfma_f32_16x16x32_bf16 v[44:47], v[152:155], v[192:195], v[44:47]
	v_mfma_f32_16x16x32_bf16 v[40:43], v[160:163], v[192:195], v[40:43]
	v_mfma_f32_16x16x32_bf16 v[28:31], v[152:155], v[200:203], v[28:31]
	v_mfma_f32_16x16x32_bf16 v[24:27], v[160:163], v[200:203], v[24:27]
	v_mfma_f32_16x16x32_bf16 v[12:15], v[152:155], v[208:211], v[12:15]
	v_mfma_f32_16x16x32_bf16 v[8:11], v[160:163], v[208:211], v[8:11]
	s_setprio 0
	s_setprio 1
	v_mfma_f32_16x16x32_bf16 v[52:55], v[164:167], v[180:183], v[52:55]
	v_mfma_f32_16x16x32_bf16 v[48:51], v[172:175], v[180:183], v[48:51]
	v_mfma_f32_16x16x32_bf16 v[36:39], v[164:167], v[188:191], v[36:39]
	v_mfma_f32_16x16x32_bf16 v[32:35], v[172:175], v[188:191], v[32:35]
	v_mfma_f32_16x16x32_bf16 v[20:23], v[164:167], v[196:199], v[20:23]
	v_mfma_f32_16x16x32_bf16 v[16:19], v[172:175], v[196:199], v[16:19]
	v_mfma_f32_16x16x32_bf16 v[4:7], v[164:167], v[204:207], v[4:7]
	v_mfma_f32_16x16x32_bf16 v[0:3], v[172:175], v[204:207], v[0:3]
	v_mfma_f32_16x16x32_bf16 v[52:55], v[168:171], v[184:187], v[52:55]
	v_mfma_f32_16x16x32_bf16 v[48:51], v[176:179], v[184:187], v[48:51]
	v_mfma_f32_16x16x32_bf16 v[36:39], v[168:171], v[192:195], v[36:39]
	v_mfma_f32_16x16x32_bf16 v[32:35], v[176:179], v[192:195], v[32:35]
	v_mfma_f32_16x16x32_bf16 v[20:23], v[168:171], v[200:203], v[20:23]
	v_mfma_f32_16x16x32_bf16 v[16:19], v[176:179], v[200:203], v[16:19]
	v_mfma_f32_16x16x32_bf16 v[4:7], v[168:171], v[208:211], v[4:7]
	v_mfma_f32_16x16x32_bf16 v[0:3], v[176:179], v[208:211], v[0:3]
	s_setprio 0
	s_barrier
	s_add_i32 s53, 0, 0x18000
	v_add_u32_e32 v151, s53, v145
	s_add_i32 s54, 0, 0x1c000
	ds_read_b128 v[140:143], v151
	ds_read_b128 v[152:155], v151 offset:1024
	ds_read_b128 v[156:159], v151 offset:2048
	ds_read_b128 v[160:163], v151 offset:3072
	v_add_u32_e32 v151, s54, v145
	ds_read_b128 v[164:167], v151
	ds_read_b128 v[168:171], v151 offset:1024
	ds_read_b128 v[172:175], v151 offset:2048
	ds_read_b128 v[176:179], v151 offset:3072
	s_add_u32 s22, s28, 0xb0000
	s_addc_u32 s23, s29, 0
	s_mov_b32 m0, s37
	v_lshl_add_u64 v[220:221], s[22:23], 0, v[128:129]
	ds_read_b128 v[180:183], v149 offset:32768
	ds_read_b128 v[184:187], v149 offset:33792
	ds_read_b128 v[188:191], v149 offset:34816
	ds_read_b128 v[192:195], v149 offset:35840
	ds_read_b128 v[196:199], v149 offset:36864
	ds_read_b128 v[200:203], v149 offset:37888
	ds_read_b128 v[204:207], v149 offset:38912
	ds_read_b128 v[208:211], v149 offset:39936
	global_load_lds_dwordx4 v[220:221], off
	v_lshl_add_u64 v[220:221], s[22:23], 0, v[130:131]
	s_mov_b32 m0, s38
	s_nop 0
	global_load_lds_dwordx4 v[220:221], off
	s_waitcnt vmcnt(8)
	s_waitcnt lgkmcnt(0)
	s_barrier
	s_setprio 1
	s_waitcnt lgkmcnt(0)
	v_mfma_f32_16x16x32_bf16 v[124:127], v[140:143], v[180:183], v[124:127]
	v_mfma_f32_16x16x32_bf16 v[120:123], v[156:159], v[180:183], v[120:123]
	v_mfma_f32_16x16x32_bf16 v[108:111], v[140:143], v[188:191], v[108:111]
	v_mfma_f32_16x16x32_bf16 v[104:107], v[156:159], v[188:191], v[104:107]
	v_mfma_f32_16x16x32_bf16 v[92:95], v[140:143], v[196:199], v[92:95]
	v_mfma_f32_16x16x32_bf16 v[88:91], v[156:159], v[196:199], v[88:91]
	v_mfma_f32_16x16x32_bf16 v[76:79], v[140:143], v[204:207], v[76:79]
	v_mfma_f32_16x16x32_bf16 v[72:75], v[156:159], v[204:207], v[72:75]
	v_mfma_f32_16x16x32_bf16 v[124:127], v[152:155], v[184:187], v[124:127]
	v_mfma_f32_16x16x32_bf16 v[120:123], v[160:163], v[184:187], v[120:123]
	v_mfma_f32_16x16x32_bf16 v[108:111], v[152:155], v[192:195], v[108:111]
	v_mfma_f32_16x16x32_bf16 v[104:107], v[160:163], v[192:195], v[104:107]
	v_mfma_f32_16x16x32_bf16 v[92:95], v[152:155], v[200:203], v[92:95]
	v_mfma_f32_16x16x32_bf16 v[88:91], v[160:163], v[200:203], v[88:91]
	v_mfma_f32_16x16x32_bf16 v[76:79], v[152:155], v[208:211], v[76:79]
	v_mfma_f32_16x16x32_bf16 v[72:75], v[160:163], v[208:211], v[72:75]
	s_setprio 0
	s_setprio 1
	v_mfma_f32_16x16x32_bf16 v[116:119], v[164:167], v[180:183], v[116:119]
	v_mfma_f32_16x16x32_bf16 v[112:115], v[172:175], v[180:183], v[112:115]
	v_mfma_f32_16x16x32_bf16 v[100:103], v[164:167], v[188:191], v[100:103]
	v_mfma_f32_16x16x32_bf16 v[96:99], v[172:175], v[188:191], v[96:99]
	v_mfma_f32_16x16x32_bf16 v[84:87], v[164:167], v[196:199], v[84:87]
	v_mfma_f32_16x16x32_bf16 v[80:83], v[172:175], v[196:199], v[80:83]
	v_mfma_f32_16x16x32_bf16 v[68:71], v[164:167], v[204:207], v[68:71]
	v_mfma_f32_16x16x32_bf16 v[64:67], v[172:175], v[204:207], v[64:67]
	v_mfma_f32_16x16x32_bf16 v[116:119], v[168:171], v[184:187], v[116:119]
	v_mfma_f32_16x16x32_bf16 v[112:115], v[176:179], v[184:187], v[112:115]
	v_mfma_f32_16x16x32_bf16 v[100:103], v[168:171], v[192:195], v[100:103]
	v_mfma_f32_16x16x32_bf16 v[96:99], v[176:179], v[192:195], v[96:99]
	v_mfma_f32_16x16x32_bf16 v[84:87], v[168:171], v[200:203], v[84:87]
	v_mfma_f32_16x16x32_bf16 v[80:83], v[176:179], v[200:203], v[80:83]
	v_mfma_f32_16x16x32_bf16 v[68:71], v[168:171], v[208:211], v[68:71]
	v_mfma_f32_16x16x32_bf16 v[64:67], v[176:179], v[208:211], v[64:67]
	s_setprio 0
	s_barrier
	s_add_i32 s22, s53, s34
	v_lshl_add_u64 v[212:213], v[212:213], 0, s[16:17]
	s_mov_b32 m0, s22
	ds_read_b128 v[180:183], v149 offset:49152
	ds_read_b128 v[184:187], v149 offset:50176
	ds_read_b128 v[188:191], v149 offset:51200
	ds_read_b128 v[192:195], v149 offset:52224
	ds_read_b128 v[196:199], v149 offset:53248
	ds_read_b128 v[200:203], v149 offset:54272
	ds_read_b128 v[204:207], v149 offset:55296
	ds_read_b128 v[208:211], v149 offset:56320
	global_load_lds_dwordx4 v[212:213], off
	s_add_i32 m0, s22, 0x2000
	s_add_u32 s22, s26, 0xb0080
	v_lshl_add_u64 v[212:213], v[214:215], 0, s[16:17]
	s_addc_u32 s23, s27, 0
	s_add_i32 s26, s54, s34
	global_load_lds_dwordx4 v[212:213], off
	v_lshl_add_u64 v[212:213], s[22:23], 0, v[128:129]
	s_mov_b32 m0, s26
	s_nop 0
	global_load_lds_dwordx4 v[212:213], off
	v_lshl_add_u64 v[212:213], s[22:23], 0, v[130:131]
	s_add_i32 m0, s26, 0x2000
	s_nop 0
	global_load_lds_dwordx4 v[212:213], off
	v_lshl_add_u64 v[212:213], v[216:217], 0, s[16:17]
	s_mov_b32 m0, s40
	s_nop 0
	global_load_lds_dwordx4 v[212:213], off
	v_lshl_add_u64 v[212:213], v[218:219], 0, s[16:17]
	s_mov_b32 m0, s41
	s_nop 0
	global_load_lds_dwordx4 v[212:213], off
	s_waitcnt vmcnt(8)
	s_waitcnt lgkmcnt(0)
	s_barrier
	s_setprio 1
	s_waitcnt lgkmcnt(0)
	v_mfma_f32_16x16x32_bf16 v[60:63], v[140:143], v[180:183], v[60:63]
	v_mfma_f32_16x16x32_bf16 v[56:59], v[156:159], v[180:183], v[56:59]
	v_mfma_f32_16x16x32_bf16 v[44:47], v[140:143], v[188:191], v[44:47]
	v_mfma_f32_16x16x32_bf16 v[40:43], v[156:159], v[188:191], v[40:43]
	v_mfma_f32_16x16x32_bf16 v[28:31], v[140:143], v[196:199], v[28:31]
	v_mfma_f32_16x16x32_bf16 v[24:27], v[156:159], v[196:199], v[24:27]
	v_mfma_f32_16x16x32_bf16 v[12:15], v[140:143], v[204:207], v[12:15]
	v_mfma_f32_16x16x32_bf16 v[8:11], v[156:159], v[204:207], v[8:11]
	v_mfma_f32_16x16x32_bf16 v[60:63], v[152:155], v[184:187], v[60:63]
	v_mfma_f32_16x16x32_bf16 v[56:59], v[160:163], v[184:187], v[56:59]
	v_mfma_f32_16x16x32_bf16 v[44:47], v[152:155], v[192:195], v[44:47]
	v_mfma_f32_16x16x32_bf16 v[40:43], v[160:163], v[192:195], v[40:43]
	v_mfma_f32_16x16x32_bf16 v[28:31], v[152:155], v[200:203], v[28:31]
	v_mfma_f32_16x16x32_bf16 v[24:27], v[160:163], v[200:203], v[24:27]
	v_mfma_f32_16x16x32_bf16 v[12:15], v[152:155], v[208:211], v[12:15]
	v_mfma_f32_16x16x32_bf16 v[8:11], v[160:163], v[208:211], v[8:11]
	s_setprio 0
	s_setprio 1
	v_mfma_f32_16x16x32_bf16 v[52:55], v[164:167], v[180:183], v[52:55]
	v_mfma_f32_16x16x32_bf16 v[48:51], v[172:175], v[180:183], v[48:51]
	v_mfma_f32_16x16x32_bf16 v[36:39], v[164:167], v[188:191], v[36:39]
	v_mfma_f32_16x16x32_bf16 v[32:35], v[172:175], v[188:191], v[32:35]
	v_mfma_f32_16x16x32_bf16 v[20:23], v[164:167], v[196:199], v[20:23]
	v_mfma_f32_16x16x32_bf16 v[16:19], v[172:175], v[196:199], v[16:19]
	v_mfma_f32_16x16x32_bf16 v[4:7], v[164:167], v[204:207], v[4:7]
	v_mfma_f32_16x16x32_bf16 v[0:3], v[172:175], v[204:207], v[0:3]
	v_mfma_f32_16x16x32_bf16 v[52:55], v[168:171], v[184:187], v[52:55]
	v_mfma_f32_16x16x32_bf16 v[48:51], v[176:179], v[184:187], v[48:51]
	v_mfma_f32_16x16x32_bf16 v[36:39], v[168:171], v[192:195], v[36:39]
	v_mfma_f32_16x16x32_bf16 v[32:35], v[176:179], v[192:195], v[32:35]
	v_mfma_f32_16x16x32_bf16 v[20:23], v[168:171], v[200:203], v[20:23]
	v_mfma_f32_16x16x32_bf16 v[16:19], v[176:179], v[200:203], v[16:19]
	v_mfma_f32_16x16x32_bf16 v[4:7], v[168:171], v[208:211], v[4:7]
	v_mfma_f32_16x16x32_bf16 v[0:3], v[176:179], v[208:211], v[0:3]
	s_setprio 0
	s_add_i32 s52, s52, 2
	s_add_u32 s50, s50, 0x100
	s_addc_u32 s51, s51, 0
	s_cmp_gt_u32 s52, 41
	s_mov_b64 s[22:23], s[24:25]
	s_barrier
	s_cbranch_scc0 .LBB0_1065
	s_and_b64 vcc, exec, s[18:19]
	s_cbranch_vccz .LBB0_1068
	s_barrier

.LBB0_1131:
	ds_read_b128 v[154:157], v160
	ds_read_b128 v[166:169], v160 offset:1024
	ds_read_b128 v[170:173], v160 offset:2048
	ds_read_b128 v[174:177], v160 offset:3072
	ds_read_b128 v[178:181], v161
	ds_read_b128 v[182:185], v161 offset:1024
	ds_read_b128 v[186:189], v161 offset:2048
	ds_read_b128 v[190:193], v161 offset:3072
	s_add_u32 s36, s34, 0xfffc0080
	s_addc_u32 s37, s35, -1
	s_cmp_eq_u32 s58, 12
	s_cselect_b32 s39, s23, s37
	s_cselect_b32 s38, s29, s36
	s_cselect_b32 s37, s21, s57
	s_cselect_b32 s36, s31, s56
	v_lshl_add_u64 v[226:227], s[34:35], 0, v[146:147]
	s_add_i32 m0, s43, 0xc000
	ds_read_b128 v[194:197], v162
	ds_read_b128 v[198:201], v162 offset:1024
	ds_read_b128 v[202:205], v162 offset:2048
	ds_read_b128 v[206:209], v162 offset:3072
	ds_read_b128 v[210:213], v162 offset:4096
	ds_read_b128 v[214:217], v162 offset:5120
	ds_read_b128 v[218:221], v162 offset:6144
	ds_read_b128 v[222:225], v162 offset:7168
	global_load_lds_dwordx4 v[226:227], off
	v_lshl_add_u64 v[226:227], s[34:35], 0, v[148:149]
	s_add_i32 m0, s43, 0xe000
	s_nop 0
	global_load_lds_dwordx4 v[226:227], off
	s_waitcnt vmcnt(8)
	s_waitcnt lgkmcnt(0)
	s_barrier
	s_setprio 1
	s_waitcnt lgkmcnt(0)
	v_mfma_f32_16x16x32_bf16 v[116:119], v[154:157], v[194:197], v[116:119]
	v_mfma_f32_16x16x32_bf16 v[112:115], v[170:173], v[194:197], v[112:115]
	v_mfma_f32_16x16x32_bf16 v[100:103], v[154:157], v[202:205], v[100:103]
	v_mfma_f32_16x16x32_bf16 v[96:99], v[170:173], v[202:205], v[96:99]
	v_mfma_f32_16x16x32_bf16 v[88:91], v[154:157], v[210:213], v[88:91]
	v_mfma_f32_16x16x32_bf16 v[84:87], v[170:173], v[210:213], v[84:87]
	v_mfma_f32_16x16x32_bf16 v[72:75], v[154:157], v[218:221], v[72:75]
	v_mfma_f32_16x16x32_bf16 v[68:71], v[170:173], v[218:221], v[68:71]
	v_mfma_f32_16x16x32_bf16 v[116:119], v[166:169], v[198:201], v[116:119]
	v_mfma_f32_16x16x32_bf16 v[112:115], v[174:177], v[198:201], v[112:115]
	v_mfma_f32_16x16x32_bf16 v[100:103], v[166:169], v[206:209], v[100:103]
	v_mfma_f32_16x16x32_bf16 v[96:99], v[174:177], v[206:209], v[96:99]
	v_mfma_f32_16x16x32_bf16 v[88:91], v[166:169], v[214:217], v[88:91]
	v_mfma_f32_16x16x32_bf16 v[84:87], v[174:177], v[214:217], v[84:87]
	v_mfma_f32_16x16x32_bf16 v[72:75], v[166:169], v[222:225], v[72:75]
	v_mfma_f32_16x16x32_bf16 v[68:71], v[174:177], v[222:225], v[68:71]
	s_setprio 0
	s_setprio 1
	v_mfma_f32_16x16x32_bf16 v[124:127], v[178:181], v[194:197], v[124:127]
	v_mfma_f32_16x16x32_bf16 v[120:123], v[186:189], v[194:197], v[120:123]
	v_mfma_f32_16x16x32_bf16 v[108:111], v[178:181], v[202:205], v[108:111]
	v_mfma_f32_16x16x32_bf16 v[104:107], v[186:189], v[202:205], v[104:107]
	v_mfma_f32_16x16x32_bf16 v[92:95], v[178:181], v[210:213], v[92:95]
	v_mfma_f32_16x16x32_bf16 v[80:83], v[186:189], v[210:213], v[80:83]
	v_mfma_f32_16x16x32_bf16 v[76:79], v[178:181], v[218:221], v[76:79]
	v_mfma_f32_16x16x32_bf16 v[64:67], v[186:189], v[218:221], v[64:67]
	v_mfma_f32_16x16x32_bf16 v[124:127], v[182:185], v[198:201], v[124:127]
	v_mfma_f32_16x16x32_bf16 v[120:123], v[190:193], v[198:201], v[120:123]
	v_mfma_f32_16x16x32_bf16 v[108:111], v[182:185], v[206:209], v[108:111]
	v_mfma_f32_16x16x32_bf16 v[104:107], v[190:193], v[206:209], v[104:107]
	v_mfma_f32_16x16x32_bf16 v[92:95], v[182:185], v[214:217], v[92:95]
	v_mfma_f32_16x16x32_bf16 v[80:83], v[190:193], v[214:217], v[80:83]
	v_mfma_f32_16x16x32_bf16 v[76:79], v[182:185], v[222:225], v[76:79]
	v_mfma_f32_16x16x32_bf16 v[64:67], v[190:193], v[222:225], v[64:67]
	s_setprio 0
	s_barrier
	s_add_i32 s59, s52, s42
	v_lshl_add_u64 v[226:227], s[36:37], 0, v[130:131]
	s_mov_b32 m0, s59
	ds_read_b128 v[194:197], v162 offset:16384
	ds_read_b128 v[198:201], v162 offset:17408
	ds_read_b128 v[202:205], v162 offset:18432
	ds_read_b128 v[206:209], v162 offset:19456
	ds_read_b128 v[210:213], v162 offset:20480
	ds_read_b128 v[214:217], v162 offset:21504
	ds_read_b128 v[218:221], v162 offset:22528
	ds_read_b128 v[222:225], v162 offset:23552
	global_load_lds_dwordx4 v[226:227], off
	s_add_i32 m0, s59, 0x2000
	s_add_u32 s60, s36, 0x40000
	v_lshl_add_u64 v[228:229], s[36:37], 0, v[134:135]
	s_addc_u32 s61, s37, 0
	s_add_i32 s59, s53, s42
	global_load_lds_dwordx4 v[228:229], off
	v_lshl_add_u64 v[230:231], s[60:61], 0, v[130:131]
	s_mov_b32 m0, s59
	v_lshl_add_u64 v[232:233], s[38:39], 0, v[132:133]
	global_load_lds_dwordx4 v[230:231], off
	v_lshl_add_u64 v[230:231], s[60:61], 0, v[134:135]
	s_add_i32 m0, s59, 0x2000
	s_nop 0
	global_load_lds_dwordx4 v[230:231], off
	v_lshl_add_u64 v[230:231], s[38:39], 0, v[128:129]
	s_mov_b32 m0, s43
	s_nop 0
	global_load_lds_dwordx4 v[230:231], off
	s_mov_b32 m0, s44
	s_nop 0
	global_load_lds_dwordx4 v[232:233], off
	s_waitcnt vmcnt(8)
	s_waitcnt lgkmcnt(0)
	s_barrier
	s_setprio 1
	s_waitcnt lgkmcnt(0)
	v_mfma_f32_16x16x32_bf16 v[56:59], v[154:157], v[194:197], v[56:59]
	v_mfma_f32_16x16x32_bf16 v[52:55], v[170:173], v[194:197], v[52:55]
	v_mfma_f32_16x16x32_bf16 v[40:43], v[154:157], v[202:205], v[40:43]
	v_mfma_f32_16x16x32_bf16 v[36:39], v[170:173], v[202:205], v[36:39]
	v_mfma_f32_16x16x32_bf16 v[24:27], v[154:157], v[210:213], v[24:27]
	v_mfma_f32_16x16x32_bf16 v[20:23], v[170:173], v[210:213], v[20:23]
	v_mfma_f32_16x16x32_bf16 v[8:11], v[154:157], v[218:221], v[8:11]
	v_mfma_f32_16x16x32_bf16 v[4:7], v[170:173], v[218:221], v[4:7]
	v_mfma_f32_16x16x32_bf16 v[56:59], v[166:169], v[198:201], v[56:59]
	v_mfma_f32_16x16x32_bf16 v[52:55], v[174:177], v[198:201], v[52:55]
	v_mfma_f32_16x16x32_bf16 v[40:43], v[166:169], v[206:209], v[40:43]
	v_mfma_f32_16x16x32_bf16 v[36:39], v[174:177], v[206:209], v[36:39]
	v_mfma_f32_16x16x32_bf16 v[24:27], v[166:169], v[214:217], v[24:27]
	v_mfma_f32_16x16x32_bf16 v[20:23], v[174:177], v[214:217], v[20:23]
	v_mfma_f32_16x16x32_bf16 v[8:11], v[166:169], v[222:225], v[8:11]
	v_mfma_f32_16x16x32_bf16 v[4:7], v[174:177], v[222:225], v[4:7]
	s_setprio 0
	s_setprio 1
	v_mfma_f32_16x16x32_bf16 v[60:63], v[178:181], v[194:197], v[60:63]
	v_mfma_f32_16x16x32_bf16 v[48:51], v[186:189], v[194:197], v[48:51]
	v_mfma_f32_16x16x32_bf16 v[44:47], v[178:181], v[202:205], v[44:47]
	v_mfma_f32_16x16x32_bf16 v[32:35], v[186:189], v[202:205], v[32:35]
	v_mfma_f32_16x16x32_bf16 v[28:31], v[178:181], v[210:213], v[28:31]
	v_mfma_f32_16x16x32_bf16 v[16:19], v[186:189], v[210:213], v[16:19]
	v_mfma_f32_16x16x32_bf16 v[12:15], v[178:181], v[218:221], v[12:15]
	v_mfma_f32_16x16x32_bf16 v[0:3], v[186:189], v[218:221], v[0:3]
	v_mfma_f32_16x16x32_bf16 v[60:63], v[182:185], v[198:201], v[60:63]
	v_mfma_f32_16x16x32_bf16 v[48:51], v[190:193], v[198:201], v[48:51]
	v_mfma_f32_16x16x32_bf16 v[44:47], v[182:185], v[206:209], v[44:47]
	v_mfma_f32_16x16x32_bf16 v[32:35], v[190:193], v[206:209], v[32:35]
	v_mfma_f32_16x16x32_bf16 v[28:31], v[182:185], v[214:217], v[28:31]
	v_mfma_f32_16x16x32_bf16 v[16:19], v[190:193], v[214:217], v[16:19]
	v_mfma_f32_16x16x32_bf16 v[12:15], v[182:185], v[222:225], v[12:15]
	v_mfma_f32_16x16x32_bf16 v[0:3], v[190:193], v[222:225], v[0:3]
	s_setprio 0
	s_barrier
	s_add_i32 s59, 0, 0x18000
	v_add_u32_e32 v165, s59, v159
	s_add_i32 s60, 0, 0x1c000
	ds_read_b128 v[154:157], v165
	ds_read_b128 v[166:169], v165 offset:1024
	ds_read_b128 v[170:173], v165 offset:2048
	ds_read_b128 v[174:177], v165 offset:3072
	v_add_u32_e32 v165, s60, v159
	ds_read_b128 v[178:181], v165
	ds_read_b128 v[182:185], v165 offset:1024
	ds_read_b128 v[186:189], v165 offset:2048
	ds_read_b128 v[190:193], v165 offset:3072
	s_add_u32 s38, s38, 0x40000
	s_addc_u32 s39, s39, 0
	s_mov_b32 m0, s45
	v_lshl_add_u64 v[234:235], s[38:39], 0, v[128:129]
	ds_read_b128 v[194:197], v162 offset:32768
	ds_read_b128 v[198:201], v162 offset:33792
	ds_read_b128 v[202:205], v162 offset:34816
	ds_read_b128 v[206:209], v162 offset:35840
	ds_read_b128 v[210:213], v162 offset:36864
	ds_read_b128 v[214:217], v162 offset:37888
	ds_read_b128 v[218:221], v162 offset:38912
	ds_read_b128 v[222:225], v162 offset:39936
	global_load_lds_dwordx4 v[234:235], off
	v_lshl_add_u64 v[234:235], s[38:39], 0, v[132:133]
	s_mov_b32 m0, s46
	s_nop 0
	global_load_lds_dwordx4 v[234:235], off
	s_waitcnt vmcnt(8)
	s_waitcnt lgkmcnt(0)
	s_barrier
	s_setprio 1
	s_waitcnt lgkmcnt(0)
	v_mfma_f32_16x16x32_bf16 v[116:119], v[154:157], v[194:197], v[116:119]
	v_mfma_f32_16x16x32_bf16 v[112:115], v[170:173], v[194:197], v[112:115]
	v_mfma_f32_16x16x32_bf16 v[100:103], v[154:157], v[202:205], v[100:103]
	v_mfma_f32_16x16x32_bf16 v[96:99], v[170:173], v[202:205], v[96:99]
	v_mfma_f32_16x16x32_bf16 v[88:91], v[154:157], v[210:213], v[88:91]
	v_mfma_f32_16x16x32_bf16 v[84:87], v[170:173], v[210:213], v[84:87]
	v_mfma_f32_16x16x32_bf16 v[72:75], v[154:157], v[218:221], v[72:75]
	v_mfma_f32_16x16x32_bf16 v[68:71], v[170:173], v[218:221], v[68:71]
	v_mfma_f32_16x16x32_bf16 v[116:119], v[166:169], v[198:201], v[116:119]
	v_mfma_f32_16x16x32_bf16 v[112:115], v[174:177], v[198:201], v[112:115]
	v_mfma_f32_16x16x32_bf16 v[100:103], v[166:169], v[206:209], v[100:103]
	v_mfma_f32_16x16x32_bf16 v[96:99], v[174:177], v[206:209], v[96:99]
	v_mfma_f32_16x16x32_bf16 v[88:91], v[166:169], v[214:217], v[88:91]
	v_mfma_f32_16x16x32_bf16 v[84:87], v[174:177], v[214:217], v[84:87]
	v_mfma_f32_16x16x32_bf16 v[72:75], v[166:169], v[222:225], v[72:75]
	v_mfma_f32_16x16x32_bf16 v[68:71], v[174:177], v[222:225], v[68:71]
	s_setprio 0
	s_setprio 1
	v_mfma_f32_16x16x32_bf16 v[124:127], v[178:181], v[194:197], v[124:127]
	v_mfma_f32_16x16x32_bf16 v[120:123], v[186:189], v[194:197], v[120:123]
	v_mfma_f32_16x16x32_bf16 v[108:111], v[178:181], v[202:205], v[108:111]
	v_mfma_f32_16x16x32_bf16 v[104:107], v[186:189], v[202:205], v[104:107]
	v_mfma_f32_16x16x32_bf16 v[92:95], v[178:181], v[210:213], v[92:95]
	v_mfma_f32_16x16x32_bf16 v[80:83], v[186:189], v[210:213], v[80:83]
	v_mfma_f32_16x16x32_bf16 v[76:79], v[178:181], v[218:221], v[76:79]
	v_mfma_f32_16x16x32_bf16 v[64:67], v[186:189], v[218:221], v[64:67]
	v_mfma_f32_16x16x32_bf16 v[124:127], v[182:185], v[198:201], v[124:127]
	v_mfma_f32_16x16x32_bf16 v[120:123], v[190:193], v[198:201], v[120:123]
	v_mfma_f32_16x16x32_bf16 v[108:111], v[182:185], v[206:209], v[108:111]
	v_mfma_f32_16x16x32_bf16 v[104:107], v[190:193], v[206:209], v[104:107]
	v_mfma_f32_16x16x32_bf16 v[92:95], v[182:185], v[214:217], v[92:95]
	v_mfma_f32_16x16x32_bf16 v[80:83], v[190:193], v[214:217], v[80:83]
	v_mfma_f32_16x16x32_bf16 v[76:79], v[182:185], v[222:225], v[76:79]
	v_mfma_f32_16x16x32_bf16 v[64:67], v[190:193], v[222:225], v[64:67]
	s_setprio 0
	s_barrier
	s_add_i32 s38, s59, s42
	v_lshl_add_u64 v[226:227], v[226:227], 0, s[12:13]
	s_mov_b32 m0, s38
	ds_read_b128 v[194:197], v162 offset:49152
	ds_read_b128 v[198:201], v162 offset:50176
	ds_read_b128 v[202:205], v162 offset:51200
	ds_read_b128 v[206:209], v162 offset:52224
	ds_read_b128 v[210:213], v162 offset:53248
	ds_read_b128 v[214:217], v162 offset:54272
	ds_read_b128 v[218:221], v162 offset:55296
	ds_read_b128 v[222:225], v162 offset:56320
	global_load_lds_dwordx4 v[226:227], off
	s_add_i32 m0, s38, 0x2000
	s_add_u32 s36, s36, 0x40080
	v_lshl_add_u64 v[226:227], v[228:229], 0, s[12:13]
	s_addc_u32 s37, s37, 0
	s_add_i32 s38, s60, s42
	global_load_lds_dwordx4 v[226:227], off
	v_lshl_add_u64 v[226:227], s[36:37], 0, v[130:131]
	s_mov_b32 m0, s38
	s_nop 0
	global_load_lds_dwordx4 v[226:227], off
	v_lshl_add_u64 v[226:227], s[36:37], 0, v[134:135]
	s_add_i32 m0, s38, 0x2000
	s_nop 0
	global_load_lds_dwordx4 v[226:227], off
	v_lshl_add_u64 v[226:227], v[230:231], 0, s[12:13]
	s_mov_b32 m0, s47
	s_nop 0
	global_load_lds_dwordx4 v[226:227], off
	v_lshl_add_u64 v[226:227], v[232:233], 0, s[12:13]
	s_mov_b32 m0, s48
	s_nop 0
	global_load_lds_dwordx4 v[226:227], off
	s_waitcnt vmcnt(8)
	s_waitcnt lgkmcnt(0)
	s_barrier
	s_setprio 1
	s_waitcnt lgkmcnt(0)
	v_mfma_f32_16x16x32_bf16 v[56:59], v[154:157], v[194:197], v[56:59]
	v_mfma_f32_16x16x32_bf16 v[52:55], v[170:173], v[194:197], v[52:55]
	v_mfma_f32_16x16x32_bf16 v[40:43], v[154:157], v[202:205], v[40:43]
	v_mfma_f32_16x16x32_bf16 v[36:39], v[170:173], v[202:205], v[36:39]
	v_mfma_f32_16x16x32_bf16 v[24:27], v[154:157], v[210:213], v[24:27]
	v_mfma_f32_16x16x32_bf16 v[20:23], v[170:173], v[210:213], v[20:23]
	v_mfma_f32_16x16x32_bf16 v[8:11], v[154:157], v[218:221], v[8:11]
	v_mfma_f32_16x16x32_bf16 v[4:7], v[170:173], v[218:221], v[4:7]
	v_mfma_f32_16x16x32_bf16 v[56:59], v[166:169], v[198:201], v[56:59]
	v_mfma_f32_16x16x32_bf16 v[52:55], v[174:177], v[198:201], v[52:55]
	v_mfma_f32_16x16x32_bf16 v[40:43], v[166:169], v[206:209], v[40:43]
	v_mfma_f32_16x16x32_bf16 v[36:39], v[174:177], v[206:209], v[36:39]
	v_mfma_f32_16x16x32_bf16 v[24:27], v[166:169], v[214:217], v[24:27]
	v_mfma_f32_16x16x32_bf16 v[20:23], v[174:177], v[214:217], v[20:23]
	v_mfma_f32_16x16x32_bf16 v[8:11], v[166:169], v[222:225], v[8:11]
	v_mfma_f32_16x16x32_bf16 v[4:7], v[174:177], v[222:225], v[4:7]
	s_setprio 0
	s_setprio 1
	v_mfma_f32_16x16x32_bf16 v[60:63], v[178:181], v[194:197], v[60:63]
	v_mfma_f32_16x16x32_bf16 v[48:51], v[186:189], v[194:197], v[48:51]
	v_mfma_f32_16x16x32_bf16 v[44:47], v[178:181], v[202:205], v[44:47]
	v_mfma_f32_16x16x32_bf16 v[32:35], v[186:189], v[202:205], v[32:35]
	v_mfma_f32_16x16x32_bf16 v[28:31], v[178:181], v[210:213], v[28:31]
	v_mfma_f32_16x16x32_bf16 v[16:19], v[186:189], v[210:213], v[16:19]
	v_mfma_f32_16x16x32_bf16 v[12:15], v[178:181], v[218:221], v[12:15]
	v_mfma_f32_16x16x32_bf16 v[0:3], v[186:189], v[218:221], v[0:3]
	v_mfma_f32_16x16x32_bf16 v[60:63], v[182:185], v[198:201], v[60:63]
	v_mfma_f32_16x16x32_bf16 v[48:51], v[190:193], v[198:201], v[48:51]
	v_mfma_f32_16x16x32_bf16 v[44:47], v[182:185], v[206:209], v[44:47]
	v_mfma_f32_16x16x32_bf16 v[32:35], v[190:193], v[206:209], v[32:35]
	v_mfma_f32_16x16x32_bf16 v[28:31], v[182:185], v[214:217], v[28:31]
	v_mfma_f32_16x16x32_bf16 v[16:19], v[190:193], v[214:217], v[16:19]
	v_mfma_f32_16x16x32_bf16 v[12:15], v[182:185], v[222:225], v[12:15]
	v_mfma_f32_16x16x32_bf16 v[0:3], v[190:193], v[222:225], v[0:3]
	s_setprio 0
	s_add_i32 s58, s58, 2
	s_add_u32 s34, s34, 0x100
	s_addc_u32 s35, s35, 0
	s_add_u32 s56, s56, 0x100
	s_addc_u32 s57, s57, 0
	s_cmp_gt_u32 s58, 13
	s_barrier
	s_cbranch_scc0 .LBB0_1131
	s_and_b64 vcc, exec, s[14:15]
	s_cbranch_vccz .LBB0_1136
	s_barrier
	v_lshl_add_u32 v154, s30, 8, v158
	s_cmp_gt_i32 s28, 21
	s_mov_b64 s[30:31], -1
	s_cbranch_scc1 .LBB0_1137

.LBB0_1219:
	ds_read_b128 v[140:143], v147
	ds_read_b128 v[152:155], v147 offset:1024
	ds_read_b128 v[156:159], v147 offset:2048
	ds_read_b128 v[160:163], v147 offset:3072
	ds_read_b128 v[164:167], v148
	ds_read_b128 v[168:171], v148 offset:1024
	ds_read_b128 v[172:175], v148 offset:2048
	ds_read_b128 v[176:179], v148 offset:3072
	s_add_u32 s26, s24, 0x100
	s_addc_u32 s27, s25, 0
	s_cmp_eq_u32 s54, 40
	s_cselect_b32 s31, s9, s27
	s_cselect_b32 s30, s8, s26
	s_cselect_b32 s29, s23, s53
	s_cselect_b32 s28, s22, s52
	v_lshl_add_u64 v[212:213], s[24:25], 0, v[132:133]
	s_add_i32 m0, s37, 0xc000
	ds_read_b128 v[180:183], v149
	ds_read_b128 v[184:187], v149 offset:1024
	ds_read_b128 v[188:191], v149 offset:2048
	ds_read_b128 v[192:195], v149 offset:3072
	ds_read_b128 v[196:199], v149 offset:4096
	ds_read_b128 v[200:203], v149 offset:5120
	ds_read_b128 v[204:207], v149 offset:6144
	ds_read_b128 v[208:211], v149 offset:7168
	global_load_lds_dwordx4 v[212:213], off
	v_lshl_add_u64 v[212:213], s[24:25], 0, v[134:135]
	s_add_i32 m0, s37, 0xe000
	s_nop 0
	global_load_lds_dwordx4 v[212:213], off
	s_waitcnt vmcnt(8)
	s_waitcnt lgkmcnt(0)
	s_barrier
	s_setprio 1
	s_waitcnt lgkmcnt(0)
	v_mfma_f32_16x16x32_bf16 v[124:127], v[140:143], v[180:183], v[124:127]
	v_mfma_f32_16x16x32_bf16 v[120:123], v[156:159], v[180:183], v[120:123]
	v_mfma_f32_16x16x32_bf16 v[108:111], v[140:143], v[188:191], v[108:111]
	v_mfma_f32_16x16x32_bf16 v[104:107], v[156:159], v[188:191], v[104:107]
	v_mfma_f32_16x16x32_bf16 v[92:95], v[140:143], v[196:199], v[92:95]
	v_mfma_f32_16x16x32_bf16 v[88:91], v[156:159], v[196:199], v[88:91]
	v_mfma_f32_16x16x32_bf16 v[76:79], v[140:143], v[204:207], v[76:79]
	v_mfma_f32_16x16x32_bf16 v[72:75], v[156:159], v[204:207], v[72:75]
	v_mfma_f32_16x16x32_bf16 v[124:127], v[152:155], v[184:187], v[124:127]
	v_mfma_f32_16x16x32_bf16 v[120:123], v[160:163], v[184:187], v[120:123]
	v_mfma_f32_16x16x32_bf16 v[108:111], v[152:155], v[192:195], v[108:111]
	v_mfma_f32_16x16x32_bf16 v[104:107], v[160:163], v[192:195], v[104:107]
	v_mfma_f32_16x16x32_bf16 v[92:95], v[152:155], v[200:203], v[92:95]
	v_mfma_f32_16x16x32_bf16 v[88:91], v[160:163], v[200:203], v[88:91]
	v_mfma_f32_16x16x32_bf16 v[76:79], v[152:155], v[208:211], v[76:79]
	v_mfma_f32_16x16x32_bf16 v[72:75], v[160:163], v[208:211], v[72:75]
	s_setprio 0
	s_setprio 1
	v_mfma_f32_16x16x32_bf16 v[116:119], v[164:167], v[180:183], v[116:119]
	v_mfma_f32_16x16x32_bf16 v[112:115], v[172:175], v[180:183], v[112:115]
	v_mfma_f32_16x16x32_bf16 v[100:103], v[164:167], v[188:191], v[100:103]
	v_mfma_f32_16x16x32_bf16 v[96:99], v[172:175], v[188:191], v[96:99]
	v_mfma_f32_16x16x32_bf16 v[84:87], v[164:167], v[196:199], v[84:87]
	v_mfma_f32_16x16x32_bf16 v[80:83], v[172:175], v[196:199], v[80:83]
	v_mfma_f32_16x16x32_bf16 v[68:71], v[164:167], v[204:207], v[68:71]
	v_mfma_f32_16x16x32_bf16 v[64:67], v[172:175], v[204:207], v[64:67]
	v_mfma_f32_16x16x32_bf16 v[116:119], v[168:171], v[184:187], v[116:119]
	v_mfma_f32_16x16x32_bf16 v[112:115], v[176:179], v[184:187], v[112:115]
	v_mfma_f32_16x16x32_bf16 v[100:103], v[168:171], v[192:195], v[100:103]
	v_mfma_f32_16x16x32_bf16 v[96:99], v[176:179], v[192:195], v[96:99]
	v_mfma_f32_16x16x32_bf16 v[84:87], v[168:171], v[200:203], v[84:87]
	v_mfma_f32_16x16x32_bf16 v[80:83], v[176:179], v[200:203], v[80:83]
	v_mfma_f32_16x16x32_bf16 v[68:71], v[168:171], v[208:211], v[68:71]
	v_mfma_f32_16x16x32_bf16 v[64:67], v[176:179], v[208:211], v[64:67]
	s_setprio 0
	s_barrier
	s_add_i32 s24, s46, s36
	v_lshl_add_u64 v[212:213], s[28:29], 0, v[128:129]
	s_mov_b32 m0, s24
	ds_read_b128 v[180:183], v149 offset:16384
	ds_read_b128 v[184:187], v149 offset:17408
	ds_read_b128 v[188:191], v149 offset:18432
	ds_read_b128 v[192:195], v149 offset:19456
	ds_read_b128 v[196:199], v149 offset:20480
	ds_read_b128 v[200:203], v149 offset:21504
	ds_read_b128 v[204:207], v149 offset:22528
	ds_read_b128 v[208:211], v149 offset:23552
	global_load_lds_dwordx4 v[212:213], off
	s_add_i32 m0, s24, 0x2000
	s_add_u32 s24, s28, 0xb0000
	v_lshl_add_u64 v[214:215], s[28:29], 0, v[130:131]
	s_addc_u32 s25, s29, 0
	s_add_i32 s55, s47, s36
	global_load_lds_dwordx4 v[214:215], off
	v_lshl_add_u64 v[216:217], s[24:25], 0, v[128:129]
	s_mov_b32 m0, s55
	v_lshl_add_u64 v[218:219], s[30:31], 0, v[130:131]
	global_load_lds_dwordx4 v[216:217], off
	v_lshl_add_u64 v[216:217], s[24:25], 0, v[130:131]
	s_add_i32 m0, s55, 0x2000
	s_nop 0
	global_load_lds_dwordx4 v[216:217], off
	v_lshl_add_u64 v[216:217], s[30:31], 0, v[128:129]
	s_mov_b32 m0, s37
	s_nop 0
	global_load_lds_dwordx4 v[216:217], off
	s_mov_b32 m0, s38
	s_nop 0
	global_load_lds_dwordx4 v[218:219], off
	s_waitcnt vmcnt(8)
	s_waitcnt lgkmcnt(0)
	s_barrier
	s_setprio 1
	s_waitcnt lgkmcnt(0)
	v_mfma_f32_16x16x32_bf16 v[60:63], v[140:143], v[180:183], v[60:63]
	v_mfma_f32_16x16x32_bf16 v[56:59], v[156:159], v[180:183], v[56:59]
	v_mfma_f32_16x16x32_bf16 v[44:47], v[140:143], v[188:191], v[44:47]
	v_mfma_f32_16x16x32_bf16 v[40:43], v[156:159], v[188:191], v[40:43]
	v_mfma_f32_16x16x32_bf16 v[28:31], v[140:143], v[196:199], v[28:31]
	v_mfma_f32_16x16x32_bf16 v[24:27], v[156:159], v[196:199], v[24:27]
	v_mfma_f32_16x16x32_bf16 v[12:15], v[140:143], v[204:207], v[12:15]
	v_mfma_f32_16x16x32_bf16 v[8:11], v[156:159], v[204:207], v[8:11]
	v_mfma_f32_16x16x32_bf16 v[60:63], v[152:155], v[184:187], v[60:63]
	v_mfma_f32_16x16x32_bf16 v[56:59], v[160:163], v[184:187], v[56:59]
	v_mfma_f32_16x16x32_bf16 v[44:47], v[152:155], v[192:195], v[44:47]
	v_mfma_f32_16x16x32_bf16 v[40:43], v[160:163], v[192:195], v[40:43]
	v_mfma_f32_16x16x32_bf16 v[28:31], v[152:155], v[200:203], v[28:31]
	v_mfma_f32_16x16x32_bf16 v[24:27], v[160:163], v[200:203], v[24:27]
	v_mfma_f32_16x16x32_bf16 v[12:15], v[152:155], v[208:211], v[12:15]
	v_mfma_f32_16x16x32_bf16 v[8:11], v[160:163], v[208:211], v[8:11]
	s_setprio 0
	s_setprio 1
	v_mfma_f32_16x16x32_bf16 v[52:55], v[164:167], v[180:183], v[52:55]
	v_mfma_f32_16x16x32_bf16 v[48:51], v[172:175], v[180:183], v[48:51]
	v_mfma_f32_16x16x32_bf16 v[36:39], v[164:167], v[188:191], v[36:39]
	v_mfma_f32_16x16x32_bf16 v[32:35], v[172:175], v[188:191], v[32:35]
	v_mfma_f32_16x16x32_bf16 v[20:23], v[164:167], v[196:199], v[20:23]
	v_mfma_f32_16x16x32_bf16 v[16:19], v[172:175], v[196:199], v[16:19]
	v_mfma_f32_16x16x32_bf16 v[4:7], v[164:167], v[204:207], v[4:7]
	v_mfma_f32_16x16x32_bf16 v[0:3], v[172:175], v[204:207], v[0:3]
	v_mfma_f32_16x16x32_bf16 v[52:55], v[168:171], v[184:187], v[52:55]
	v_mfma_f32_16x16x32_bf16 v[48:51], v[176:179], v[184:187], v[48:51]
	v_mfma_f32_16x16x32_bf16 v[36:39], v[168:171], v[192:195], v[36:39]
	v_mfma_f32_16x16x32_bf16 v[32:35], v[176:179], v[192:195], v[32:35]
	v_mfma_f32_16x16x32_bf16 v[20:23], v[168:171], v[200:203], v[20:23]
	v_mfma_f32_16x16x32_bf16 v[16:19], v[176:179], v[200:203], v[16:19]
	v_mfma_f32_16x16x32_bf16 v[4:7], v[168:171], v[208:211], v[4:7]
	v_mfma_f32_16x16x32_bf16 v[0:3], v[176:179], v[208:211], v[0:3]
	s_setprio 0
	s_barrier
	s_add_i32 s55, 0, 0x18000
	v_add_u32_e32 v151, s55, v145
	s_add_i32 s56, 0, 0x1c000
	ds_read_b128 v[140:143], v151
	ds_read_b128 v[152:155], v151 offset:1024
	ds_read_b128 v[156:159], v151 offset:2048
	ds_read_b128 v[160:163], v151 offset:3072
	v_add_u32_e32 v151, s56, v145
	ds_read_b128 v[164:167], v151
	ds_read_b128 v[168:171], v151 offset:1024
	ds_read_b128 v[172:175], v151 offset:2048
	ds_read_b128 v[176:179], v151 offset:3072
	s_add_u32 s24, s30, 0xb0000
	s_addc_u32 s25, s31, 0
	s_mov_b32 m0, s39
	v_lshl_add_u64 v[220:221], s[24:25], 0, v[128:129]
	ds_read_b128 v[180:183], v149 offset:32768
	ds_read_b128 v[184:187], v149 offset:33792
	ds_read_b128 v[188:191], v149 offset:34816
	ds_read_b128 v[192:195], v149 offset:35840
	ds_read_b128 v[196:199], v149 offset:36864
	ds_read_b128 v[200:203], v149 offset:37888
	ds_read_b128 v[204:207], v149 offset:38912
	ds_read_b128 v[208:211], v149 offset:39936
	global_load_lds_dwordx4 v[220:221], off
	v_lshl_add_u64 v[220:221], s[24:25], 0, v[130:131]
	s_mov_b32 m0, s40
	s_nop 0
	global_load_lds_dwordx4 v[220:221], off
	s_waitcnt vmcnt(8)
	s_waitcnt lgkmcnt(0)
	s_barrier
	s_setprio 1
	s_waitcnt lgkmcnt(0)
	v_mfma_f32_16x16x32_bf16 v[124:127], v[140:143], v[180:183], v[124:127]
	v_mfma_f32_16x16x32_bf16 v[120:123], v[156:159], v[180:183], v[120:123]
	v_mfma_f32_16x16x32_bf16 v[108:111], v[140:143], v[188:191], v[108:111]
	v_mfma_f32_16x16x32_bf16 v[104:107], v[156:159], v[188:191], v[104:107]
	v_mfma_f32_16x16x32_bf16 v[92:95], v[140:143], v[196:199], v[92:95]
	v_mfma_f32_16x16x32_bf16 v[88:91], v[156:159], v[196:199], v[88:91]
	v_mfma_f32_16x16x32_bf16 v[76:79], v[140:143], v[204:207], v[76:79]
	v_mfma_f32_16x16x32_bf16 v[72:75], v[156:159], v[204:207], v[72:75]
	v_mfma_f32_16x16x32_bf16 v[124:127], v[152:155], v[184:187], v[124:127]
	v_mfma_f32_16x16x32_bf16 v[120:123], v[160:163], v[184:187], v[120:123]
	v_mfma_f32_16x16x32_bf16 v[108:111], v[152:155], v[192:195], v[108:111]
	v_mfma_f32_16x16x32_bf16 v[104:107], v[160:163], v[192:195], v[104:107]
	v_mfma_f32_16x16x32_bf16 v[92:95], v[152:155], v[200:203], v[92:95]
	v_mfma_f32_16x16x32_bf16 v[88:91], v[160:163], v[200:203], v[88:91]
	v_mfma_f32_16x16x32_bf16 v[76:79], v[152:155], v[208:211], v[76:79]
	v_mfma_f32_16x16x32_bf16 v[72:75], v[160:163], v[208:211], v[72:75]
	s_setprio 0
	s_setprio 1
	v_mfma_f32_16x16x32_bf16 v[116:119], v[164:167], v[180:183], v[116:119]
	v_mfma_f32_16x16x32_bf16 v[112:115], v[172:175], v[180:183], v[112:115]
	v_mfma_f32_16x16x32_bf16 v[100:103], v[164:167], v[188:191], v[100:103]
	v_mfma_f32_16x16x32_bf16 v[96:99], v[172:175], v[188:191], v[96:99]
	v_mfma_f32_16x16x32_bf16 v[84:87], v[164:167], v[196:199], v[84:87]
	v_mfma_f32_16x16x32_bf16 v[80:83], v[172:175], v[196:199], v[80:83]
	v_mfma_f32_16x16x32_bf16 v[68:71], v[164:167], v[204:207], v[68:71]
	v_mfma_f32_16x16x32_bf16 v[64:67], v[172:175], v[204:207], v[64:67]
	v_mfma_f32_16x16x32_bf16 v[116:119], v[168:171], v[184:187], v[116:119]
	v_mfma_f32_16x16x32_bf16 v[112:115], v[176:179], v[184:187], v[112:115]
	v_mfma_f32_16x16x32_bf16 v[100:103], v[168:171], v[192:195], v[100:103]
	v_mfma_f32_16x16x32_bf16 v[96:99], v[176:179], v[192:195], v[96:99]
	v_mfma_f32_16x16x32_bf16 v[84:87], v[168:171], v[200:203], v[84:87]
	v_mfma_f32_16x16x32_bf16 v[80:83], v[176:179], v[200:203], v[80:83]
	v_mfma_f32_16x16x32_bf16 v[68:71], v[168:171], v[208:211], v[68:71]
	v_mfma_f32_16x16x32_bf16 v[64:67], v[176:179], v[208:211], v[64:67]
	s_setprio 0
	s_barrier
	s_add_i32 s24, s55, s36
	v_lshl_add_u64 v[212:213], v[212:213], 0, s[18:19]
	s_mov_b32 m0, s24
	ds_read_b128 v[180:183], v149 offset:49152
	ds_read_b128 v[184:187], v149 offset:50176
	ds_read_b128 v[188:191], v149 offset:51200
	ds_read_b128 v[192:195], v149 offset:52224
	ds_read_b128 v[196:199], v149 offset:53248
	ds_read_b128 v[200:203], v149 offset:54272
	ds_read_b128 v[204:207], v149 offset:55296
	ds_read_b128 v[208:211], v149 offset:56320
	global_load_lds_dwordx4 v[212:213], off
	s_add_i32 m0, s24, 0x2000
	s_add_u32 s24, s28, 0xb0080
	v_lshl_add_u64 v[212:213], v[214:215], 0, s[18:19]
	s_addc_u32 s25, s29, 0
	s_add_i32 s28, s56, s36
	global_load_lds_dwordx4 v[212:213], off
	v_lshl_add_u64 v[212:213], s[24:25], 0, v[128:129]
	s_mov_b32 m0, s28
	s_nop 0
	global_load_lds_dwordx4 v[212:213], off
	v_lshl_add_u64 v[212:213], s[24:25], 0, v[130:131]
	s_add_i32 m0, s28, 0x2000
	s_nop 0
	global_load_lds_dwordx4 v[212:213], off
	v_lshl_add_u64 v[212:213], v[216:217], 0, s[18:19]
	s_mov_b32 m0, s42
	s_nop 0
	global_load_lds_dwordx4 v[212:213], off
	v_lshl_add_u64 v[212:213], v[218:219], 0, s[18:19]
	s_mov_b32 m0, s43
	s_nop 0
	global_load_lds_dwordx4 v[212:213], off
	s_waitcnt vmcnt(8)
	s_waitcnt lgkmcnt(0)
	s_barrier
	s_setprio 1
	s_waitcnt lgkmcnt(0)
	v_mfma_f32_16x16x32_bf16 v[60:63], v[140:143], v[180:183], v[60:63]
	v_mfma_f32_16x16x32_bf16 v[56:59], v[156:159], v[180:183], v[56:59]
	v_mfma_f32_16x16x32_bf16 v[44:47], v[140:143], v[188:191], v[44:47]
	v_mfma_f32_16x16x32_bf16 v[40:43], v[156:159], v[188:191], v[40:43]
	v_mfma_f32_16x16x32_bf16 v[28:31], v[140:143], v[196:199], v[28:31]
	v_mfma_f32_16x16x32_bf16 v[24:27], v[156:159], v[196:199], v[24:27]
	v_mfma_f32_16x16x32_bf16 v[12:15], v[140:143], v[204:207], v[12:15]
	v_mfma_f32_16x16x32_bf16 v[8:11], v[156:159], v[204:207], v[8:11]
	v_mfma_f32_16x16x32_bf16 v[60:63], v[152:155], v[184:187], v[60:63]
	v_mfma_f32_16x16x32_bf16 v[56:59], v[160:163], v[184:187], v[56:59]
	v_mfma_f32_16x16x32_bf16 v[44:47], v[152:155], v[192:195], v[44:47]
	v_mfma_f32_16x16x32_bf16 v[40:43], v[160:163], v[192:195], v[40:43]
	v_mfma_f32_16x16x32_bf16 v[28:31], v[152:155], v[200:203], v[28:31]
	v_mfma_f32_16x16x32_bf16 v[24:27], v[160:163], v[200:203], v[24:27]
	v_mfma_f32_16x16x32_bf16 v[12:15], v[152:155], v[208:211], v[12:15]
	v_mfma_f32_16x16x32_bf16 v[8:11], v[160:163], v[208:211], v[8:11]
	s_setprio 0
	s_setprio 1
	v_mfma_f32_16x16x32_bf16 v[52:55], v[164:167], v[180:183], v[52:55]
	v_mfma_f32_16x16x32_bf16 v[48:51], v[172:175], v[180:183], v[48:51]
	v_mfma_f32_16x16x32_bf16 v[36:39], v[164:167], v[188:191], v[36:39]
	v_mfma_f32_16x16x32_bf16 v[32:35], v[172:175], v[188:191], v[32:35]
	v_mfma_f32_16x16x32_bf16 v[20:23], v[164:167], v[196:199], v[20:23]
	v_mfma_f32_16x16x32_bf16 v[16:19], v[172:175], v[196:199], v[16:19]
	v_mfma_f32_16x16x32_bf16 v[4:7], v[164:167], v[204:207], v[4:7]
	v_mfma_f32_16x16x32_bf16 v[0:3], v[172:175], v[204:207], v[0:3]
	v_mfma_f32_16x16x32_bf16 v[52:55], v[168:171], v[184:187], v[52:55]
	v_mfma_f32_16x16x32_bf16 v[48:51], v[176:179], v[184:187], v[48:51]
	v_mfma_f32_16x16x32_bf16 v[36:39], v[168:171], v[192:195], v[36:39]
	v_mfma_f32_16x16x32_bf16 v[32:35], v[176:179], v[192:195], v[32:35]
	v_mfma_f32_16x16x32_bf16 v[20:23], v[168:171], v[200:203], v[20:23]
	v_mfma_f32_16x16x32_bf16 v[16:19], v[176:179], v[200:203], v[16:19]
	v_mfma_f32_16x16x32_bf16 v[4:7], v[168:171], v[208:211], v[4:7]
	v_mfma_f32_16x16x32_bf16 v[0:3], v[176:179], v[208:211], v[0:3]
	s_setprio 0
	s_add_i32 s54, s54, 2
	s_add_u32 s52, s52, 0x100
	s_addc_u32 s53, s53, 0
	s_cmp_gt_u32 s54, 41
	s_mov_b64 s[24:25], s[26:27]
	s_barrier
	s_cbranch_scc0 .LBB0_1219
	s_and_b64 vcc, exec, s[20:21]
	s_cbranch_vccz .LBB0_1222
	s_barrier

.LBB0_1337:
	ds_read_b128 v[144:147], v151
	ds_read_b128 v[156:159], v151 offset:1024
	ds_read_b128 v[160:163], v151 offset:2048
	ds_read_b128 v[164:167], v151 offset:3072
	ds_read_b128 v[168:171], v152
	ds_read_b128 v[172:175], v152 offset:1024
	ds_read_b128 v[176:179], v152 offset:2048
	ds_read_b128 v[180:183], v152 offset:3072
	s_add_u32 s26, s24, 0xfffc0080
	s_addc_u32 s27, s25, -1
	s_cmp_eq_u32 s50, 12
	s_cselect_b32 s29, s17, s27
	s_cselect_b32 s28, s23, s26
	s_cselect_b32 s27, s15, s49
	s_cselect_b32 s26, s47, s48
	v_lshl_add_u64 v[216:217], s[24:25], 0, v[136:137]
	s_add_i32 m0, s35, 0xc000
	ds_read_b128 v[184:187], v153
	ds_read_b128 v[188:191], v153 offset:1024
	ds_read_b128 v[192:195], v153 offset:2048
	ds_read_b128 v[196:199], v153 offset:3072
	ds_read_b128 v[200:203], v153 offset:4096
	ds_read_b128 v[204:207], v153 offset:5120
	ds_read_b128 v[208:211], v153 offset:6144
	ds_read_b128 v[212:215], v153 offset:7168
	global_load_lds_dwordx4 v[216:217], off
	v_lshl_add_u64 v[216:217], s[24:25], 0, v[138:139]
	s_add_i32 m0, s35, 0xe000
	s_nop 0
	global_load_lds_dwordx4 v[216:217], off
	s_waitcnt vmcnt(8)
	s_waitcnt lgkmcnt(0)
	s_barrier
	s_setprio 1
	s_waitcnt lgkmcnt(0)
	v_mfma_f32_16x16x32_bf16 v[124:127], v[144:147], v[184:187], v[124:127]
	v_mfma_f32_16x16x32_bf16 v[120:123], v[160:163], v[184:187], v[120:123]
	v_mfma_f32_16x16x32_bf16 v[108:111], v[144:147], v[192:195], v[108:111]
	v_mfma_f32_16x16x32_bf16 v[104:107], v[160:163], v[192:195], v[104:107]
	v_mfma_f32_16x16x32_bf16 v[92:95], v[144:147], v[200:203], v[92:95]
	v_mfma_f32_16x16x32_bf16 v[88:91], v[160:163], v[200:203], v[88:91]
	v_mfma_f32_16x16x32_bf16 v[76:79], v[144:147], v[208:211], v[76:79]
	v_mfma_f32_16x16x32_bf16 v[72:75], v[160:163], v[208:211], v[72:75]
	v_mfma_f32_16x16x32_bf16 v[124:127], v[156:159], v[188:191], v[124:127]
	v_mfma_f32_16x16x32_bf16 v[120:123], v[164:167], v[188:191], v[120:123]
	v_mfma_f32_16x16x32_bf16 v[108:111], v[156:159], v[196:199], v[108:111]
	v_mfma_f32_16x16x32_bf16 v[104:107], v[164:167], v[196:199], v[104:107]
	v_mfma_f32_16x16x32_bf16 v[92:95], v[156:159], v[204:207], v[92:95]
	v_mfma_f32_16x16x32_bf16 v[88:91], v[164:167], v[204:207], v[88:91]
	v_mfma_f32_16x16x32_bf16 v[76:79], v[156:159], v[212:215], v[76:79]
	v_mfma_f32_16x16x32_bf16 v[72:75], v[164:167], v[212:215], v[72:75]
	s_setprio 0
	s_setprio 1
	v_mfma_f32_16x16x32_bf16 v[116:119], v[168:171], v[184:187], v[116:119]
	v_mfma_f32_16x16x32_bf16 v[112:115], v[176:179], v[184:187], v[112:115]
	v_mfma_f32_16x16x32_bf16 v[100:103], v[168:171], v[192:195], v[100:103]
	v_mfma_f32_16x16x32_bf16 v[96:99], v[176:179], v[192:195], v[96:99]
	v_mfma_f32_16x16x32_bf16 v[84:87], v[168:171], v[200:203], v[84:87]
	v_mfma_f32_16x16x32_bf16 v[80:83], v[176:179], v[200:203], v[80:83]
	v_mfma_f32_16x16x32_bf16 v[68:71], v[168:171], v[208:211], v[68:71]
	v_mfma_f32_16x16x32_bf16 v[64:67], v[176:179], v[208:211], v[64:67]
	v_mfma_f32_16x16x32_bf16 v[116:119], v[172:175], v[188:191], v[116:119]
	v_mfma_f32_16x16x32_bf16 v[112:115], v[180:183], v[188:191], v[112:115]
	v_mfma_f32_16x16x32_bf16 v[100:103], v[172:175], v[196:199], v[100:103]
	v_mfma_f32_16x16x32_bf16 v[96:99], v[180:183], v[196:199], v[96:99]
	v_mfma_f32_16x16x32_bf16 v[84:87], v[172:175], v[204:207], v[84:87]
	v_mfma_f32_16x16x32_bf16 v[80:83], v[180:183], v[204:207], v[80:83]
	v_mfma_f32_16x16x32_bf16 v[68:71], v[172:175], v[212:215], v[68:71]
	v_mfma_f32_16x16x32_bf16 v[64:67], v[180:183], v[212:215], v[64:67]
	s_setprio 0
	s_barrier
	s_add_i32 s51, s44, s34
	v_lshl_add_u64 v[216:217], s[26:27], 0, v[130:131]
	s_mov_b32 m0, s51
	ds_read_b128 v[184:187], v153 offset:16384
	ds_read_b128 v[188:191], v153 offset:17408
	ds_read_b128 v[192:195], v153 offset:18432
	ds_read_b128 v[196:199], v153 offset:19456
	ds_read_b128 v[200:203], v153 offset:20480
	ds_read_b128 v[204:207], v153 offset:21504
	ds_read_b128 v[208:211], v153 offset:22528
	ds_read_b128 v[212:215], v153 offset:23552
	global_load_lds_dwordx4 v[216:217], off
	s_add_i32 m0, s51, 0x2000
	s_add_u32 s52, s26, 0x40000
	v_lshl_add_u64 v[218:219], s[26:27], 0, v[134:135]
	s_addc_u32 s53, s27, 0
	s_add_i32 s51, s45, s34
	global_load_lds_dwordx4 v[218:219], off
	v_lshl_add_u64 v[220:221], s[52:53], 0, v[130:131]
	s_mov_b32 m0, s51
	v_lshl_add_u64 v[222:223], s[28:29], 0, v[132:133]
	global_load_lds_dwordx4 v[220:221], off
	v_lshl_add_u64 v[220:221], s[52:53], 0, v[134:135]
	s_add_i32 m0, s51, 0x2000
	s_nop 0
	global_load_lds_dwordx4 v[220:221], off
	v_lshl_add_u64 v[220:221], s[28:29], 0, v[128:129]
	s_mov_b32 m0, s35
	s_nop 0
	global_load_lds_dwordx4 v[220:221], off
	s_mov_b32 m0, s36
	s_nop 0
	global_load_lds_dwordx4 v[222:223], off
	s_waitcnt vmcnt(8)
	s_waitcnt lgkmcnt(0)
	s_barrier
	s_setprio 1
	s_waitcnt lgkmcnt(0)
	v_mfma_f32_16x16x32_bf16 v[60:63], v[144:147], v[184:187], v[60:63]
	v_mfma_f32_16x16x32_bf16 v[56:59], v[160:163], v[184:187], v[56:59]
	v_mfma_f32_16x16x32_bf16 v[44:47], v[144:147], v[192:195], v[44:47]
	v_mfma_f32_16x16x32_bf16 v[40:43], v[160:163], v[192:195], v[40:43]
	v_mfma_f32_16x16x32_bf16 v[28:31], v[144:147], v[200:203], v[28:31]
	v_mfma_f32_16x16x32_bf16 v[24:27], v[160:163], v[200:203], v[24:27]
	v_mfma_f32_16x16x32_bf16 v[12:15], v[144:147], v[208:211], v[12:15]
	v_mfma_f32_16x16x32_bf16 v[8:11], v[160:163], v[208:211], v[8:11]
	v_mfma_f32_16x16x32_bf16 v[60:63], v[156:159], v[188:191], v[60:63]
	v_mfma_f32_16x16x32_bf16 v[56:59], v[164:167], v[188:191], v[56:59]
	v_mfma_f32_16x16x32_bf16 v[44:47], v[156:159], v[196:199], v[44:47]
	v_mfma_f32_16x16x32_bf16 v[40:43], v[164:167], v[196:199], v[40:43]
	v_mfma_f32_16x16x32_bf16 v[28:31], v[156:159], v[204:207], v[28:31]
	v_mfma_f32_16x16x32_bf16 v[24:27], v[164:167], v[204:207], v[24:27]
	v_mfma_f32_16x16x32_bf16 v[12:15], v[156:159], v[212:215], v[12:15]
	v_mfma_f32_16x16x32_bf16 v[8:11], v[164:167], v[212:215], v[8:11]
	s_setprio 0
	s_setprio 1
	v_mfma_f32_16x16x32_bf16 v[52:55], v[168:171], v[184:187], v[52:55]
	v_mfma_f32_16x16x32_bf16 v[48:51], v[176:179], v[184:187], v[48:51]
	v_mfma_f32_16x16x32_bf16 v[36:39], v[168:171], v[192:195], v[36:39]
	v_mfma_f32_16x16x32_bf16 v[32:35], v[176:179], v[192:195], v[32:35]
	v_mfma_f32_16x16x32_bf16 v[20:23], v[168:171], v[200:203], v[20:23]
	v_mfma_f32_16x16x32_bf16 v[16:19], v[176:179], v[200:203], v[16:19]
	v_mfma_f32_16x16x32_bf16 v[4:7], v[168:171], v[208:211], v[4:7]
	v_mfma_f32_16x16x32_bf16 v[0:3], v[176:179], v[208:211], v[0:3]
	v_mfma_f32_16x16x32_bf16 v[52:55], v[172:175], v[188:191], v[52:55]
	v_mfma_f32_16x16x32_bf16 v[48:51], v[180:183], v[188:191], v[48:51]
	v_mfma_f32_16x16x32_bf16 v[36:39], v[172:175], v[196:199], v[36:39]
	v_mfma_f32_16x16x32_bf16 v[32:35], v[180:183], v[196:199], v[32:35]
	v_mfma_f32_16x16x32_bf16 v[20:23], v[172:175], v[204:207], v[20:23]
	v_mfma_f32_16x16x32_bf16 v[16:19], v[180:183], v[204:207], v[16:19]
	v_mfma_f32_16x16x32_bf16 v[4:7], v[172:175], v[212:215], v[4:7]
	v_mfma_f32_16x16x32_bf16 v[0:3], v[180:183], v[212:215], v[0:3]
	s_setprio 0
	s_barrier
	s_add_i32 s51, 0, 0x18000
	s_add_i32 s52, 0, 0x1c000
	v_add_u32_e32 v164, s51, v149
	v_add_u32_e32 v180, s52, v149
	ds_read_b128 v[144:147], v164
	ds_read_b128 v[156:159], v164 offset:1024
	ds_read_b128 v[160:163], v164 offset:2048
	ds_read_b128 v[164:167], v164 offset:3072
	ds_read_b128 v[168:171], v180
	ds_read_b128 v[172:175], v180 offset:1024
	ds_read_b128 v[176:179], v180 offset:2048
	ds_read_b128 v[180:183], v180 offset:3072
	s_add_u32 s28, s28, 0x40000
	s_addc_u32 s29, s29, 0
	s_mov_b32 m0, s37
	v_lshl_add_u64 v[224:225], s[28:29], 0, v[128:129]
	ds_read_b128 v[184:187], v153 offset:32768
	ds_read_b128 v[188:191], v153 offset:33792
	ds_read_b128 v[192:195], v153 offset:34816
	ds_read_b128 v[196:199], v153 offset:35840
	ds_read_b128 v[200:203], v153 offset:36864
	ds_read_b128 v[204:207], v153 offset:37888
	ds_read_b128 v[208:211], v153 offset:38912
	ds_read_b128 v[212:215], v153 offset:39936
	global_load_lds_dwordx4 v[224:225], off
	v_lshl_add_u64 v[224:225], s[28:29], 0, v[132:133]
	s_mov_b32 m0, s38
	s_nop 0
	global_load_lds_dwordx4 v[224:225], off
	s_waitcnt vmcnt(8)
	s_waitcnt lgkmcnt(0)
	s_barrier
	s_setprio 1
	s_waitcnt lgkmcnt(0)
	v_mfma_f32_16x16x32_bf16 v[124:127], v[144:147], v[184:187], v[124:127]
	v_mfma_f32_16x16x32_bf16 v[120:123], v[160:163], v[184:187], v[120:123]
	v_mfma_f32_16x16x32_bf16 v[108:111], v[144:147], v[192:195], v[108:111]
	v_mfma_f32_16x16x32_bf16 v[104:107], v[160:163], v[192:195], v[104:107]
	v_mfma_f32_16x16x32_bf16 v[92:95], v[144:147], v[200:203], v[92:95]
	v_mfma_f32_16x16x32_bf16 v[88:91], v[160:163], v[200:203], v[88:91]
	v_mfma_f32_16x16x32_bf16 v[76:79], v[144:147], v[208:211], v[76:79]
	v_mfma_f32_16x16x32_bf16 v[72:75], v[160:163], v[208:211], v[72:75]
	v_mfma_f32_16x16x32_bf16 v[124:127], v[156:159], v[188:191], v[124:127]
	v_mfma_f32_16x16x32_bf16 v[120:123], v[164:167], v[188:191], v[120:123]
	v_mfma_f32_16x16x32_bf16 v[108:111], v[156:159], v[196:199], v[108:111]
	v_mfma_f32_16x16x32_bf16 v[104:107], v[164:167], v[196:199], v[104:107]
	v_mfma_f32_16x16x32_bf16 v[92:95], v[156:159], v[204:207], v[92:95]
	v_mfma_f32_16x16x32_bf16 v[88:91], v[164:167], v[204:207], v[88:91]
	v_mfma_f32_16x16x32_bf16 v[76:79], v[156:159], v[212:215], v[76:79]
	v_mfma_f32_16x16x32_bf16 v[72:75], v[164:167], v[212:215], v[72:75]
	s_setprio 0
	s_setprio 1
	v_mfma_f32_16x16x32_bf16 v[116:119], v[168:171], v[184:187], v[116:119]
	v_mfma_f32_16x16x32_bf16 v[112:115], v[176:179], v[184:187], v[112:115]
	v_mfma_f32_16x16x32_bf16 v[100:103], v[168:171], v[192:195], v[100:103]
	v_mfma_f32_16x16x32_bf16 v[96:99], v[176:179], v[192:195], v[96:99]
	v_mfma_f32_16x16x32_bf16 v[84:87], v[168:171], v[200:203], v[84:87]
	v_mfma_f32_16x16x32_bf16 v[80:83], v[176:179], v[200:203], v[80:83]
	v_mfma_f32_16x16x32_bf16 v[68:71], v[168:171], v[208:211], v[68:71]
	v_mfma_f32_16x16x32_bf16 v[64:67], v[176:179], v[208:211], v[64:67]
	v_mfma_f32_16x16x32_bf16 v[116:119], v[172:175], v[188:191], v[116:119]
	v_mfma_f32_16x16x32_bf16 v[112:115], v[180:183], v[188:191], v[112:115]
	v_mfma_f32_16x16x32_bf16 v[100:103], v[172:175], v[196:199], v[100:103]
	v_mfma_f32_16x16x32_bf16 v[96:99], v[180:183], v[196:199], v[96:99]
	v_mfma_f32_16x16x32_bf16 v[84:87], v[172:175], v[204:207], v[84:87]
	v_mfma_f32_16x16x32_bf16 v[80:83], v[180:183], v[204:207], v[80:83]
	v_mfma_f32_16x16x32_bf16 v[68:71], v[172:175], v[212:215], v[68:71]
	v_mfma_f32_16x16x32_bf16 v[64:67], v[180:183], v[212:215], v[64:67]
	s_setprio 0
	s_barrier
	s_add_i32 s28, s51, s34
	v_lshl_add_u64 v[216:217], v[216:217], 0, s[10:11]
	s_mov_b32 m0, s28
	ds_read_b128 v[184:187], v153 offset:49152
	ds_read_b128 v[188:191], v153 offset:50176
	ds_read_b128 v[192:195], v153 offset:51200
	ds_read_b128 v[196:199], v153 offset:52224
	ds_read_b128 v[200:203], v153 offset:53248
	ds_read_b128 v[204:207], v153 offset:54272
	ds_read_b128 v[208:211], v153 offset:55296
	ds_read_b128 v[212:215], v153 offset:56320
	global_load_lds_dwordx4 v[216:217], off
	s_add_i32 m0, s28, 0x2000
	s_add_u32 s26, s26, 0x40080
	v_lshl_add_u64 v[216:217], v[218:219], 0, s[10:11]
	s_addc_u32 s27, s27, 0
	s_add_i32 s28, s52, s34
	global_load_lds_dwordx4 v[216:217], off
	v_lshl_add_u64 v[216:217], s[26:27], 0, v[130:131]
	s_mov_b32 m0, s28
	s_nop 0
	global_load_lds_dwordx4 v[216:217], off
	v_lshl_add_u64 v[216:217], s[26:27], 0, v[134:135]
	s_add_i32 m0, s28, 0x2000
	s_nop 0
	global_load_lds_dwordx4 v[216:217], off
	v_lshl_add_u64 v[216:217], v[220:221], 0, s[10:11]
	s_mov_b32 m0, s40
	s_nop 0
	global_load_lds_dwordx4 v[216:217], off
	v_lshl_add_u64 v[216:217], v[222:223], 0, s[10:11]
	s_mov_b32 m0, s41
	s_nop 0
	global_load_lds_dwordx4 v[216:217], off
	s_waitcnt vmcnt(8)
	s_waitcnt lgkmcnt(0)
	s_barrier
	s_setprio 1
	s_waitcnt lgkmcnt(0)
	v_mfma_f32_16x16x32_bf16 v[60:63], v[144:147], v[184:187], v[60:63]
	v_mfma_f32_16x16x32_bf16 v[56:59], v[160:163], v[184:187], v[56:59]
	v_mfma_f32_16x16x32_bf16 v[44:47], v[144:147], v[192:195], v[44:47]
	v_mfma_f32_16x16x32_bf16 v[40:43], v[160:163], v[192:195], v[40:43]
	v_mfma_f32_16x16x32_bf16 v[28:31], v[144:147], v[200:203], v[28:31]
	v_mfma_f32_16x16x32_bf16 v[24:27], v[160:163], v[200:203], v[24:27]
	v_mfma_f32_16x16x32_bf16 v[12:15], v[144:147], v[208:211], v[12:15]
	v_mfma_f32_16x16x32_bf16 v[8:11], v[160:163], v[208:211], v[8:11]
	v_mfma_f32_16x16x32_bf16 v[60:63], v[156:159], v[188:191], v[60:63]
	v_mfma_f32_16x16x32_bf16 v[56:59], v[164:167], v[188:191], v[56:59]
	v_mfma_f32_16x16x32_bf16 v[44:47], v[156:159], v[196:199], v[44:47]
	v_mfma_f32_16x16x32_bf16 v[40:43], v[164:167], v[196:199], v[40:43]
	v_mfma_f32_16x16x32_bf16 v[28:31], v[156:159], v[204:207], v[28:31]
	v_mfma_f32_16x16x32_bf16 v[24:27], v[164:167], v[204:207], v[24:27]
	v_mfma_f32_16x16x32_bf16 v[12:15], v[156:159], v[212:215], v[12:15]
	v_mfma_f32_16x16x32_bf16 v[8:11], v[164:167], v[212:215], v[8:11]
	s_setprio 0
	s_setprio 1
	v_mfma_f32_16x16x32_bf16 v[52:55], v[168:171], v[184:187], v[52:55]
	v_mfma_f32_16x16x32_bf16 v[48:51], v[176:179], v[184:187], v[48:51]
	v_mfma_f32_16x16x32_bf16 v[36:39], v[168:171], v[192:195], v[36:39]
	v_mfma_f32_16x16x32_bf16 v[32:35], v[176:179], v[192:195], v[32:35]
	v_mfma_f32_16x16x32_bf16 v[20:23], v[168:171], v[200:203], v[20:23]
	v_mfma_f32_16x16x32_bf16 v[16:19], v[176:179], v[200:203], v[16:19]
	v_mfma_f32_16x16x32_bf16 v[4:7], v[168:171], v[208:211], v[4:7]
	v_mfma_f32_16x16x32_bf16 v[0:3], v[176:179], v[208:211], v[0:3]
	v_mfma_f32_16x16x32_bf16 v[52:55], v[172:175], v[188:191], v[52:55]
	v_mfma_f32_16x16x32_bf16 v[48:51], v[180:183], v[188:191], v[48:51]
	v_mfma_f32_16x16x32_bf16 v[36:39], v[172:175], v[196:199], v[36:39]
	v_mfma_f32_16x16x32_bf16 v[32:35], v[180:183], v[196:199], v[32:35]
	v_mfma_f32_16x16x32_bf16 v[20:23], v[172:175], v[204:207], v[20:23]
	v_mfma_f32_16x16x32_bf16 v[16:19], v[180:183], v[204:207], v[16:19]
	v_mfma_f32_16x16x32_bf16 v[4:7], v[172:175], v[212:215], v[4:7]
	v_mfma_f32_16x16x32_bf16 v[0:3], v[180:183], v[212:215], v[0:3]
	s_setprio 0
	s_add_i32 s50, s50, 2
	s_add_u32 s24, s24, 0x100
	s_addc_u32 s25, s25, 0
	s_add_u32 s48, s48, 0x100
	s_addc_u32 s49, s49, 0
	s_cmp_gt_u32 s50, 13
	s_barrier
	s_cbranch_scc0 .LBB0_1337
	s_and_b64 vcc, exec, s[12:13]
	s_cbranch_vccz .LBB0_1340
	s_barrier

.LBB0_1403:
	ds_read_b128 v[128:131], v164
	ds_read_b128 v[160:163], v164 offset:1024
	ds_read_b128 v[168:171], v164 offset:2048
	ds_read_b128 v[172:175], v164 offset:3072
	ds_read_b128 v[176:179], v165
	ds_read_b128 v[180:183], v165 offset:1024
	ds_read_b128 v[184:187], v165 offset:2048
	ds_read_b128 v[188:191], v165 offset:3072
	s_add_u32 s30, s28, 0xfffe0080
	s_addc_u32 s31, s29, -1
	s_cmp_eq_u32 s56, 4
	s_cselect_b32 s35, s5, s31
	s_cselect_b32 s34, s23, s30
	s_cselect_b32 s31, s21, s55
	s_cselect_b32 s30, s53, s54
	v_lshl_add_u64 v[156:157], s[28:29], 0, v[148:149]
	s_add_i32 m0, s39, 0xc000
	ds_read_b128 v[192:195], v166
	ds_read_b128 v[196:199], v166 offset:1024
	ds_read_b128 v[200:203], v166 offset:2048
	ds_read_b128 v[204:207], v166 offset:3072
	ds_read_b128 v[208:211], v166 offset:4096
	ds_read_b128 v[212:215], v166 offset:5120
	ds_read_b128 v[216:219], v166 offset:6144
	ds_read_b128 v[220:223], v166 offset:7168
	global_load_lds_dwordx4 v[156:157], off
	v_lshl_add_u64 v[156:157], s[28:29], 0, v[150:151]
	s_add_i32 m0, s39, 0xe000
	s_nop 0
	global_load_lds_dwordx4 v[156:157], off
	s_waitcnt vmcnt(8)
	s_waitcnt lgkmcnt(0)
	s_barrier
	s_setprio 1
	s_waitcnt lgkmcnt(0)
	v_mfma_f32_16x16x32_bf16 v[124:127], v[128:131], v[192:195], v[124:127]
	v_mfma_f32_16x16x32_bf16 v[120:123], v[168:171], v[192:195], v[120:123]
	v_mfma_f32_16x16x32_bf16 v[108:111], v[128:131], v[200:203], v[108:111]
	v_mfma_f32_16x16x32_bf16 v[104:107], v[168:171], v[200:203], v[104:107]
	v_mfma_f32_16x16x32_bf16 v[92:95], v[128:131], v[208:211], v[92:95]
	v_mfma_f32_16x16x32_bf16 v[88:91], v[168:171], v[208:211], v[88:91]
	v_mfma_f32_16x16x32_bf16 v[76:79], v[128:131], v[216:219], v[76:79]
	v_mfma_f32_16x16x32_bf16 v[72:75], v[168:171], v[216:219], v[72:75]
	v_mfma_f32_16x16x32_bf16 v[124:127], v[160:163], v[196:199], v[124:127]
	v_mfma_f32_16x16x32_bf16 v[120:123], v[172:175], v[196:199], v[120:123]
	v_mfma_f32_16x16x32_bf16 v[108:111], v[160:163], v[204:207], v[108:111]
	v_mfma_f32_16x16x32_bf16 v[104:107], v[172:175], v[204:207], v[104:107]
	v_mfma_f32_16x16x32_bf16 v[92:95], v[160:163], v[212:215], v[92:95]
	v_mfma_f32_16x16x32_bf16 v[88:91], v[172:175], v[212:215], v[88:91]
	v_mfma_f32_16x16x32_bf16 v[76:79], v[160:163], v[220:223], v[76:79]
	v_mfma_f32_16x16x32_bf16 v[72:75], v[172:175], v[220:223], v[72:75]
	s_setprio 0
	s_setprio 1
	v_mfma_f32_16x16x32_bf16 v[116:119], v[176:179], v[192:195], v[116:119]
	v_mfma_f32_16x16x32_bf16 v[112:115], v[184:187], v[192:195], v[112:115]
	v_mfma_f32_16x16x32_bf16 v[100:103], v[176:179], v[200:203], v[100:103]
	v_mfma_f32_16x16x32_bf16 v[96:99], v[184:187], v[200:203], v[96:99]
	v_mfma_f32_16x16x32_bf16 v[84:87], v[176:179], v[208:211], v[84:87]
	v_mfma_f32_16x16x32_bf16 v[80:83], v[184:187], v[208:211], v[80:83]
	v_mfma_f32_16x16x32_bf16 v[68:71], v[176:179], v[216:219], v[68:71]
	v_mfma_f32_16x16x32_bf16 v[64:67], v[184:187], v[216:219], v[64:67]
	v_mfma_f32_16x16x32_bf16 v[116:119], v[180:183], v[196:199], v[116:119]
	v_mfma_f32_16x16x32_bf16 v[112:115], v[188:191], v[196:199], v[112:115]
	v_mfma_f32_16x16x32_bf16 v[100:103], v[180:183], v[204:207], v[100:103]
	v_mfma_f32_16x16x32_bf16 v[96:99], v[188:191], v[204:207], v[96:99]
	v_mfma_f32_16x16x32_bf16 v[84:87], v[180:183], v[212:215], v[84:87]
	v_mfma_f32_16x16x32_bf16 v[80:83], v[188:191], v[212:215], v[80:83]
	v_mfma_f32_16x16x32_bf16 v[68:71], v[180:183], v[220:223], v[68:71]
	v_mfma_f32_16x16x32_bf16 v[64:67], v[188:191], v[220:223], v[64:67]
	s_setprio 0
	s_barrier
	s_add_i32 s57, s50, s38
	v_lshl_add_u64 v[156:157], s[30:31], 0, v[134:135]
	s_mov_b32 m0, s57
	ds_read_b128 v[192:195], v166 offset:16384
	ds_read_b128 v[196:199], v166 offset:17408
	ds_read_b128 v[200:203], v166 offset:18432
	ds_read_b128 v[204:207], v166 offset:19456
	ds_read_b128 v[208:211], v166 offset:20480
	ds_read_b128 v[212:215], v166 offset:21504
	ds_read_b128 v[216:219], v166 offset:22528
	ds_read_b128 v[220:223], v166 offset:23552
	global_load_lds_dwordx4 v[156:157], off
	s_add_i32 m0, s57, 0x2000
	s_add_u32 s58, s30, 0x20000
	v_lshl_add_u64 v[224:225], s[30:31], 0, v[138:139]
	s_addc_u32 s59, s31, 0
	s_add_i32 s57, s51, s38
	global_load_lds_dwordx4 v[224:225], off
	v_lshl_add_u64 v[226:227], s[58:59], 0, v[134:135]
	s_mov_b32 m0, s57
	v_lshl_add_u64 v[228:229], s[34:35], 0, v[136:137]
	global_load_lds_dwordx4 v[226:227], off
	v_lshl_add_u64 v[226:227], s[58:59], 0, v[138:139]
	s_add_i32 m0, s57, 0x2000
	s_nop 0
	global_load_lds_dwordx4 v[226:227], off
	v_lshl_add_u64 v[226:227], s[34:35], 0, v[132:133]
	s_mov_b32 m0, s39
	s_nop 0
	global_load_lds_dwordx4 v[226:227], off
	s_mov_b32 m0, s40
	s_nop 0
	global_load_lds_dwordx4 v[228:229], off
	s_waitcnt vmcnt(8)
	s_waitcnt lgkmcnt(0)
	s_barrier
	s_setprio 1
	s_waitcnt lgkmcnt(0)
	v_mfma_f32_16x16x32_bf16 v[60:63], v[128:131], v[192:195], v[60:63]
	v_mfma_f32_16x16x32_bf16 v[56:59], v[168:171], v[192:195], v[56:59]
	v_mfma_f32_16x16x32_bf16 v[44:47], v[128:131], v[200:203], v[44:47]
	v_mfma_f32_16x16x32_bf16 v[40:43], v[168:171], v[200:203], v[40:43]
	v_mfma_f32_16x16x32_bf16 v[28:31], v[128:131], v[208:211], v[28:31]
	v_mfma_f32_16x16x32_bf16 v[24:27], v[168:171], v[208:211], v[24:27]
	v_mfma_f32_16x16x32_bf16 v[12:15], v[128:131], v[216:219], v[12:15]
	v_mfma_f32_16x16x32_bf16 v[8:11], v[168:171], v[216:219], v[8:11]
	v_mfma_f32_16x16x32_bf16 v[60:63], v[160:163], v[196:199], v[60:63]
	v_mfma_f32_16x16x32_bf16 v[56:59], v[172:175], v[196:199], v[56:59]
	v_mfma_f32_16x16x32_bf16 v[44:47], v[160:163], v[204:207], v[44:47]
	v_mfma_f32_16x16x32_bf16 v[40:43], v[172:175], v[204:207], v[40:43]
	v_mfma_f32_16x16x32_bf16 v[28:31], v[160:163], v[212:215], v[28:31]
	v_mfma_f32_16x16x32_bf16 v[24:27], v[172:175], v[212:215], v[24:27]
	v_mfma_f32_16x16x32_bf16 v[12:15], v[160:163], v[220:223], v[12:15]
	v_mfma_f32_16x16x32_bf16 v[8:11], v[172:175], v[220:223], v[8:11]
	s_setprio 0
	s_setprio 1
	v_mfma_f32_16x16x32_bf16 v[52:55], v[176:179], v[192:195], v[52:55]
	v_mfma_f32_16x16x32_bf16 v[48:51], v[184:187], v[192:195], v[48:51]
	v_mfma_f32_16x16x32_bf16 v[36:39], v[176:179], v[200:203], v[36:39]
	v_mfma_f32_16x16x32_bf16 v[32:35], v[184:187], v[200:203], v[32:35]
	v_mfma_f32_16x16x32_bf16 v[20:23], v[176:179], v[208:211], v[20:23]
	v_mfma_f32_16x16x32_bf16 v[16:19], v[184:187], v[208:211], v[16:19]
	v_mfma_f32_16x16x32_bf16 v[4:7], v[176:179], v[216:219], v[4:7]
	v_mfma_f32_16x16x32_bf16 v[0:3], v[184:187], v[216:219], v[0:3]
	v_mfma_f32_16x16x32_bf16 v[52:55], v[180:183], v[196:199], v[52:55]
	v_mfma_f32_16x16x32_bf16 v[48:51], v[188:191], v[196:199], v[48:51]
	v_mfma_f32_16x16x32_bf16 v[36:39], v[180:183], v[204:207], v[36:39]
	v_mfma_f32_16x16x32_bf16 v[32:35], v[188:191], v[204:207], v[32:35]
	v_mfma_f32_16x16x32_bf16 v[20:23], v[180:183], v[212:215], v[20:23]
	v_mfma_f32_16x16x32_bf16 v[16:19], v[188:191], v[212:215], v[16:19]
	v_mfma_f32_16x16x32_bf16 v[4:7], v[180:183], v[220:223], v[4:7]
	v_mfma_f32_16x16x32_bf16 v[0:3], v[188:191], v[220:223], v[0:3]
	s_setprio 0
	s_barrier
	s_add_i32 s57, 0, 0x18000
	v_add_u32_e32 v140, s57, v159
	s_add_i32 s58, 0, 0x1c000
	ds_read_b128 v[128:131], v140
	ds_read_b128 v[160:163], v140 offset:1024
	ds_read_b128 v[168:171], v140 offset:2048
	ds_read_b128 v[172:175], v140 offset:3072
	v_add_u32_e32 v140, s58, v159
	ds_read_b128 v[176:179], v140
	ds_read_b128 v[180:183], v140 offset:1024
	ds_read_b128 v[184:187], v140 offset:2048
	ds_read_b128 v[188:191], v140 offset:3072
	s_add_u32 s34, s34, 0x20000
	s_addc_u32 s35, s35, 0
	s_mov_b32 m0, s41
	v_lshl_add_u64 v[230:231], s[34:35], 0, v[132:133]
	ds_read_b128 v[192:195], v166 offset:32768
	ds_read_b128 v[196:199], v166 offset:33792
	ds_read_b128 v[200:203], v166 offset:34816
	ds_read_b128 v[204:207], v166 offset:35840
	ds_read_b128 v[208:211], v166 offset:36864
	ds_read_b128 v[212:215], v166 offset:37888
	ds_read_b128 v[216:219], v166 offset:38912
	ds_read_b128 v[220:223], v166 offset:39936
	global_load_lds_dwordx4 v[230:231], off
	v_lshl_add_u64 v[230:231], s[34:35], 0, v[136:137]
	s_mov_b32 m0, s42
	s_nop 0
	global_load_lds_dwordx4 v[230:231], off
	s_waitcnt vmcnt(8)
	s_waitcnt lgkmcnt(0)
	s_barrier
	s_setprio 1
	s_waitcnt lgkmcnt(0)
	v_mfma_f32_16x16x32_bf16 v[124:127], v[128:131], v[192:195], v[124:127]
	v_mfma_f32_16x16x32_bf16 v[120:123], v[168:171], v[192:195], v[120:123]
	v_mfma_f32_16x16x32_bf16 v[108:111], v[128:131], v[200:203], v[108:111]
	v_mfma_f32_16x16x32_bf16 v[104:107], v[168:171], v[200:203], v[104:107]
	v_mfma_f32_16x16x32_bf16 v[92:95], v[128:131], v[208:211], v[92:95]
	v_mfma_f32_16x16x32_bf16 v[88:91], v[168:171], v[208:211], v[88:91]
	v_mfma_f32_16x16x32_bf16 v[76:79], v[128:131], v[216:219], v[76:79]
	v_mfma_f32_16x16x32_bf16 v[72:75], v[168:171], v[216:219], v[72:75]
	v_mfma_f32_16x16x32_bf16 v[124:127], v[160:163], v[196:199], v[124:127]
	v_mfma_f32_16x16x32_bf16 v[120:123], v[172:175], v[196:199], v[120:123]
	v_mfma_f32_16x16x32_bf16 v[108:111], v[160:163], v[204:207], v[108:111]
	v_mfma_f32_16x16x32_bf16 v[104:107], v[172:175], v[204:207], v[104:107]
	v_mfma_f32_16x16x32_bf16 v[92:95], v[160:163], v[212:215], v[92:95]
	v_mfma_f32_16x16x32_bf16 v[88:91], v[172:175], v[212:215], v[88:91]
	v_mfma_f32_16x16x32_bf16 v[76:79], v[160:163], v[220:223], v[76:79]
	v_mfma_f32_16x16x32_bf16 v[72:75], v[172:175], v[220:223], v[72:75]
	s_setprio 0
	s_setprio 1
	v_mfma_f32_16x16x32_bf16 v[116:119], v[176:179], v[192:195], v[116:119]
	v_mfma_f32_16x16x32_bf16 v[112:115], v[184:187], v[192:195], v[112:115]
	v_mfma_f32_16x16x32_bf16 v[100:103], v[176:179], v[200:203], v[100:103]
	v_mfma_f32_16x16x32_bf16 v[96:99], v[184:187], v[200:203], v[96:99]
	v_mfma_f32_16x16x32_bf16 v[84:87], v[176:179], v[208:211], v[84:87]
	v_mfma_f32_16x16x32_bf16 v[80:83], v[184:187], v[208:211], v[80:83]
	v_mfma_f32_16x16x32_bf16 v[68:71], v[176:179], v[216:219], v[68:71]
	v_mfma_f32_16x16x32_bf16 v[64:67], v[184:187], v[216:219], v[64:67]
	v_mfma_f32_16x16x32_bf16 v[116:119], v[180:183], v[196:199], v[116:119]
	v_mfma_f32_16x16x32_bf16 v[112:115], v[188:191], v[196:199], v[112:115]
	v_mfma_f32_16x16x32_bf16 v[100:103], v[180:183], v[204:207], v[100:103]
	v_mfma_f32_16x16x32_bf16 v[96:99], v[188:191], v[204:207], v[96:99]
	v_mfma_f32_16x16x32_bf16 v[84:87], v[180:183], v[212:215], v[84:87]
	v_mfma_f32_16x16x32_bf16 v[80:83], v[188:191], v[212:215], v[80:83]
	v_mfma_f32_16x16x32_bf16 v[68:71], v[180:183], v[220:223], v[68:71]
	v_mfma_f32_16x16x32_bf16 v[64:67], v[188:191], v[220:223], v[64:67]
	s_setprio 0
	s_barrier
	s_add_i32 s34, s57, s38
	v_lshl_add_u64 v[156:157], v[156:157], 0, s[14:15]
	s_mov_b32 m0, s34
	ds_read_b128 v[192:195], v166 offset:49152
	ds_read_b128 v[196:199], v166 offset:50176
	ds_read_b128 v[200:203], v166 offset:51200
	ds_read_b128 v[204:207], v166 offset:52224
	ds_read_b128 v[208:211], v166 offset:53248
	ds_read_b128 v[212:215], v166 offset:54272
	ds_read_b128 v[216:219], v166 offset:55296
	ds_read_b128 v[220:223], v166 offset:56320
	global_load_lds_dwordx4 v[156:157], off
	s_add_i32 m0, s34, 0x2000
	s_add_u32 s30, s30, 0x20080
	v_lshl_add_u64 v[156:157], v[224:225], 0, s[14:15]
	s_addc_u32 s31, s31, 0
	s_add_i32 s34, s58, s38
	global_load_lds_dwordx4 v[156:157], off
	v_lshl_add_u64 v[156:157], s[30:31], 0, v[134:135]
	s_mov_b32 m0, s34
	s_nop 0
	global_load_lds_dwordx4 v[156:157], off
	v_lshl_add_u64 v[156:157], s[30:31], 0, v[138:139]
	s_add_i32 m0, s34, 0x2000
	s_nop 0
	global_load_lds_dwordx4 v[156:157], off
	v_lshl_add_u64 v[156:157], v[226:227], 0, s[14:15]
	s_mov_b32 m0, s44
	s_nop 0
	global_load_lds_dwordx4 v[156:157], off
	v_lshl_add_u64 v[156:157], v[228:229], 0, s[14:15]
	s_mov_b32 m0, s45
	s_nop 0
	global_load_lds_dwordx4 v[156:157], off
	s_waitcnt vmcnt(8)
	s_waitcnt lgkmcnt(0)
	s_barrier
	s_setprio 1
	s_waitcnt lgkmcnt(0)
	v_mfma_f32_16x16x32_bf16 v[60:63], v[128:131], v[192:195], v[60:63]
	v_mfma_f32_16x16x32_bf16 v[56:59], v[168:171], v[192:195], v[56:59]
	v_mfma_f32_16x16x32_bf16 v[44:47], v[128:131], v[200:203], v[44:47]
	v_mfma_f32_16x16x32_bf16 v[40:43], v[168:171], v[200:203], v[40:43]
	v_mfma_f32_16x16x32_bf16 v[28:31], v[128:131], v[208:211], v[28:31]
	v_mfma_f32_16x16x32_bf16 v[24:27], v[168:171], v[208:211], v[24:27]
	v_mfma_f32_16x16x32_bf16 v[12:15], v[128:131], v[216:219], v[12:15]
	v_mfma_f32_16x16x32_bf16 v[8:11], v[168:171], v[216:219], v[8:11]
	v_mfma_f32_16x16x32_bf16 v[60:63], v[160:163], v[196:199], v[60:63]
	v_mfma_f32_16x16x32_bf16 v[56:59], v[172:175], v[196:199], v[56:59]
	v_mfma_f32_16x16x32_bf16 v[44:47], v[160:163], v[204:207], v[44:47]
	v_mfma_f32_16x16x32_bf16 v[40:43], v[172:175], v[204:207], v[40:43]
	v_mfma_f32_16x16x32_bf16 v[28:31], v[160:163], v[212:215], v[28:31]
	v_mfma_f32_16x16x32_bf16 v[24:27], v[172:175], v[212:215], v[24:27]
	v_mfma_f32_16x16x32_bf16 v[12:15], v[160:163], v[220:223], v[12:15]
	v_mfma_f32_16x16x32_bf16 v[8:11], v[172:175], v[220:223], v[8:11]
	s_setprio 0
	s_setprio 1
	v_mfma_f32_16x16x32_bf16 v[52:55], v[176:179], v[192:195], v[52:55]
	v_mfma_f32_16x16x32_bf16 v[48:51], v[184:187], v[192:195], v[48:51]
	v_mfma_f32_16x16x32_bf16 v[36:39], v[176:179], v[200:203], v[36:39]
	v_mfma_f32_16x16x32_bf16 v[32:35], v[184:187], v[200:203], v[32:35]
	v_mfma_f32_16x16x32_bf16 v[20:23], v[176:179], v[208:211], v[20:23]
	v_mfma_f32_16x16x32_bf16 v[16:19], v[184:187], v[208:211], v[16:19]
	v_mfma_f32_16x16x32_bf16 v[4:7], v[176:179], v[216:219], v[4:7]
	v_mfma_f32_16x16x32_bf16 v[0:3], v[184:187], v[216:219], v[0:3]
	v_mfma_f32_16x16x32_bf16 v[52:55], v[180:183], v[196:199], v[52:55]
	v_mfma_f32_16x16x32_bf16 v[48:51], v[188:191], v[196:199], v[48:51]
	v_mfma_f32_16x16x32_bf16 v[36:39], v[180:183], v[204:207], v[36:39]
	v_mfma_f32_16x16x32_bf16 v[32:35], v[188:191], v[204:207], v[32:35]
	v_mfma_f32_16x16x32_bf16 v[20:23], v[180:183], v[212:215], v[20:23]
	v_mfma_f32_16x16x32_bf16 v[16:19], v[188:191], v[212:215], v[16:19]
	v_mfma_f32_16x16x32_bf16 v[4:7], v[180:183], v[220:223], v[4:7]
	v_mfma_f32_16x16x32_bf16 v[0:3], v[188:191], v[220:223], v[0:3]
	s_setprio 0
	s_add_i32 s56, s56, 2
	s_add_u32 s28, s28, 0x100
	s_addc_u32 s29, s29, 0
	s_add_u32 s54, s54, 0x100
	s_addc_u32 s55, s55, 0
	s_cmp_gt_u32 s56, 5
	s_barrier
	s_cbranch_scc0 .LBB0_1403
	s_and_b64 vcc, exec, s[16:17]
	s_cbranch_vccz .LBB0_1406
	s_barrier

.LBB0_1553:
	ds_read_b128 v[140:143], v147
	ds_read_b128 v[152:155], v147 offset:1024
	ds_read_b128 v[156:159], v147 offset:2048
	ds_read_b128 v[160:163], v147 offset:3072
	ds_read_b128 v[164:167], v148
	ds_read_b128 v[168:171], v148 offset:1024
	ds_read_b128 v[172:175], v148 offset:2048
	ds_read_b128 v[176:179], v148 offset:3072
	s_add_u32 s28, s26, 0xfffc0080
	s_addc_u32 s29, s27, -1
	s_cmp_eq_u32 s54, 12
	s_cselect_b32 s31, s19, s29
	s_cselect_b32 s30, s25, s28
	s_cselect_b32 s29, s17, s53
	s_cselect_b32 s28, s51, s52
	v_lshl_add_u64 v[212:213], s[26:27], 0, v[132:133]
	s_add_i32 m0, s39, 0xc000
	ds_read_b128 v[180:183], v149
	ds_read_b128 v[184:187], v149 offset:1024
	ds_read_b128 v[188:191], v149 offset:2048
	ds_read_b128 v[192:195], v149 offset:3072
	ds_read_b128 v[196:199], v149 offset:4096
	ds_read_b128 v[200:203], v149 offset:5120
	ds_read_b128 v[204:207], v149 offset:6144
	ds_read_b128 v[208:211], v149 offset:7168
	global_load_lds_dwordx4 v[212:213], off
	v_lshl_add_u64 v[212:213], s[26:27], 0, v[134:135]
	s_add_i32 m0, s39, 0xe000
	s_nop 0
	global_load_lds_dwordx4 v[212:213], off
	s_waitcnt vmcnt(8)
	s_waitcnt lgkmcnt(0)
	s_barrier
	s_setprio 1
	s_waitcnt lgkmcnt(0)
	v_mfma_f32_16x16x32_bf16 v[124:127], v[140:143], v[180:183], v[124:127]
	v_mfma_f32_16x16x32_bf16 v[120:123], v[156:159], v[180:183], v[120:123]
	v_mfma_f32_16x16x32_bf16 v[108:111], v[140:143], v[188:191], v[108:111]
	v_mfma_f32_16x16x32_bf16 v[104:107], v[156:159], v[188:191], v[104:107]
	v_mfma_f32_16x16x32_bf16 v[92:95], v[140:143], v[196:199], v[92:95]
	v_mfma_f32_16x16x32_bf16 v[88:91], v[156:159], v[196:199], v[88:91]
	v_mfma_f32_16x16x32_bf16 v[76:79], v[140:143], v[204:207], v[76:79]
	v_mfma_f32_16x16x32_bf16 v[72:75], v[156:159], v[204:207], v[72:75]
	v_mfma_f32_16x16x32_bf16 v[124:127], v[152:155], v[184:187], v[124:127]
	v_mfma_f32_16x16x32_bf16 v[120:123], v[160:163], v[184:187], v[120:123]
	v_mfma_f32_16x16x32_bf16 v[108:111], v[152:155], v[192:195], v[108:111]
	v_mfma_f32_16x16x32_bf16 v[104:107], v[160:163], v[192:195], v[104:107]
	v_mfma_f32_16x16x32_bf16 v[92:95], v[152:155], v[200:203], v[92:95]
	v_mfma_f32_16x16x32_bf16 v[88:91], v[160:163], v[200:203], v[88:91]
	v_mfma_f32_16x16x32_bf16 v[76:79], v[152:155], v[208:211], v[76:79]
	v_mfma_f32_16x16x32_bf16 v[72:75], v[160:163], v[208:211], v[72:75]
	s_setprio 0
	s_setprio 1
	v_mfma_f32_16x16x32_bf16 v[116:119], v[164:167], v[180:183], v[116:119]
	v_mfma_f32_16x16x32_bf16 v[112:115], v[172:175], v[180:183], v[112:115]
	v_mfma_f32_16x16x32_bf16 v[100:103], v[164:167], v[188:191], v[100:103]
	v_mfma_f32_16x16x32_bf16 v[96:99], v[172:175], v[188:191], v[96:99]
	v_mfma_f32_16x16x32_bf16 v[84:87], v[164:167], v[196:199], v[84:87]
	v_mfma_f32_16x16x32_bf16 v[80:83], v[172:175], v[196:199], v[80:83]
	v_mfma_f32_16x16x32_bf16 v[68:71], v[164:167], v[204:207], v[68:71]
	v_mfma_f32_16x16x32_bf16 v[64:67], v[172:175], v[204:207], v[64:67]
	v_mfma_f32_16x16x32_bf16 v[116:119], v[168:171], v[184:187], v[116:119]
	v_mfma_f32_16x16x32_bf16 v[112:115], v[176:179], v[184:187], v[112:115]
	v_mfma_f32_16x16x32_bf16 v[100:103], v[168:171], v[192:195], v[100:103]
	v_mfma_f32_16x16x32_bf16 v[96:99], v[176:179], v[192:195], v[96:99]
	v_mfma_f32_16x16x32_bf16 v[84:87], v[168:171], v[200:203], v[84:87]
	v_mfma_f32_16x16x32_bf16 v[80:83], v[176:179], v[200:203], v[80:83]
	v_mfma_f32_16x16x32_bf16 v[68:71], v[168:171], v[208:211], v[68:71]
	v_mfma_f32_16x16x32_bf16 v[64:67], v[176:179], v[208:211], v[64:67]
	s_setprio 0
	s_barrier
	s_add_i32 s55, s48, s38
	v_lshl_add_u64 v[212:213], s[28:29], 0, v[128:129]
	s_mov_b32 m0, s55
	ds_read_b128 v[180:183], v149 offset:16384
	ds_read_b128 v[184:187], v149 offset:17408
	ds_read_b128 v[188:191], v149 offset:18432
	ds_read_b128 v[192:195], v149 offset:19456
	ds_read_b128 v[196:199], v149 offset:20480
	ds_read_b128 v[200:203], v149 offset:21504
	ds_read_b128 v[204:207], v149 offset:22528
	ds_read_b128 v[208:211], v149 offset:23552
	global_load_lds_dwordx4 v[212:213], off
	s_add_i32 m0, s55, 0x2000
	s_add_u32 s56, s28, 0x40000
	v_lshl_add_u64 v[214:215], s[28:29], 0, v[130:131]
	s_addc_u32 s57, s29, 0
	s_add_i32 s55, s49, s38
	global_load_lds_dwordx4 v[214:215], off
	v_lshl_add_u64 v[216:217], s[56:57], 0, v[128:129]
	s_mov_b32 m0, s55
	v_lshl_add_u64 v[218:219], s[30:31], 0, v[130:131]
	global_load_lds_dwordx4 v[216:217], off
	v_lshl_add_u64 v[216:217], s[56:57], 0, v[130:131]
	s_add_i32 m0, s55, 0x2000
	s_nop 0
	global_load_lds_dwordx4 v[216:217], off
	v_lshl_add_u64 v[216:217], s[30:31], 0, v[128:129]
	s_mov_b32 m0, s39
	s_nop 0
	global_load_lds_dwordx4 v[216:217], off
	s_mov_b32 m0, s40
	s_nop 0
	global_load_lds_dwordx4 v[218:219], off
	s_waitcnt vmcnt(8)
	s_waitcnt lgkmcnt(0)
	s_barrier
	s_setprio 1
	s_waitcnt lgkmcnt(0)
	v_mfma_f32_16x16x32_bf16 v[60:63], v[140:143], v[180:183], v[60:63]
	v_mfma_f32_16x16x32_bf16 v[56:59], v[156:159], v[180:183], v[56:59]
	v_mfma_f32_16x16x32_bf16 v[44:47], v[140:143], v[188:191], v[44:47]
	v_mfma_f32_16x16x32_bf16 v[40:43], v[156:159], v[188:191], v[40:43]
	v_mfma_f32_16x16x32_bf16 v[28:31], v[140:143], v[196:199], v[28:31]
	v_mfma_f32_16x16x32_bf16 v[24:27], v[156:159], v[196:199], v[24:27]
	v_mfma_f32_16x16x32_bf16 v[12:15], v[140:143], v[204:207], v[12:15]
	v_mfma_f32_16x16x32_bf16 v[8:11], v[156:159], v[204:207], v[8:11]
	v_mfma_f32_16x16x32_bf16 v[60:63], v[152:155], v[184:187], v[60:63]
	v_mfma_f32_16x16x32_bf16 v[56:59], v[160:163], v[184:187], v[56:59]
	v_mfma_f32_16x16x32_bf16 v[44:47], v[152:155], v[192:195], v[44:47]
	v_mfma_f32_16x16x32_bf16 v[40:43], v[160:163], v[192:195], v[40:43]
	v_mfma_f32_16x16x32_bf16 v[28:31], v[152:155], v[200:203], v[28:31]
	v_mfma_f32_16x16x32_bf16 v[24:27], v[160:163], v[200:203], v[24:27]
	v_mfma_f32_16x16x32_bf16 v[12:15], v[152:155], v[208:211], v[12:15]
	v_mfma_f32_16x16x32_bf16 v[8:11], v[160:163], v[208:211], v[8:11]
	s_setprio 0
	s_setprio 1
	v_mfma_f32_16x16x32_bf16 v[52:55], v[164:167], v[180:183], v[52:55]
	v_mfma_f32_16x16x32_bf16 v[48:51], v[172:175], v[180:183], v[48:51]
	v_mfma_f32_16x16x32_bf16 v[36:39], v[164:167], v[188:191], v[36:39]
	v_mfma_f32_16x16x32_bf16 v[32:35], v[172:175], v[188:191], v[32:35]
	v_mfma_f32_16x16x32_bf16 v[20:23], v[164:167], v[196:199], v[20:23]
	v_mfma_f32_16x16x32_bf16 v[16:19], v[172:175], v[196:199], v[16:19]
	v_mfma_f32_16x16x32_bf16 v[4:7], v[164:167], v[204:207], v[4:7]
	v_mfma_f32_16x16x32_bf16 v[0:3], v[172:175], v[204:207], v[0:3]
	v_mfma_f32_16x16x32_bf16 v[52:55], v[168:171], v[184:187], v[52:55]
	v_mfma_f32_16x16x32_bf16 v[48:51], v[176:179], v[184:187], v[48:51]
	v_mfma_f32_16x16x32_bf16 v[36:39], v[168:171], v[192:195], v[36:39]
	v_mfma_f32_16x16x32_bf16 v[32:35], v[176:179], v[192:195], v[32:35]
	v_mfma_f32_16x16x32_bf16 v[20:23], v[168:171], v[200:203], v[20:23]
	v_mfma_f32_16x16x32_bf16 v[16:19], v[176:179], v[200:203], v[16:19]
	v_mfma_f32_16x16x32_bf16 v[4:7], v[168:171], v[208:211], v[4:7]
	v_mfma_f32_16x16x32_bf16 v[0:3], v[176:179], v[208:211], v[0:3]
	s_setprio 0
	s_barrier
	s_add_i32 s55, 0, 0x18000
	v_add_u32_e32 v151, s55, v145
	s_add_i32 s56, 0, 0x1c000
	ds_read_b128 v[140:143], v151
	ds_read_b128 v[152:155], v151 offset:1024
	ds_read_b128 v[156:159], v151 offset:2048
	ds_read_b128 v[160:163], v151 offset:3072
	v_add_u32_e32 v151, s56, v145
	ds_read_b128 v[164:167], v151
	ds_read_b128 v[168:171], v151 offset:1024
	ds_read_b128 v[172:175], v151 offset:2048
	ds_read_b128 v[176:179], v151 offset:3072
	s_add_u32 s30, s30, 0x40000
	s_addc_u32 s31, s31, 0
	s_mov_b32 m0, s41
	v_lshl_add_u64 v[220:221], s[30:31], 0, v[128:129]
	ds_read_b128 v[180:183], v149 offset:32768
	ds_read_b128 v[184:187], v149 offset:33792
	ds_read_b128 v[188:191], v149 offset:34816
	ds_read_b128 v[192:195], v149 offset:35840
	ds_read_b128 v[196:199], v149 offset:36864
	ds_read_b128 v[200:203], v149 offset:37888
	ds_read_b128 v[204:207], v149 offset:38912
	ds_read_b128 v[208:211], v149 offset:39936
	global_load_lds_dwordx4 v[220:221], off
	v_lshl_add_u64 v[220:221], s[30:31], 0, v[130:131]
	s_mov_b32 m0, s42
	s_nop 0
	global_load_lds_dwordx4 v[220:221], off
	s_waitcnt vmcnt(8)
	s_waitcnt lgkmcnt(0)
	s_barrier
	s_setprio 1
	s_waitcnt lgkmcnt(0)
	v_mfma_f32_16x16x32_bf16 v[124:127], v[140:143], v[180:183], v[124:127]
	v_mfma_f32_16x16x32_bf16 v[120:123], v[156:159], v[180:183], v[120:123]
	v_mfma_f32_16x16x32_bf16 v[108:111], v[140:143], v[188:191], v[108:111]
	v_mfma_f32_16x16x32_bf16 v[104:107], v[156:159], v[188:191], v[104:107]
	v_mfma_f32_16x16x32_bf16 v[92:95], v[140:143], v[196:199], v[92:95]
	v_mfma_f32_16x16x32_bf16 v[88:91], v[156:159], v[196:199], v[88:91]
	v_mfma_f32_16x16x32_bf16 v[76:79], v[140:143], v[204:207], v[76:79]
	v_mfma_f32_16x16x32_bf16 v[72:75], v[156:159], v[204:207], v[72:75]
	v_mfma_f32_16x16x32_bf16 v[124:127], v[152:155], v[184:187], v[124:127]
	v_mfma_f32_16x16x32_bf16 v[120:123], v[160:163], v[184:187], v[120:123]
	v_mfma_f32_16x16x32_bf16 v[108:111], v[152:155], v[192:195], v[108:111]
	v_mfma_f32_16x16x32_bf16 v[104:107], v[160:163], v[192:195], v[104:107]
	v_mfma_f32_16x16x32_bf16 v[92:95], v[152:155], v[200:203], v[92:95]
	v_mfma_f32_16x16x32_bf16 v[88:91], v[160:163], v[200:203], v[88:91]
	v_mfma_f32_16x16x32_bf16 v[76:79], v[152:155], v[208:211], v[76:79]
	v_mfma_f32_16x16x32_bf16 v[72:75], v[160:163], v[208:211], v[72:75]
	s_setprio 0
	s_setprio 1
	v_mfma_f32_16x16x32_bf16 v[116:119], v[164:167], v[180:183], v[116:119]
	v_mfma_f32_16x16x32_bf16 v[112:115], v[172:175], v[180:183], v[112:115]
	v_mfma_f32_16x16x32_bf16 v[100:103], v[164:167], v[188:191], v[100:103]
	v_mfma_f32_16x16x32_bf16 v[96:99], v[172:175], v[188:191], v[96:99]
	v_mfma_f32_16x16x32_bf16 v[84:87], v[164:167], v[196:199], v[84:87]
	v_mfma_f32_16x16x32_bf16 v[80:83], v[172:175], v[196:199], v[80:83]
	v_mfma_f32_16x16x32_bf16 v[68:71], v[164:167], v[204:207], v[68:71]
	v_mfma_f32_16x16x32_bf16 v[64:67], v[172:175], v[204:207], v[64:67]
	v_mfma_f32_16x16x32_bf16 v[116:119], v[168:171], v[184:187], v[116:119]
	v_mfma_f32_16x16x32_bf16 v[112:115], v[176:179], v[184:187], v[112:115]
	v_mfma_f32_16x16x32_bf16 v[100:103], v[168:171], v[192:195], v[100:103]
	v_mfma_f32_16x16x32_bf16 v[96:99], v[176:179], v[192:195], v[96:99]
	v_mfma_f32_16x16x32_bf16 v[84:87], v[168:171], v[200:203], v[84:87]
	v_mfma_f32_16x16x32_bf16 v[80:83], v[176:179], v[200:203], v[80:83]
	v_mfma_f32_16x16x32_bf16 v[68:71], v[168:171], v[208:211], v[68:71]
	v_mfma_f32_16x16x32_bf16 v[64:67], v[176:179], v[208:211], v[64:67]
	s_setprio 0
	s_barrier
	s_add_i32 s30, s55, s38
	v_lshl_add_u64 v[212:213], v[212:213], 0, s[12:13]
	s_mov_b32 m0, s30
	ds_read_b128 v[180:183], v149 offset:49152
	ds_read_b128 v[184:187], v149 offset:50176
	ds_read_b128 v[188:191], v149 offset:51200
	ds_read_b128 v[192:195], v149 offset:52224
	ds_read_b128 v[196:199], v149 offset:53248
	ds_read_b128 v[200:203], v149 offset:54272
	ds_read_b128 v[204:207], v149 offset:55296
	ds_read_b128 v[208:211], v149 offset:56320
	global_load_lds_dwordx4 v[212:213], off
	s_add_i32 m0, s30, 0x2000
	s_add_u32 s28, s28, 0x40080
	v_lshl_add_u64 v[212:213], v[214:215], 0, s[12:13]
	s_addc_u32 s29, s29, 0
	s_add_i32 s30, s56, s38
	global_load_lds_dwordx4 v[212:213], off
	v_lshl_add_u64 v[212:213], s[28:29], 0, v[128:129]
	s_mov_b32 m0, s30
	s_nop 0
	global_load_lds_dwordx4 v[212:213], off
	v_lshl_add_u64 v[212:213], s[28:29], 0, v[130:131]
	s_add_i32 m0, s30, 0x2000
	s_nop 0
	global_load_lds_dwordx4 v[212:213], off
	v_lshl_add_u64 v[212:213], v[216:217], 0, s[12:13]
	s_mov_b32 m0, s44
	s_nop 0
	global_load_lds_dwordx4 v[212:213], off
	v_lshl_add_u64 v[212:213], v[218:219], 0, s[12:13]
	s_mov_b32 m0, s45
	s_nop 0
	global_load_lds_dwordx4 v[212:213], off
	s_waitcnt vmcnt(8)
	s_waitcnt lgkmcnt(0)
	s_barrier
	s_setprio 1
	s_waitcnt lgkmcnt(0)
	v_mfma_f32_16x16x32_bf16 v[60:63], v[140:143], v[180:183], v[60:63]
	v_mfma_f32_16x16x32_bf16 v[56:59], v[156:159], v[180:183], v[56:59]
	v_mfma_f32_16x16x32_bf16 v[44:47], v[140:143], v[188:191], v[44:47]
	v_mfma_f32_16x16x32_bf16 v[40:43], v[156:159], v[188:191], v[40:43]
	v_mfma_f32_16x16x32_bf16 v[28:31], v[140:143], v[196:199], v[28:31]
	v_mfma_f32_16x16x32_bf16 v[24:27], v[156:159], v[196:199], v[24:27]
	v_mfma_f32_16x16x32_bf16 v[12:15], v[140:143], v[204:207], v[12:15]
	v_mfma_f32_16x16x32_bf16 v[8:11], v[156:159], v[204:207], v[8:11]
	v_mfma_f32_16x16x32_bf16 v[60:63], v[152:155], v[184:187], v[60:63]
	v_mfma_f32_16x16x32_bf16 v[56:59], v[160:163], v[184:187], v[56:59]
	v_mfma_f32_16x16x32_bf16 v[44:47], v[152:155], v[192:195], v[44:47]
	v_mfma_f32_16x16x32_bf16 v[40:43], v[160:163], v[192:195], v[40:43]
	v_mfma_f32_16x16x32_bf16 v[28:31], v[152:155], v[200:203], v[28:31]
	v_mfma_f32_16x16x32_bf16 v[24:27], v[160:163], v[200:203], v[24:27]
	v_mfma_f32_16x16x32_bf16 v[12:15], v[152:155], v[208:211], v[12:15]
	v_mfma_f32_16x16x32_bf16 v[8:11], v[160:163], v[208:211], v[8:11]
	s_setprio 0
	s_setprio 1
	v_mfma_f32_16x16x32_bf16 v[52:55], v[164:167], v[180:183], v[52:55]
	v_mfma_f32_16x16x32_bf16 v[48:51], v[172:175], v[180:183], v[48:51]
	v_mfma_f32_16x16x32_bf16 v[36:39], v[164:167], v[188:191], v[36:39]
	v_mfma_f32_16x16x32_bf16 v[32:35], v[172:175], v[188:191], v[32:35]
	v_mfma_f32_16x16x32_bf16 v[20:23], v[164:167], v[196:199], v[20:23]
	v_mfma_f32_16x16x32_bf16 v[16:19], v[172:175], v[196:199], v[16:19]
	v_mfma_f32_16x16x32_bf16 v[4:7], v[164:167], v[204:207], v[4:7]
	v_mfma_f32_16x16x32_bf16 v[0:3], v[172:175], v[204:207], v[0:3]
	v_mfma_f32_16x16x32_bf16 v[52:55], v[168:171], v[184:187], v[52:55]
	v_mfma_f32_16x16x32_bf16 v[48:51], v[176:179], v[184:187], v[48:51]
	v_mfma_f32_16x16x32_bf16 v[36:39], v[168:171], v[192:195], v[36:39]
	v_mfma_f32_16x16x32_bf16 v[32:35], v[176:179], v[192:195], v[32:35]
	v_mfma_f32_16x16x32_bf16 v[20:23], v[168:171], v[200:203], v[20:23]
	v_mfma_f32_16x16x32_bf16 v[16:19], v[176:179], v[200:203], v[16:19]
	v_mfma_f32_16x16x32_bf16 v[4:7], v[168:171], v[208:211], v[4:7]
	v_mfma_f32_16x16x32_bf16 v[0:3], v[176:179], v[208:211], v[0:3]
	s_setprio 0
	s_add_i32 s54, s54, 2
	s_add_u32 s26, s26, 0x100
	s_addc_u32 s27, s27, 0
	s_add_u32 s52, s52, 0x100
	s_addc_u32 s53, s53, 0
	s_cmp_gt_u32 s54, 13
	s_barrier
	s_cbranch_scc0 .LBB0_1553
	s_and_b64 vcc, exec, s[14:15]
	s_cbranch_vccz .LBB0_1556
	s_barrier

.LBB0_1619:
	ds_read_b128 v[152:155], v143
	ds_read_b128 v[162:165], v143 offset:1024
	ds_read_b128 v[166:169], v143 offset:2048
	ds_read_b128 v[170:173], v143 offset:3072
	ds_read_b128 v[174:177], v158
	ds_read_b128 v[178:181], v158 offset:1024
	ds_read_b128 v[182:185], v158 offset:2048
	ds_read_b128 v[186:189], v158 offset:3072
	s_add_u32 s30, s28, 0xfffc0080
	s_addc_u32 s31, s29, -1
	s_cmp_eq_u32 s55, 12
	s_cselect_b32 s35, s19, s31
	s_cselect_b32 s34, s25, s30
	s_cselect_b32 s31, s17, s54
	s_cselect_b32 s30, s27, s53
	s_waitcnt lgkmcnt(0)
	v_lshl_add_u64 v[156:157], s[28:29], 0, v[144:145]
	s_add_i32 m0, s39, 0xc000
	ds_read_b128 v[190:193], v159
	ds_read_b128 v[194:197], v159 offset:1024
	ds_read_b128 v[198:201], v159 offset:2048
	ds_read_b128 v[202:205], v159 offset:3072
	ds_read_b128 v[206:209], v159 offset:4096
	ds_read_b128 v[210:213], v159 offset:5120
	ds_read_b128 v[214:217], v159 offset:6144
	ds_read_b128 v[218:221], v159 offset:7168
	global_load_lds_dwordx4 v[156:157], off
	v_lshl_add_u64 v[156:157], s[28:29], 0, v[146:147]
	s_add_i32 m0, s39, 0xe000
	s_nop 0
	global_load_lds_dwordx4 v[156:157], off
	s_waitcnt vmcnt(8)
	s_waitcnt lgkmcnt(0)
	s_barrier
	s_setprio 1
	s_waitcnt lgkmcnt(0)
	v_mfma_f32_16x16x32_bf16 v[116:119], v[152:155], v[190:193], v[116:119]
	v_mfma_f32_16x16x32_bf16 v[112:115], v[166:169], v[190:193], v[112:115]
	v_mfma_f32_16x16x32_bf16 v[100:103], v[152:155], v[198:201], v[100:103]
	v_mfma_f32_16x16x32_bf16 v[96:99], v[166:169], v[198:201], v[96:99]
	v_mfma_f32_16x16x32_bf16 v[88:91], v[152:155], v[206:209], v[88:91]
	v_mfma_f32_16x16x32_bf16 v[84:87], v[166:169], v[206:209], v[84:87]
	v_mfma_f32_16x16x32_bf16 v[72:75], v[152:155], v[214:217], v[72:75]
	v_mfma_f32_16x16x32_bf16 v[68:71], v[166:169], v[214:217], v[68:71]
	v_mfma_f32_16x16x32_bf16 v[116:119], v[162:165], v[194:197], v[116:119]
	v_mfma_f32_16x16x32_bf16 v[112:115], v[170:173], v[194:197], v[112:115]
	v_mfma_f32_16x16x32_bf16 v[100:103], v[162:165], v[202:205], v[100:103]
	v_mfma_f32_16x16x32_bf16 v[96:99], v[170:173], v[202:205], v[96:99]
	v_mfma_f32_16x16x32_bf16 v[88:91], v[162:165], v[210:213], v[88:91]
	v_mfma_f32_16x16x32_bf16 v[84:87], v[170:173], v[210:213], v[84:87]
	v_mfma_f32_16x16x32_bf16 v[72:75], v[162:165], v[218:221], v[72:75]
	v_mfma_f32_16x16x32_bf16 v[68:71], v[170:173], v[218:221], v[68:71]
	s_setprio 0
	s_setprio 1
	v_mfma_f32_16x16x32_bf16 v[124:127], v[174:177], v[190:193], v[124:127]
	v_mfma_f32_16x16x32_bf16 v[120:123], v[182:185], v[190:193], v[120:123]
	v_mfma_f32_16x16x32_bf16 v[108:111], v[174:177], v[198:201], v[108:111]
	v_mfma_f32_16x16x32_bf16 v[104:107], v[182:185], v[198:201], v[104:107]
	v_mfma_f32_16x16x32_bf16 v[92:95], v[174:177], v[206:209], v[92:95]
	v_mfma_f32_16x16x32_bf16 v[80:83], v[182:185], v[206:209], v[80:83]
	v_mfma_f32_16x16x32_bf16 v[76:79], v[174:177], v[214:217], v[76:79]
	v_mfma_f32_16x16x32_bf16 v[64:67], v[182:185], v[214:217], v[64:67]
	v_mfma_f32_16x16x32_bf16 v[124:127], v[178:181], v[194:197], v[124:127]
	v_mfma_f32_16x16x32_bf16 v[120:123], v[186:189], v[194:197], v[120:123]
	v_mfma_f32_16x16x32_bf16 v[108:111], v[178:181], v[202:205], v[108:111]
	v_mfma_f32_16x16x32_bf16 v[104:107], v[186:189], v[202:205], v[104:107]
	v_mfma_f32_16x16x32_bf16 v[92:95], v[178:181], v[210:213], v[92:95]
	v_mfma_f32_16x16x32_bf16 v[80:83], v[186:189], v[210:213], v[80:83]
	v_mfma_f32_16x16x32_bf16 v[76:79], v[178:181], v[218:221], v[76:79]
	v_mfma_f32_16x16x32_bf16 v[64:67], v[186:189], v[218:221], v[64:67]
	s_setprio 0
	s_barrier
	s_add_i32 s56, s49, s38
	v_lshl_add_u64 v[156:157], s[30:31], 0, v[130:131]
	s_mov_b32 m0, s56
	ds_read_b128 v[190:193], v159 offset:16384
	ds_read_b128 v[194:197], v159 offset:17408
	ds_read_b128 v[198:201], v159 offset:18432
	ds_read_b128 v[202:205], v159 offset:19456
	ds_read_b128 v[206:209], v159 offset:20480
	ds_read_b128 v[210:213], v159 offset:21504
	ds_read_b128 v[214:217], v159 offset:22528
	ds_read_b128 v[218:221], v159 offset:23552
	global_load_lds_dwordx4 v[156:157], off
	s_add_i32 m0, s56, 0x2000
	s_add_u32 s56, s30, 0x40000
	v_lshl_add_u64 v[222:223], s[30:31], 0, v[134:135]
	s_addc_u32 s57, s31, 0
	s_add_i32 s58, s50, s38
	global_load_lds_dwordx4 v[222:223], off
	v_lshl_add_u64 v[224:225], s[56:57], 0, v[130:131]
	s_mov_b32 m0, s58
	v_lshl_add_u64 v[226:227], s[34:35], 0, v[132:133]
	global_load_lds_dwordx4 v[224:225], off
	v_lshl_add_u64 v[224:225], s[56:57], 0, v[134:135]
	s_add_i32 m0, s58, 0x2000
	s_nop 0
	global_load_lds_dwordx4 v[224:225], off
	v_lshl_add_u64 v[224:225], s[34:35], 0, v[128:129]
	s_mov_b32 m0, s39
	s_nop 0
	global_load_lds_dwordx4 v[224:225], off
	s_mov_b32 m0, s40
	s_nop 0
	global_load_lds_dwordx4 v[226:227], off
	s_waitcnt vmcnt(8)
	s_waitcnt lgkmcnt(0)
	s_barrier
	s_setprio 1
	s_waitcnt lgkmcnt(0)
	v_mfma_f32_16x16x32_bf16 v[56:59], v[152:155], v[190:193], v[56:59]
	v_mfma_f32_16x16x32_bf16 v[52:55], v[166:169], v[190:193], v[52:55]
	v_mfma_f32_16x16x32_bf16 v[40:43], v[152:155], v[198:201], v[40:43]
	v_mfma_f32_16x16x32_bf16 v[36:39], v[166:169], v[198:201], v[36:39]
	v_mfma_f32_16x16x32_bf16 v[24:27], v[152:155], v[206:209], v[24:27]
	v_mfma_f32_16x16x32_bf16 v[20:23], v[166:169], v[206:209], v[20:23]
	v_mfma_f32_16x16x32_bf16 v[8:11], v[152:155], v[214:217], v[8:11]
	v_mfma_f32_16x16x32_bf16 v[4:7], v[166:169], v[214:217], v[4:7]
	v_mfma_f32_16x16x32_bf16 v[56:59], v[162:165], v[194:197], v[56:59]
	v_mfma_f32_16x16x32_bf16 v[52:55], v[170:173], v[194:197], v[52:55]
	v_mfma_f32_16x16x32_bf16 v[40:43], v[162:165], v[202:205], v[40:43]
	v_mfma_f32_16x16x32_bf16 v[36:39], v[170:173], v[202:205], v[36:39]
	v_mfma_f32_16x16x32_bf16 v[24:27], v[162:165], v[210:213], v[24:27]
	v_mfma_f32_16x16x32_bf16 v[20:23], v[170:173], v[210:213], v[20:23]
	v_mfma_f32_16x16x32_bf16 v[8:11], v[162:165], v[218:221], v[8:11]
	v_mfma_f32_16x16x32_bf16 v[4:7], v[170:173], v[218:221], v[4:7]
	s_setprio 0
	s_setprio 1
	v_mfma_f32_16x16x32_bf16 v[60:63], v[174:177], v[190:193], v[60:63]
	v_mfma_f32_16x16x32_bf16 v[48:51], v[182:185], v[190:193], v[48:51]
	v_mfma_f32_16x16x32_bf16 v[44:47], v[174:177], v[198:201], v[44:47]
	v_mfma_f32_16x16x32_bf16 v[32:35], v[182:185], v[198:201], v[32:35]
	v_mfma_f32_16x16x32_bf16 v[28:31], v[174:177], v[206:209], v[28:31]
	v_mfma_f32_16x16x32_bf16 v[16:19], v[182:185], v[206:209], v[16:19]
	v_mfma_f32_16x16x32_bf16 v[12:15], v[174:177], v[214:217], v[12:15]
	v_mfma_f32_16x16x32_bf16 v[0:3], v[182:185], v[214:217], v[0:3]
	v_mfma_f32_16x16x32_bf16 v[60:63], v[178:181], v[194:197], v[60:63]
	v_mfma_f32_16x16x32_bf16 v[48:51], v[186:189], v[194:197], v[48:51]
	v_mfma_f32_16x16x32_bf16 v[44:47], v[178:181], v[202:205], v[44:47]
	v_mfma_f32_16x16x32_bf16 v[32:35], v[186:189], v[202:205], v[32:35]
	v_mfma_f32_16x16x32_bf16 v[28:31], v[178:181], v[210:213], v[28:31]
	v_mfma_f32_16x16x32_bf16 v[16:19], v[186:189], v[210:213], v[16:19]
	v_mfma_f32_16x16x32_bf16 v[12:15], v[178:181], v[218:221], v[12:15]
	v_mfma_f32_16x16x32_bf16 v[0:3], v[186:189], v[218:221], v[0:3]
	s_setprio 0
	s_barrier
	s_add_i32 s56, 0, 0x18000
	s_add_i32 s57, 0, 0x1c000
	v_add_u32_e32 v170, s56, v141
	v_add_u32_e32 v186, s57, v141
	ds_read_b128 v[152:155], v170
	ds_read_b128 v[162:165], v170 offset:1024
	ds_read_b128 v[166:169], v170 offset:2048
	ds_read_b128 v[170:173], v170 offset:3072
	ds_read_b128 v[174:177], v186
	ds_read_b128 v[178:181], v186 offset:1024
	ds_read_b128 v[182:185], v186 offset:2048
	ds_read_b128 v[186:189], v186 offset:3072
	s_add_u32 s34, s34, 0x40000
	s_addc_u32 s35, s35, 0
	s_mov_b32 m0, s41
	v_lshl_add_u64 v[228:229], s[34:35], 0, v[128:129]
	ds_read_b128 v[190:193], v159 offset:32768
	ds_read_b128 v[194:197], v159 offset:33792
	ds_read_b128 v[198:201], v159 offset:34816
	ds_read_b128 v[202:205], v159 offset:35840
	ds_read_b128 v[206:209], v159 offset:36864
	ds_read_b128 v[210:213], v159 offset:37888
	ds_read_b128 v[214:217], v159 offset:38912
	ds_read_b128 v[218:221], v159 offset:39936
	global_load_lds_dwordx4 v[228:229], off
	v_lshl_add_u64 v[228:229], s[34:35], 0, v[132:133]
	s_mov_b32 m0, s42
	s_nop 0
	global_load_lds_dwordx4 v[228:229], off
	s_waitcnt vmcnt(8)
	s_waitcnt lgkmcnt(0)
	s_barrier
	s_setprio 1
	s_waitcnt lgkmcnt(0)
	v_mfma_f32_16x16x32_bf16 v[116:119], v[152:155], v[190:193], v[116:119]
	v_mfma_f32_16x16x32_bf16 v[112:115], v[166:169], v[190:193], v[112:115]
	v_mfma_f32_16x16x32_bf16 v[100:103], v[152:155], v[198:201], v[100:103]
	v_mfma_f32_16x16x32_bf16 v[96:99], v[166:169], v[198:201], v[96:99]
	v_mfma_f32_16x16x32_bf16 v[88:91], v[152:155], v[206:209], v[88:91]
	v_mfma_f32_16x16x32_bf16 v[84:87], v[166:169], v[206:209], v[84:87]
	v_mfma_f32_16x16x32_bf16 v[72:75], v[152:155], v[214:217], v[72:75]
	v_mfma_f32_16x16x32_bf16 v[68:71], v[166:169], v[214:217], v[68:71]
	v_mfma_f32_16x16x32_bf16 v[116:119], v[162:165], v[194:197], v[116:119]
	v_mfma_f32_16x16x32_bf16 v[112:115], v[170:173], v[194:197], v[112:115]
	v_mfma_f32_16x16x32_bf16 v[100:103], v[162:165], v[202:205], v[100:103]
	v_mfma_f32_16x16x32_bf16 v[96:99], v[170:173], v[202:205], v[96:99]
	v_mfma_f32_16x16x32_bf16 v[88:91], v[162:165], v[210:213], v[88:91]
	v_mfma_f32_16x16x32_bf16 v[84:87], v[170:173], v[210:213], v[84:87]
	v_mfma_f32_16x16x32_bf16 v[72:75], v[162:165], v[218:221], v[72:75]
	v_mfma_f32_16x16x32_bf16 v[68:71], v[170:173], v[218:221], v[68:71]
	s_setprio 0
	s_setprio 1
	v_mfma_f32_16x16x32_bf16 v[124:127], v[174:177], v[190:193], v[124:127]
	v_mfma_f32_16x16x32_bf16 v[120:123], v[182:185], v[190:193], v[120:123]
	v_mfma_f32_16x16x32_bf16 v[108:111], v[174:177], v[198:201], v[108:111]
	v_mfma_f32_16x16x32_bf16 v[104:107], v[182:185], v[198:201], v[104:107]
	v_mfma_f32_16x16x32_bf16 v[92:95], v[174:177], v[206:209], v[92:95]
	v_mfma_f32_16x16x32_bf16 v[80:83], v[182:185], v[206:209], v[80:83]
	v_mfma_f32_16x16x32_bf16 v[76:79], v[174:177], v[214:217], v[76:79]
	v_mfma_f32_16x16x32_bf16 v[64:67], v[182:185], v[214:217], v[64:67]
	v_mfma_f32_16x16x32_bf16 v[124:127], v[178:181], v[194:197], v[124:127]
	v_mfma_f32_16x16x32_bf16 v[120:123], v[186:189], v[194:197], v[120:123]
	v_mfma_f32_16x16x32_bf16 v[108:111], v[178:181], v[202:205], v[108:111]
	v_mfma_f32_16x16x32_bf16 v[104:107], v[186:189], v[202:205], v[104:107]
	v_mfma_f32_16x16x32_bf16 v[92:95], v[178:181], v[210:213], v[92:95]
	v_mfma_f32_16x16x32_bf16 v[80:83], v[186:189], v[210:213], v[80:83]
	v_mfma_f32_16x16x32_bf16 v[76:79], v[178:181], v[218:221], v[76:79]
	v_mfma_f32_16x16x32_bf16 v[64:67], v[186:189], v[218:221], v[64:67]
	s_setprio 0
	s_barrier
	s_add_i32 s34, s56, s38
	v_lshl_add_u64 v[156:157], v[156:157], 0, s[10:11]
	s_mov_b32 m0, s34
	ds_read_b128 v[190:193], v159 offset:49152
	ds_read_b128 v[194:197], v159 offset:50176
	ds_read_b128 v[198:201], v159 offset:51200
	ds_read_b128 v[202:205], v159 offset:52224
	ds_read_b128 v[206:209], v159 offset:53248
	ds_read_b128 v[210:213], v159 offset:54272
	ds_read_b128 v[214:217], v159 offset:55296
	ds_read_b128 v[218:221], v159 offset:56320
	global_load_lds_dwordx4 v[156:157], off
	s_add_i32 m0, s34, 0x2000
	s_add_u32 s30, s30, 0x40080
	v_lshl_add_u64 v[156:157], v[222:223], 0, s[10:11]
	s_addc_u32 s31, s31, 0
	s_add_i32 s34, s57, s38
	global_load_lds_dwordx4 v[156:157], off
	v_lshl_add_u64 v[156:157], s[30:31], 0, v[130:131]
	s_mov_b32 m0, s34
	s_nop 0
	global_load_lds_dwordx4 v[156:157], off
	v_lshl_add_u64 v[156:157], s[30:31], 0, v[134:135]
	s_add_i32 m0, s34, 0x2000
	s_nop 0
	global_load_lds_dwordx4 v[156:157], off
	v_lshl_add_u64 v[156:157], v[224:225], 0, s[10:11]
	s_mov_b32 m0, s43
	s_nop 0
	global_load_lds_dwordx4 v[156:157], off
	v_lshl_add_u64 v[156:157], v[226:227], 0, s[10:11]
	s_mov_b32 m0, s44
	s_nop 0
	global_load_lds_dwordx4 v[156:157], off
	s_waitcnt vmcnt(8)
	s_waitcnt lgkmcnt(0)
	s_barrier
	s_setprio 1
	s_waitcnt lgkmcnt(0)
	v_mfma_f32_16x16x32_bf16 v[56:59], v[152:155], v[190:193], v[56:59]
	v_mfma_f32_16x16x32_bf16 v[52:55], v[166:169], v[190:193], v[52:55]
	v_mfma_f32_16x16x32_bf16 v[40:43], v[152:155], v[198:201], v[40:43]
	v_mfma_f32_16x16x32_bf16 v[36:39], v[166:169], v[198:201], v[36:39]
	v_mfma_f32_16x16x32_bf16 v[24:27], v[152:155], v[206:209], v[24:27]
	v_mfma_f32_16x16x32_bf16 v[20:23], v[166:169], v[206:209], v[20:23]
	v_mfma_f32_16x16x32_bf16 v[8:11], v[152:155], v[214:217], v[8:11]
	v_mfma_f32_16x16x32_bf16 v[4:7], v[166:169], v[214:217], v[4:7]
	v_mfma_f32_16x16x32_bf16 v[56:59], v[162:165], v[194:197], v[56:59]
	v_mfma_f32_16x16x32_bf16 v[52:55], v[170:173], v[194:197], v[52:55]
	v_mfma_f32_16x16x32_bf16 v[40:43], v[162:165], v[202:205], v[40:43]
	v_mfma_f32_16x16x32_bf16 v[36:39], v[170:173], v[202:205], v[36:39]
	v_mfma_f32_16x16x32_bf16 v[24:27], v[162:165], v[210:213], v[24:27]
	v_mfma_f32_16x16x32_bf16 v[20:23], v[170:173], v[210:213], v[20:23]
	v_mfma_f32_16x16x32_bf16 v[8:11], v[162:165], v[218:221], v[8:11]
	v_mfma_f32_16x16x32_bf16 v[4:7], v[170:173], v[218:221], v[4:7]
	s_setprio 0
	s_setprio 1
	v_mfma_f32_16x16x32_bf16 v[60:63], v[174:177], v[190:193], v[60:63]
	v_mfma_f32_16x16x32_bf16 v[48:51], v[182:185], v[190:193], v[48:51]
	v_mfma_f32_16x16x32_bf16 v[44:47], v[174:177], v[198:201], v[44:47]
	v_mfma_f32_16x16x32_bf16 v[32:35], v[182:185], v[198:201], v[32:35]
	v_mfma_f32_16x16x32_bf16 v[28:31], v[174:177], v[206:209], v[28:31]
	v_mfma_f32_16x16x32_bf16 v[16:19], v[182:185], v[206:209], v[16:19]
	v_mfma_f32_16x16x32_bf16 v[12:15], v[174:177], v[214:217], v[12:15]
	v_mfma_f32_16x16x32_bf16 v[0:3], v[182:185], v[214:217], v[0:3]
	v_mfma_f32_16x16x32_bf16 v[60:63], v[178:181], v[194:197], v[60:63]
	v_mfma_f32_16x16x32_bf16 v[48:51], v[186:189], v[194:197], v[48:51]
	v_mfma_f32_16x16x32_bf16 v[44:47], v[178:181], v[202:205], v[44:47]
	v_mfma_f32_16x16x32_bf16 v[32:35], v[186:189], v[202:205], v[32:35]
	v_mfma_f32_16x16x32_bf16 v[28:31], v[178:181], v[210:213], v[28:31]
	v_mfma_f32_16x16x32_bf16 v[16:19], v[186:189], v[210:213], v[16:19]
	v_mfma_f32_16x16x32_bf16 v[12:15], v[178:181], v[218:221], v[12:15]
	v_mfma_f32_16x16x32_bf16 v[0:3], v[186:189], v[218:221], v[0:3]
	s_setprio 0
	s_add_i32 s55, s55, 2
	s_add_u32 s28, s28, 0x100
	s_addc_u32 s29, s29, 0
	s_add_u32 s53, s53, 0x100
	s_addc_u32 s54, s54, 0
	s_cmp_gt_u32 s55, 13
	s_barrier
	s_cbranch_scc0 .LBB0_1619
	s_and_b64 vcc, exec, s[12:13]
	s_cbranch_vccz .LBB0_1624
	s_barrier
	v_lshl_add_u32 v152, s26, 8, v139
	s_cmp_gt_i32 s24, 21
	s_mov_b64 s[26:27], -1
	s_cbranch_scc1 .LBB0_1625

.LBB0_1705:
	ds_read_b128 v[148:151], v145
	ds_read_b128 v[152:155], v145 offset:1024
	ds_read_b128 v[156:159], v145 offset:2048
	ds_read_b128 v[160:163], v145 offset:3072
	ds_read_b128 v[164:167], v146
	ds_read_b128 v[168:171], v146 offset:1024
	ds_read_b128 v[172:175], v146 offset:2048
	ds_read_b128 v[176:179], v146 offset:3072
	s_add_u32 s26, s24, 0x100
	s_addc_u32 s27, s25, 0
	s_cmp_eq_u32 s58, 40
	s_cselect_b32 s31, s5, s27
	s_cselect_b32 s30, s4, s26
	s_cselect_b32 s29, s23, s57
	s_cselect_b32 s28, s22, s56
	v_lshl_add_u64 v[140:141], s[24:25], 0, v[132:133]
	s_add_i32 m0, s38, 0xc000
	ds_read_b128 v[180:183], v147
	ds_read_b128 v[184:187], v147 offset:1024
	ds_read_b128 v[188:191], v147 offset:2048
	ds_read_b128 v[192:195], v147 offset:3072
	ds_read_b128 v[196:199], v147 offset:4096
	ds_read_b128 v[200:203], v147 offset:5120
	ds_read_b128 v[204:207], v147 offset:6144
	ds_read_b128 v[208:211], v147 offset:7168
	global_load_lds_dwordx4 v[140:141], off
	v_lshl_add_u64 v[140:141], s[24:25], 0, v[134:135]
	s_add_i32 m0, s38, 0xe000
	s_nop 0
	global_load_lds_dwordx4 v[140:141], off
	s_waitcnt vmcnt(8)
	s_waitcnt lgkmcnt(0)
	s_barrier
	s_setprio 1
	s_waitcnt lgkmcnt(0)
	v_mfma_f32_16x16x32_bf16 v[124:127], v[148:151], v[180:183], v[124:127]
	v_mfma_f32_16x16x32_bf16 v[120:123], v[156:159], v[180:183], v[120:123]
	v_mfma_f32_16x16x32_bf16 v[116:119], v[148:151], v[188:191], v[116:119]
	v_mfma_f32_16x16x32_bf16 v[112:115], v[156:159], v[188:191], v[112:115]
	v_mfma_f32_16x16x32_bf16 v[92:95], v[148:151], v[196:199], v[92:95]
	v_mfma_f32_16x16x32_bf16 v[88:91], v[156:159], v[196:199], v[88:91]
	v_mfma_f32_16x16x32_bf16 v[84:87], v[148:151], v[204:207], v[84:87]
	v_mfma_f32_16x16x32_bf16 v[80:83], v[156:159], v[204:207], v[80:83]
	v_mfma_f32_16x16x32_bf16 v[124:127], v[152:155], v[184:187], v[124:127]
	v_mfma_f32_16x16x32_bf16 v[120:123], v[160:163], v[184:187], v[120:123]
	v_mfma_f32_16x16x32_bf16 v[116:119], v[152:155], v[192:195], v[116:119]
	v_mfma_f32_16x16x32_bf16 v[112:115], v[160:163], v[192:195], v[112:115]
	v_mfma_f32_16x16x32_bf16 v[92:95], v[152:155], v[200:203], v[92:95]
	v_mfma_f32_16x16x32_bf16 v[88:91], v[160:163], v[200:203], v[88:91]
	v_mfma_f32_16x16x32_bf16 v[84:87], v[152:155], v[208:211], v[84:87]
	v_mfma_f32_16x16x32_bf16 v[80:83], v[160:163], v[208:211], v[80:83]
	s_setprio 0
	s_setprio 1
	v_mfma_f32_16x16x32_bf16 v[108:111], v[164:167], v[180:183], v[108:111]
	v_mfma_f32_16x16x32_bf16 v[104:107], v[172:175], v[180:183], v[104:107]
	v_mfma_f32_16x16x32_bf16 v[100:103], v[164:167], v[188:191], v[100:103]
	v_mfma_f32_16x16x32_bf16 v[96:99], v[172:175], v[188:191], v[96:99]
	v_mfma_f32_16x16x32_bf16 v[76:79], v[164:167], v[196:199], v[76:79]
	v_mfma_f32_16x16x32_bf16 v[72:75], v[172:175], v[196:199], v[72:75]
	v_mfma_f32_16x16x32_bf16 v[68:71], v[164:167], v[204:207], v[68:71]
	v_mfma_f32_16x16x32_bf16 v[64:67], v[172:175], v[204:207], v[64:67]
	v_mfma_f32_16x16x32_bf16 v[108:111], v[168:171], v[184:187], v[108:111]
	v_mfma_f32_16x16x32_bf16 v[104:107], v[176:179], v[184:187], v[104:107]
	v_mfma_f32_16x16x32_bf16 v[100:103], v[168:171], v[192:195], v[100:103]
	v_mfma_f32_16x16x32_bf16 v[96:99], v[176:179], v[192:195], v[96:99]
	v_mfma_f32_16x16x32_bf16 v[76:79], v[168:171], v[200:203], v[76:79]
	v_mfma_f32_16x16x32_bf16 v[72:75], v[176:179], v[200:203], v[72:75]
	v_mfma_f32_16x16x32_bf16 v[68:71], v[168:171], v[208:211], v[68:71]
	v_mfma_f32_16x16x32_bf16 v[64:67], v[176:179], v[208:211], v[64:67]
	s_setprio 0
	s_barrier
	s_add_i32 s24, s46, s37
	v_lshl_add_u64 v[140:141], s[28:29], 0, v[128:129]
	s_mov_b32 m0, s24
	ds_read_b128 v[180:183], v147 offset:16384
	ds_read_b128 v[184:187], v147 offset:17408
	ds_read_b128 v[188:191], v147 offset:18432
	ds_read_b128 v[192:195], v147 offset:19456
	ds_read_b128 v[196:199], v147 offset:20480
	ds_read_b128 v[200:203], v147 offset:21504
	ds_read_b128 v[204:207], v147 offset:22528
	ds_read_b128 v[208:211], v147 offset:23552
	global_load_lds_dwordx4 v[140:141], off
	s_add_i32 m0, s24, 0x2000
	s_add_u32 s24, s28, 0xb0000
	v_lshl_add_u64 v[212:213], s[28:29], 0, v[130:131]
	s_addc_u32 s25, s29, 0
	s_add_i32 s59, s47, s37
	global_load_lds_dwordx4 v[212:213], off
	v_lshl_add_u64 v[214:215], s[24:25], 0, v[128:129]
	s_mov_b32 m0, s59
	v_lshl_add_u64 v[216:217], s[30:31], 0, v[130:131]
	global_load_lds_dwordx4 v[214:215], off
	v_lshl_add_u64 v[214:215], s[24:25], 0, v[130:131]
	s_add_i32 m0, s59, 0x2000
	s_nop 0
	global_load_lds_dwordx4 v[214:215], off
	v_lshl_add_u64 v[214:215], s[30:31], 0, v[128:129]
	s_mov_b32 m0, s38
	s_nop 0
	global_load_lds_dwordx4 v[214:215], off
	s_mov_b32 m0, s39
	s_nop 0
	global_load_lds_dwordx4 v[216:217], off
	s_waitcnt vmcnt(8)
	s_waitcnt lgkmcnt(0)
	s_barrier
	s_setprio 1
	s_waitcnt lgkmcnt(0)
	v_mfma_f32_16x16x32_bf16 v[60:63], v[148:151], v[180:183], v[60:63]
	v_mfma_f32_16x16x32_bf16 v[56:59], v[156:159], v[180:183], v[56:59]
	v_mfma_f32_16x16x32_bf16 v[52:55], v[148:151], v[188:191], v[52:55]
	v_mfma_f32_16x16x32_bf16 v[48:51], v[156:159], v[188:191], v[48:51]
	v_mfma_f32_16x16x32_bf16 v[28:31], v[148:151], v[196:199], v[28:31]
	v_mfma_f32_16x16x32_bf16 v[24:27], v[156:159], v[196:199], v[24:27]
	v_mfma_f32_16x16x32_bf16 v[20:23], v[148:151], v[204:207], v[20:23]
	v_mfma_f32_16x16x32_bf16 v[16:19], v[156:159], v[204:207], v[16:19]
	v_mfma_f32_16x16x32_bf16 v[60:63], v[152:155], v[184:187], v[60:63]
	v_mfma_f32_16x16x32_bf16 v[56:59], v[160:163], v[184:187], v[56:59]
	v_mfma_f32_16x16x32_bf16 v[52:55], v[152:155], v[192:195], v[52:55]
	v_mfma_f32_16x16x32_bf16 v[48:51], v[160:163], v[192:195], v[48:51]
	v_mfma_f32_16x16x32_bf16 v[28:31], v[152:155], v[200:203], v[28:31]
	v_mfma_f32_16x16x32_bf16 v[24:27], v[160:163], v[200:203], v[24:27]
	v_mfma_f32_16x16x32_bf16 v[20:23], v[152:155], v[208:211], v[20:23]
	v_mfma_f32_16x16x32_bf16 v[16:19], v[160:163], v[208:211], v[16:19]
	s_setprio 0
	s_setprio 1
	v_mfma_f32_16x16x32_bf16 v[44:47], v[164:167], v[180:183], v[44:47]
	v_mfma_f32_16x16x32_bf16 v[40:43], v[172:175], v[180:183], v[40:43]
	v_mfma_f32_16x16x32_bf16 v[36:39], v[164:167], v[188:191], v[36:39]
	v_mfma_f32_16x16x32_bf16 v[32:35], v[172:175], v[188:191], v[32:35]
	v_mfma_f32_16x16x32_bf16 v[12:15], v[164:167], v[196:199], v[12:15]
	v_mfma_f32_16x16x32_bf16 v[8:11], v[172:175], v[196:199], v[8:11]
	v_mfma_f32_16x16x32_bf16 v[4:7], v[164:167], v[204:207], v[4:7]
	v_mfma_f32_16x16x32_bf16 v[0:3], v[172:175], v[204:207], v[0:3]
	v_mfma_f32_16x16x32_bf16 v[44:47], v[168:171], v[184:187], v[44:47]
	v_mfma_f32_16x16x32_bf16 v[40:43], v[176:179], v[184:187], v[40:43]
	v_mfma_f32_16x16x32_bf16 v[36:39], v[168:171], v[192:195], v[36:39]
	v_mfma_f32_16x16x32_bf16 v[32:35], v[176:179], v[192:195], v[32:35]
	v_mfma_f32_16x16x32_bf16 v[12:15], v[168:171], v[200:203], v[12:15]
	v_mfma_f32_16x16x32_bf16 v[8:11], v[176:179], v[200:203], v[8:11]
	v_mfma_f32_16x16x32_bf16 v[4:7], v[168:171], v[208:211], v[4:7]
	v_mfma_f32_16x16x32_bf16 v[0:3], v[176:179], v[208:211], v[0:3]
	s_setprio 0
	s_barrier
	s_add_i32 s59, 0, 0x18000
	s_add_i32 s60, 0, 0x1c000
	v_add_u32_e32 v160, s59, v143
	v_add_u32_e32 v176, s60, v143
	ds_read_b128 v[148:151], v160
	ds_read_b128 v[152:155], v160 offset:1024
	ds_read_b128 v[156:159], v160 offset:2048
	ds_read_b128 v[160:163], v160 offset:3072
	ds_read_b128 v[164:167], v176
	ds_read_b128 v[168:171], v176 offset:1024
	ds_read_b128 v[172:175], v176 offset:2048
	ds_read_b128 v[176:179], v176 offset:3072
	s_add_u32 s24, s30, 0xb0000
	s_addc_u32 s25, s31, 0
	s_mov_b32 m0, s40
	v_lshl_add_u64 v[218:219], s[24:25], 0, v[128:129]
	ds_read_b128 v[180:183], v147 offset:32768
	ds_read_b128 v[184:187], v147 offset:33792
	ds_read_b128 v[188:191], v147 offset:34816
	ds_read_b128 v[192:195], v147 offset:35840
	ds_read_b128 v[196:199], v147 offset:36864
	ds_read_b128 v[200:203], v147 offset:37888
	ds_read_b128 v[204:207], v147 offset:38912
	ds_read_b128 v[208:211], v147 offset:39936
	global_load_lds_dwordx4 v[218:219], off
	v_lshl_add_u64 v[218:219], s[24:25], 0, v[130:131]
	s_mov_b32 m0, s41
	s_nop 0
	global_load_lds_dwordx4 v[218:219], off
	s_waitcnt vmcnt(8)
	s_waitcnt lgkmcnt(0)
	s_barrier
	s_setprio 1
	s_waitcnt lgkmcnt(0)
	v_mfma_f32_16x16x32_bf16 v[124:127], v[148:151], v[180:183], v[124:127]
	v_mfma_f32_16x16x32_bf16 v[120:123], v[156:159], v[180:183], v[120:123]
	v_mfma_f32_16x16x32_bf16 v[116:119], v[148:151], v[188:191], v[116:119]
	v_mfma_f32_16x16x32_bf16 v[112:115], v[156:159], v[188:191], v[112:115]
	v_mfma_f32_16x16x32_bf16 v[92:95], v[148:151], v[196:199], v[92:95]
	v_mfma_f32_16x16x32_bf16 v[88:91], v[156:159], v[196:199], v[88:91]
	v_mfma_f32_16x16x32_bf16 v[84:87], v[148:151], v[204:207], v[84:87]
	v_mfma_f32_16x16x32_bf16 v[80:83], v[156:159], v[204:207], v[80:83]
	v_mfma_f32_16x16x32_bf16 v[124:127], v[152:155], v[184:187], v[124:127]
	v_mfma_f32_16x16x32_bf16 v[120:123], v[160:163], v[184:187], v[120:123]
	v_mfma_f32_16x16x32_bf16 v[116:119], v[152:155], v[192:195], v[116:119]
	v_mfma_f32_16x16x32_bf16 v[112:115], v[160:163], v[192:195], v[112:115]
	v_mfma_f32_16x16x32_bf16 v[92:95], v[152:155], v[200:203], v[92:95]
	v_mfma_f32_16x16x32_bf16 v[88:91], v[160:163], v[200:203], v[88:91]
	v_mfma_f32_16x16x32_bf16 v[84:87], v[152:155], v[208:211], v[84:87]
	v_mfma_f32_16x16x32_bf16 v[80:83], v[160:163], v[208:211], v[80:83]
	s_setprio 0
	s_setprio 1
	v_mfma_f32_16x16x32_bf16 v[108:111], v[164:167], v[180:183], v[108:111]
	v_mfma_f32_16x16x32_bf16 v[104:107], v[172:175], v[180:183], v[104:107]
	v_mfma_f32_16x16x32_bf16 v[100:103], v[164:167], v[188:191], v[100:103]
	v_mfma_f32_16x16x32_bf16 v[96:99], v[172:175], v[188:191], v[96:99]
	v_mfma_f32_16x16x32_bf16 v[76:79], v[164:167], v[196:199], v[76:79]
	v_mfma_f32_16x16x32_bf16 v[72:75], v[172:175], v[196:199], v[72:75]
	v_mfma_f32_16x16x32_bf16 v[68:71], v[164:167], v[204:207], v[68:71]
	v_mfma_f32_16x16x32_bf16 v[64:67], v[172:175], v[204:207], v[64:67]
	v_mfma_f32_16x16x32_bf16 v[108:111], v[168:171], v[184:187], v[108:111]
	v_mfma_f32_16x16x32_bf16 v[104:107], v[176:179], v[184:187], v[104:107]
	v_mfma_f32_16x16x32_bf16 v[100:103], v[168:171], v[192:195], v[100:103]
	v_mfma_f32_16x16x32_bf16 v[96:99], v[176:179], v[192:195], v[96:99]
	v_mfma_f32_16x16x32_bf16 v[76:79], v[168:171], v[200:203], v[76:79]
	v_mfma_f32_16x16x32_bf16 v[72:75], v[176:179], v[200:203], v[72:75]
	v_mfma_f32_16x16x32_bf16 v[68:71], v[168:171], v[208:211], v[68:71]
	v_mfma_f32_16x16x32_bf16 v[64:67], v[176:179], v[208:211], v[64:67]
	s_setprio 0
	s_barrier
	s_add_i32 s24, s59, s37
	v_lshl_add_u64 v[140:141], v[140:141], 0, s[12:13]
	s_mov_b32 m0, s24
	ds_read_b128 v[180:183], v147 offset:49152
	ds_read_b128 v[184:187], v147 offset:50176
	ds_read_b128 v[188:191], v147 offset:51200
	ds_read_b128 v[192:195], v147 offset:52224
	ds_read_b128 v[196:199], v147 offset:53248
	ds_read_b128 v[200:203], v147 offset:54272
	ds_read_b128 v[204:207], v147 offset:55296
	ds_read_b128 v[208:211], v147 offset:56320
	global_load_lds_dwordx4 v[140:141], off
	s_add_i32 m0, s24, 0x2000
	s_add_u32 s24, s28, 0xb0080
	v_lshl_add_u64 v[140:141], v[212:213], 0, s[12:13]
	s_addc_u32 s25, s29, 0
	s_add_i32 s28, s60, s37
	global_load_lds_dwordx4 v[140:141], off
	v_lshl_add_u64 v[140:141], s[24:25], 0, v[128:129]
	s_mov_b32 m0, s28
	s_nop 0
	global_load_lds_dwordx4 v[140:141], off
	v_lshl_add_u64 v[140:141], s[24:25], 0, v[130:131]
	s_add_i32 m0, s28, 0x2000
	s_nop 0
	global_load_lds_dwordx4 v[140:141], off
	v_lshl_add_u64 v[140:141], v[214:215], 0, s[12:13]
	s_mov_b32 m0, s43
	s_nop 0
	global_load_lds_dwordx4 v[140:141], off
	v_lshl_add_u64 v[140:141], v[216:217], 0, s[12:13]
	s_mov_b32 m0, s44
	s_nop 0
	global_load_lds_dwordx4 v[140:141], off
	s_waitcnt vmcnt(8)
	s_waitcnt lgkmcnt(0)
	s_barrier
	s_setprio 1
	s_waitcnt lgkmcnt(0)
	v_mfma_f32_16x16x32_bf16 v[60:63], v[148:151], v[180:183], v[60:63]
	v_mfma_f32_16x16x32_bf16 v[56:59], v[156:159], v[180:183], v[56:59]
	v_mfma_f32_16x16x32_bf16 v[52:55], v[148:151], v[188:191], v[52:55]
	v_mfma_f32_16x16x32_bf16 v[48:51], v[156:159], v[188:191], v[48:51]
	v_mfma_f32_16x16x32_bf16 v[28:31], v[148:151], v[196:199], v[28:31]
	v_mfma_f32_16x16x32_bf16 v[24:27], v[156:159], v[196:199], v[24:27]
	v_mfma_f32_16x16x32_bf16 v[20:23], v[148:151], v[204:207], v[20:23]
	v_mfma_f32_16x16x32_bf16 v[16:19], v[156:159], v[204:207], v[16:19]
	v_mfma_f32_16x16x32_bf16 v[60:63], v[152:155], v[184:187], v[60:63]
	v_mfma_f32_16x16x32_bf16 v[56:59], v[160:163], v[184:187], v[56:59]
	v_mfma_f32_16x16x32_bf16 v[52:55], v[152:155], v[192:195], v[52:55]
	v_mfma_f32_16x16x32_bf16 v[48:51], v[160:163], v[192:195], v[48:51]
	v_mfma_f32_16x16x32_bf16 v[28:31], v[152:155], v[200:203], v[28:31]
	v_mfma_f32_16x16x32_bf16 v[24:27], v[160:163], v[200:203], v[24:27]
	v_mfma_f32_16x16x32_bf16 v[20:23], v[152:155], v[208:211], v[20:23]
	v_mfma_f32_16x16x32_bf16 v[16:19], v[160:163], v[208:211], v[16:19]
	s_setprio 0
	s_setprio 1
	v_mfma_f32_16x16x32_bf16 v[44:47], v[164:167], v[180:183], v[44:47]
	v_mfma_f32_16x16x32_bf16 v[40:43], v[172:175], v[180:183], v[40:43]
	v_mfma_f32_16x16x32_bf16 v[36:39], v[164:167], v[188:191], v[36:39]
	v_mfma_f32_16x16x32_bf16 v[32:35], v[172:175], v[188:191], v[32:35]
	v_mfma_f32_16x16x32_bf16 v[12:15], v[164:167], v[196:199], v[12:15]
	v_mfma_f32_16x16x32_bf16 v[8:11], v[172:175], v[196:199], v[8:11]
	v_mfma_f32_16x16x32_bf16 v[4:7], v[164:167], v[204:207], v[4:7]
	v_mfma_f32_16x16x32_bf16 v[0:3], v[172:175], v[204:207], v[0:3]
	v_mfma_f32_16x16x32_bf16 v[44:47], v[168:171], v[184:187], v[44:47]
	v_mfma_f32_16x16x32_bf16 v[40:43], v[176:179], v[184:187], v[40:43]
	v_mfma_f32_16x16x32_bf16 v[36:39], v[168:171], v[192:195], v[36:39]
	v_mfma_f32_16x16x32_bf16 v[32:35], v[176:179], v[192:195], v[32:35]
	v_mfma_f32_16x16x32_bf16 v[12:15], v[168:171], v[200:203], v[12:15]
	v_mfma_f32_16x16x32_bf16 v[8:11], v[176:179], v[200:203], v[8:11]
	v_mfma_f32_16x16x32_bf16 v[4:7], v[168:171], v[208:211], v[4:7]
	v_mfma_f32_16x16x32_bf16 v[0:3], v[176:179], v[208:211], v[0:3]
	s_setprio 0
	s_add_i32 s58, s58, 2
	s_add_u32 s56, s56, 0x100
	s_addc_u32 s57, s57, 0
	s_cmp_gt_u32 s58, 41
	s_mov_b64 s[24:25], s[26:27]
	s_barrier
	s_cbranch_scc0 .LBB0_1705
	s_and_b64 vcc, exec, s[14:15]
	s_cbranch_vccz .LBB0_1708
	s_barrier
